# GEMM K-loops: first-iteration counted waits leave the previous unit's epilogue stores in flight (vmcnt 8+stores)
# baseline (speedup 1.0000x reference)
; #define PG8_STAGE(bufoff, gbase, voff) do { _Pragma("unroll") for (int _i = 0; _i < 2; ++_i) \
;         __builtin_amdgcn_global_load_lds((const unsigned*)((const char*)(gbase) + (voff)[_i]), (PG8_LAS unsigned*)(lds + (bufoff) + ldsw + _i * 8192), 16, 0, 0); } while (0)
; #define PG8_LDA(dst, b, h) do { _Pragma("unroll") for (int m = 0; m < 4; ++m) _Pragma("unroll") for (int k = 0; k < 2; ++k) dst[m][k] = *(const PG8_LAS bf16x8*)(lds + PG8_SA(b, h) + aoff + m * 2048 + k * 1024); } while (0)
; #define PG8_LDB(dst, b, h) do { _Pragma("unroll") for (int n = 0; n < 2; ++n) _Pragma("unroll") for (int k = 0; k < 2; ++k) dst[n][k] = *(const PG8_LAS bf16x8*)(lds + PG8_SB(b, h) + boff + n * 2048 + k * 1024); } while (0)
; #define PG8_MMA(ai, bj, At, Bt) do { __builtin_amdgcn_s_setprio(1); _Pragma("unroll") for (int m = 0; m < 4; ++m) _Pragma("unroll") for (int n = 0; n < 2; ++n) _Pragma("unroll") for (int k = 0; k < 2; ++k) \
;         acc[ai][bj][m][n] = __builtin_amdgcn_mfma_f32_16x16x32_bf16(Bt[n][k], At[m][k], acc[ai][bj][m][n], 0, 0, 0); __builtin_amdgcn_s_setprio(0); } while (0)
; #define PG8_WAIT_V(n) asm volatile("s_waitcnt vmcnt(" #n ")" ::: "memory")
; #define PG8_BAR __builtin_amdgcn_s_barrier()
; template <class Epi, class Sched, bool ALIGN_EPI = false, bool SP2 = false>
; __device__ __forceinline__ void gemm_phase(PG8_LAS unsigned char* lds, const Gemm g, const Sched& S, const Epi& E, const int wid) {
;     ...
;         for (int t = 0; t < nt; t += 2) {
;             const bool last = (t == nt - 2);
;             const char* a1 = cA + (size_t)(t + 1) * kstep;
;             const char* a2 = last ? nA : cA + (size_t)(t + 2) * kstep; const char* b2 = last ? nB : cB + (size_t)(t + 2) * kstep;
;             const char* a3 = a2 + kstep; const char* b3 = b2 + kstep;
;             if (last && has_next) S.a_ready(nxt);
;             if constexpr (SP2) {
;             PG8_LDB(B0, 0, 0); PG8_LDB(B1, 0, 1); PG8_SCHED; PG8_LDA(At, 0, 0); PG8_STAGE(PG8_SA(1, 1), a1 + hstep, voffA);
;             PG8_WAIT_V(8); PG8_WAIT_L(0); PG8_BAR; PG8_MMA(0, 0, At, B0); PG8_MMA(0, 1, At, B1); PG8_BAR; PG8_SCHED;
;             PG8_LDA(At, 0, 1); PG8_STAGE(PG8_SB(0, 0), b2, voffB); PG8_STAGE(PG8_SB(0, 1), b2 + hstep, voffB); PG8_STAGE(PG8_SA(0, 0), a2, voffA);
;             PG8_WAIT_V(8); PG8_WAIT_L(0); PG8_BAR; PG8_MMA(1, 0, At, B0); PG8_MMA(1, 1, At, B1); PG8_BAR; PG8_SCHED;
.LBB0_20:
	ds_read_b128 v[128:131], v165
	ds_read_b128 v[146:149], v165 offset:1024
	ds_read_b128 v[150:153], v165 offset:2048
	ds_read_b128 v[154:157], v165 offset:3072
	ds_read_b128 v[158:161], v166
	ds_read_b128 v[172:175], v166 offset:1024
	ds_read_b128 v[176:179], v166 offset:2048
	ds_read_b128 v[180:183], v166 offset:3072
	s_add_i32 s38, s36, 2
	s_add_u32 s33, s4, 0x80
	s_addc_u32 s37, s5, 0
	s_cmp_eq_u32 s57, s36
	s_cselect_b32 s36, s30, s33
	s_cselect_b32 s37, s31, s37
	s_cselect_b32 s71, s35, s1
	s_cselect_b32 s70, s34, s0
	v_lshl_add_u64 v[216:217], s[4:5], 0, v[140:141]
	s_add_i32 m0, s47, 0xc000
	ds_read_b128 v[184:187], v167
	ds_read_b128 v[188:191], v167 offset:1024
	ds_read_b128 v[192:195], v167 offset:2048
	ds_read_b128 v[196:199], v167 offset:3072
	ds_read_b128 v[200:203], v167 offset:4096
	ds_read_b128 v[204:207], v167 offset:5120
	ds_read_b128 v[208:211], v167 offset:6144
	ds_read_b128 v[212:215], v167 offset:7168
	global_load_lds_dwordx4 v[216:217], off
	v_lshl_add_u64 v[216:217], s[4:5], 0, v[142:143]
	s_add_i32 m0, s47, 0xe000
	s_nop 0
	global_load_lds_dwordx4 v[216:217], off
	s_cmp_lg_u32 s38, 2
	s_cbranch_scc1 .Lw8__20_0
	s_cmp_eq_u32 s52, 1
	s_cbranch_scc1 .Lw8__20_0
	s_waitcnt vmcnt(24)
	s_branch .Lwj__20_0
.Lw8__20_0:
	s_waitcnt vmcnt(8)
.Lwj__20_0:
	s_waitcnt lgkmcnt(0)
	s_barrier
	s_setprio 1
	s_waitcnt lgkmcnt(0)
	v_mfma_f32_16x16x32_bf16 v[124:127], v[128:131], v[184:187], v[124:127]
	v_mfma_f32_16x16x32_bf16 v[120:123], v[150:153], v[184:187], v[120:123]
	v_mfma_f32_16x16x32_bf16 v[108:111], v[128:131], v[192:195], v[108:111]
	v_mfma_f32_16x16x32_bf16 v[104:107], v[150:153], v[192:195], v[104:107]
	v_mfma_f32_16x16x32_bf16 v[92:95], v[128:131], v[200:203], v[92:95]
	v_mfma_f32_16x16x32_bf16 v[88:91], v[150:153], v[200:203], v[88:91]
	v_mfma_f32_16x16x32_bf16 v[76:79], v[128:131], v[208:211], v[76:79]
	v_mfma_f32_16x16x32_bf16 v[72:75], v[150:153], v[208:211], v[72:75]
	v_mfma_f32_16x16x32_bf16 v[124:127], v[146:149], v[188:191], v[124:127]
	v_mfma_f32_16x16x32_bf16 v[120:123], v[154:157], v[188:191], v[120:123]
	v_mfma_f32_16x16x32_bf16 v[108:111], v[146:149], v[196:199], v[108:111]
	v_mfma_f32_16x16x32_bf16 v[104:107], v[154:157], v[196:199], v[104:107]
	v_mfma_f32_16x16x32_bf16 v[92:95], v[146:149], v[204:207], v[92:95]
	v_mfma_f32_16x16x32_bf16 v[88:91], v[154:157], v[204:207], v[88:91]
	v_mfma_f32_16x16x32_bf16 v[76:79], v[146:149], v[212:215], v[76:79]
	v_mfma_f32_16x16x32_bf16 v[72:75], v[154:157], v[212:215], v[72:75]
	s_setprio 0
	s_setprio 1
	v_mfma_f32_16x16x32_bf16 v[116:119], v[158:161], v[184:187], v[116:119]
	v_mfma_f32_16x16x32_bf16 v[112:115], v[176:179], v[184:187], v[112:115]
	v_mfma_f32_16x16x32_bf16 v[100:103], v[158:161], v[192:195], v[100:103]
	v_mfma_f32_16x16x32_bf16 v[96:99], v[176:179], v[192:195], v[96:99]
	v_mfma_f32_16x16x32_bf16 v[84:87], v[158:161], v[200:203], v[84:87]
	v_mfma_f32_16x16x32_bf16 v[80:83], v[176:179], v[200:203], v[80:83]
	v_mfma_f32_16x16x32_bf16 v[68:71], v[158:161], v[208:211], v[68:71]
	v_mfma_f32_16x16x32_bf16 v[64:67], v[176:179], v[208:211], v[64:67]
	v_mfma_f32_16x16x32_bf16 v[116:119], v[172:175], v[188:191], v[116:119]
	v_mfma_f32_16x16x32_bf16 v[112:115], v[180:183], v[188:191], v[112:115]
	v_mfma_f32_16x16x32_bf16 v[100:103], v[172:175], v[196:199], v[100:103]
	v_mfma_f32_16x16x32_bf16 v[96:99], v[180:183], v[196:199], v[96:99]
	v_mfma_f32_16x16x32_bf16 v[84:87], v[172:175], v[204:207], v[84:87]
	v_mfma_f32_16x16x32_bf16 v[80:83], v[180:183], v[204:207], v[80:83]
	v_mfma_f32_16x16x32_bf16 v[68:71], v[172:175], v[212:215], v[68:71]
	v_mfma_f32_16x16x32_bf16 v[64:67], v[180:183], v[212:215], v[64:67]
	s_setprio 0
	s_barrier
	s_add_i32 s33, s60, s40
	v_lshl_add_u64 v[216:217], s[70:71], 0, v[136:137]
	s_mov_b32 m0, s33
	ds_read_b128 v[184:187], v167 offset:16384
	ds_read_b128 v[188:191], v167 offset:17408
	ds_read_b128 v[192:195], v167 offset:18432
	ds_read_b128 v[196:199], v167 offset:19456
	ds_read_b128 v[200:203], v167 offset:20480
	ds_read_b128 v[204:207], v167 offset:21504
	ds_read_b128 v[208:211], v167 offset:22528
	ds_read_b128 v[212:215], v167 offset:23552
	global_load_lds_dwordx4 v[216:217], off
	s_add_i32 m0, s33, 0x2000
	v_lshl_add_u64 v[218:219], s[70:71], 0, v[132:133]
	s_add_u32 s70, s70, s6
	s_addc_u32 s71, s71, s7
	s_add_i32 s33, s61, s40
	global_load_lds_dwordx4 v[218:219], off
	v_lshl_add_u64 v[220:221], s[70:71], 0, v[136:137]
	s_mov_b32 m0, s33
	v_lshl_add_u64 v[222:223], s[70:71], 0, v[132:133]
	global_load_lds_dwordx4 v[220:221], off
	s_add_i32 m0, s33, 0x2000
	v_lshl_add_u64 v[224:225], s[36:37], 0, v[138:139]
	global_load_lds_dwordx4 v[222:223], off
	s_mov_b32 m0, s47
	v_lshl_add_u64 v[226:227], s[36:37], 0, v[134:135]
	global_load_lds_dwordx4 v[224:225], off
	s_mov_b32 m0, s49
	s_nop 0
	global_load_lds_dwordx4 v[226:227], off
	s_cmp_lg_u32 s38, 2
	s_cbranch_scc1 .Lw8__20_1
	s_cmp_eq_u32 s52, 1
	s_cbranch_scc1 .Lw8__20_1
	s_waitcnt vmcnt(24)
	s_branch .Lwj__20_1

; #define PG8_STAGE(bufoff, gbase, voff) do { _Pragma("unroll") for (int _i = 0; _i < 2; ++_i) \
;         __builtin_amdgcn_global_load_lds((const unsigned*)((const char*)(gbase) + (voff)[_i]), (PG8_LAS unsigned*)(lds + (bufoff) + ldsw + _i * 8192), 16, 0, 0); } while (0)
; #define PG8_LDA(dst, b, h) do { _Pragma("unroll") for (int m = 0; m < 4; ++m) _Pragma("unroll") for (int k = 0; k < 2; ++k) dst[m][k] = *(const PG8_LAS bf16x8*)(lds + PG8_SA(b, h) + aoff + m * 2048 + k * 1024); } while (0)
; #define PG8_LDB(dst, b, h) do { _Pragma("unroll") for (int n = 0; n < 2; ++n) _Pragma("unroll") for (int k = 0; k < 2; ++k) dst[n][k] = *(const PG8_LAS bf16x8*)(lds + PG8_SB(b, h) + boff + n * 2048 + k * 1024); } while (0)
; #define PG8_MMA(ai, bj, At, Bt) do { __builtin_amdgcn_s_setprio(1); _Pragma("unroll") for (int m = 0; m < 4; ++m) _Pragma("unroll") for (int n = 0; n < 2; ++n) _Pragma("unroll") for (int k = 0; k < 2; ++k) \
;         acc[ai][bj][m][n] = __builtin_amdgcn_mfma_f32_16x16x32_bf16(Bt[n][k], At[m][k], acc[ai][bj][m][n], 0, 0, 0); __builtin_amdgcn_s_setprio(0); } while (0)
; #define PG8_WAIT_V(n) asm volatile("s_waitcnt vmcnt(" #n ")" ::: "memory")
; #define PG8_WAIT_L(n) asm volatile("s_waitcnt lgkmcnt(" #n ")" ::: "memory")
; #define PG8_BAR __builtin_amdgcn_s_barrier()
; #define PG8_SCHED __builtin_amdgcn_sched_barrier(0)
; template <class Epi, class Sched, bool ALIGN_EPI = false, bool SP2 = false>
; __device__ __forceinline__ void gemm_phase(PG8_LAS unsigned char* lds, const Gemm g, const Sched& S, const Epi& E, const int wid) {
;     ...
;             PG8_WAIT_V(8); PG8_WAIT_L(0); PG8_BAR; PG8_MMA(1, 0, At, B0); PG8_MMA(1, 1, At, B1); PG8_BAR; PG8_SCHED;
;             PG8_LDB(B0, 1, 0); PG8_LDB(B1, 1, 1); PG8_SCHED; PG8_LDA(At, 1, 0); PG8_STAGE(PG8_SA(0, 1), a2 + hstep, voffA);
;             PG8_WAIT_V(8); PG8_WAIT_L(0); PG8_BAR; PG8_MMA(0, 0, At, B0); PG8_MMA(0, 1, At, B1); PG8_BAR; PG8_SCHED;
.Lwj__20_1:
	s_waitcnt lgkmcnt(0)
	s_barrier
	s_setprio 1
	s_waitcnt lgkmcnt(0)
	v_mfma_f32_16x16x32_bf16 v[60:63], v[128:131], v[184:187], v[60:63]
	v_mfma_f32_16x16x32_bf16 v[56:59], v[150:153], v[184:187], v[56:59]
	v_mfma_f32_16x16x32_bf16 v[44:47], v[128:131], v[192:195], v[44:47]
	v_mfma_f32_16x16x32_bf16 v[40:43], v[150:153], v[192:195], v[40:43]
	v_mfma_f32_16x16x32_bf16 v[28:31], v[128:131], v[200:203], v[28:31]
	v_mfma_f32_16x16x32_bf16 v[24:27], v[150:153], v[200:203], v[24:27]
	v_mfma_f32_16x16x32_bf16 v[12:15], v[128:131], v[208:211], v[12:15]
	v_mfma_f32_16x16x32_bf16 v[8:11], v[150:153], v[208:211], v[8:11]
	v_mfma_f32_16x16x32_bf16 v[60:63], v[146:149], v[188:191], v[60:63]
	v_mfma_f32_16x16x32_bf16 v[56:59], v[154:157], v[188:191], v[56:59]
	v_mfma_f32_16x16x32_bf16 v[44:47], v[146:149], v[196:199], v[44:47]
	v_mfma_f32_16x16x32_bf16 v[40:43], v[154:157], v[196:199], v[40:43]
	v_mfma_f32_16x16x32_bf16 v[28:31], v[146:149], v[204:207], v[28:31]
	v_mfma_f32_16x16x32_bf16 v[24:27], v[154:157], v[204:207], v[24:27]
	v_mfma_f32_16x16x32_bf16 v[12:15], v[146:149], v[212:215], v[12:15]
	v_mfma_f32_16x16x32_bf16 v[8:11], v[154:157], v[212:215], v[8:11]
	s_setprio 0
	s_setprio 1
	v_mfma_f32_16x16x32_bf16 v[52:55], v[158:161], v[184:187], v[52:55]
	v_mfma_f32_16x16x32_bf16 v[48:51], v[176:179], v[184:187], v[48:51]
	v_mfma_f32_16x16x32_bf16 v[36:39], v[158:161], v[192:195], v[36:39]
	v_mfma_f32_16x16x32_bf16 v[32:35], v[176:179], v[192:195], v[32:35]
	v_mfma_f32_16x16x32_bf16 v[20:23], v[158:161], v[200:203], v[20:23]
	v_mfma_f32_16x16x32_bf16 v[16:19], v[176:179], v[200:203], v[16:19]
	v_mfma_f32_16x16x32_bf16 v[4:7], v[158:161], v[208:211], v[4:7]
	v_mfma_f32_16x16x32_bf16 v[0:3], v[176:179], v[208:211], v[0:3]
	v_mfma_f32_16x16x32_bf16 v[52:55], v[172:175], v[188:191], v[52:55]
	v_mfma_f32_16x16x32_bf16 v[48:51], v[180:183], v[188:191], v[48:51]
	v_mfma_f32_16x16x32_bf16 v[36:39], v[172:175], v[196:199], v[36:39]
	v_mfma_f32_16x16x32_bf16 v[32:35], v[180:183], v[196:199], v[32:35]
	v_mfma_f32_16x16x32_bf16 v[20:23], v[172:175], v[204:207], v[20:23]
	v_mfma_f32_16x16x32_bf16 v[16:19], v[180:183], v[204:207], v[16:19]
	v_mfma_f32_16x16x32_bf16 v[4:7], v[172:175], v[212:215], v[4:7]
	v_mfma_f32_16x16x32_bf16 v[0:3], v[180:183], v[212:215], v[0:3]
	s_setprio 0
	s_barrier
	s_add_i32 s33, 0, 0x18000
	s_add_i32 s39, 0, 0x1c000
	v_add_u32_e32 v154, s33, v164
	v_add_u32_e32 v180, s39, v164
	ds_read_b128 v[128:131], v154
	ds_read_b128 v[146:149], v154 offset:1024
	ds_read_b128 v[150:153], v154 offset:2048
	ds_read_b128 v[154:157], v154 offset:3072
	ds_read_b128 v[158:161], v180
	ds_read_b128 v[172:175], v180 offset:1024
	ds_read_b128 v[176:179], v180 offset:2048
	ds_read_b128 v[180:183], v180 offset:3072
	s_add_u32 s36, s36, s6
	s_addc_u32 s37, s37, s7
	s_mov_b32 m0, s50
	v_lshl_add_u64 v[228:229], s[36:37], 0, v[138:139]
	ds_read_b128 v[184:187], v167 offset:32768
	ds_read_b128 v[188:191], v167 offset:33792
	ds_read_b128 v[192:195], v167 offset:34816
	ds_read_b128 v[196:199], v167 offset:35840
	ds_read_b128 v[200:203], v167 offset:36864
	ds_read_b128 v[204:207], v167 offset:37888
	ds_read_b128 v[208:211], v167 offset:38912
	ds_read_b128 v[212:215], v167 offset:39936
	global_load_lds_dwordx4 v[228:229], off
	v_lshl_add_u64 v[228:229], s[36:37], 0, v[134:135]
	s_mov_b32 m0, s51
	s_nop 0
	global_load_lds_dwordx4 v[228:229], off
	s_waitcnt vmcnt(8)
	s_waitcnt lgkmcnt(0)
	s_barrier
	s_setprio 1
	s_waitcnt lgkmcnt(0)
	v_mfma_f32_16x16x32_bf16 v[124:127], v[128:131], v[184:187], v[124:127]
	v_mfma_f32_16x16x32_bf16 v[120:123], v[150:153], v[184:187], v[120:123]
	v_mfma_f32_16x16x32_bf16 v[108:111], v[128:131], v[192:195], v[108:111]
	v_mfma_f32_16x16x32_bf16 v[104:107], v[150:153], v[192:195], v[104:107]
	v_mfma_f32_16x16x32_bf16 v[92:95], v[128:131], v[200:203], v[92:95]
	v_mfma_f32_16x16x32_bf16 v[88:91], v[150:153], v[200:203], v[88:91]
	v_mfma_f32_16x16x32_bf16 v[76:79], v[128:131], v[208:211], v[76:79]
	v_mfma_f32_16x16x32_bf16 v[72:75], v[150:153], v[208:211], v[72:75]
	v_mfma_f32_16x16x32_bf16 v[124:127], v[146:149], v[188:191], v[124:127]
	v_mfma_f32_16x16x32_bf16 v[120:123], v[154:157], v[188:191], v[120:123]
	v_mfma_f32_16x16x32_bf16 v[108:111], v[146:149], v[196:199], v[108:111]
	v_mfma_f32_16x16x32_bf16 v[104:107], v[154:157], v[196:199], v[104:107]
	v_mfma_f32_16x16x32_bf16 v[92:95], v[146:149], v[204:207], v[92:95]
	v_mfma_f32_16x16x32_bf16 v[88:91], v[154:157], v[204:207], v[88:91]
	v_mfma_f32_16x16x32_bf16 v[76:79], v[146:149], v[212:215], v[76:79]
	v_mfma_f32_16x16x32_bf16 v[72:75], v[154:157], v[212:215], v[72:75]
	s_setprio 0
	s_setprio 1
	v_mfma_f32_16x16x32_bf16 v[116:119], v[158:161], v[184:187], v[116:119]
	v_mfma_f32_16x16x32_bf16 v[112:115], v[176:179], v[184:187], v[112:115]
	v_mfma_f32_16x16x32_bf16 v[100:103], v[158:161], v[192:195], v[100:103]
	v_mfma_f32_16x16x32_bf16 v[96:99], v[176:179], v[192:195], v[96:99]
	v_mfma_f32_16x16x32_bf16 v[84:87], v[158:161], v[200:203], v[84:87]
	v_mfma_f32_16x16x32_bf16 v[80:83], v[176:179], v[200:203], v[80:83]
	v_mfma_f32_16x16x32_bf16 v[68:71], v[158:161], v[208:211], v[68:71]
	v_mfma_f32_16x16x32_bf16 v[64:67], v[176:179], v[208:211], v[64:67]
	v_mfma_f32_16x16x32_bf16 v[116:119], v[172:175], v[188:191], v[116:119]
	v_mfma_f32_16x16x32_bf16 v[112:115], v[180:183], v[188:191], v[112:115]
	v_mfma_f32_16x16x32_bf16 v[100:103], v[172:175], v[196:199], v[100:103]
	v_mfma_f32_16x16x32_bf16 v[96:99], v[180:183], v[196:199], v[96:99]
	v_mfma_f32_16x16x32_bf16 v[84:87], v[172:175], v[204:207], v[84:87]
	v_mfma_f32_16x16x32_bf16 v[80:83], v[180:183], v[204:207], v[80:83]
	v_mfma_f32_16x16x32_bf16 v[68:71], v[172:175], v[212:215], v[68:71]
	v_mfma_f32_16x16x32_bf16 v[64:67], v[180:183], v[212:215], v[64:67]
	s_setprio 0
	s_barrier
; #define PG8_STAGE(bufoff, gbase, voff) do { _Pragma("unroll") for (int _i = 0; _i < 2; ++_i) \
;         __builtin_amdgcn_global_load_lds((const unsigned*)((const char*)(gbase) + (voff)[_i]), (PG8_LAS unsigned*)(lds + (bufoff) + ldsw + _i * 8192), 16, 0, 0); } while (0)
; #define PG8_LDA(dst, b, h) do { _Pragma("unroll") for (int m = 0; m < 4; ++m) _Pragma("unroll") for (int k = 0; k < 2; ++k) dst[m][k] = *(const PG8_LAS bf16x8*)(lds + PG8_SA(b, h) + aoff + m * 2048 + k * 1024); } while (0)
; #define PG8_MMA(ai, bj, At, Bt) do { __builtin_amdgcn_s_setprio(1); _Pragma("unroll") for (int m = 0; m < 4; ++m) _Pragma("unroll") for (int n = 0; n < 2; ++n) _Pragma("unroll") for (int k = 0; k < 2; ++k) \
;         acc[ai][bj][m][n] = __builtin_amdgcn_mfma_f32_16x16x32_bf16(Bt[n][k], At[m][k], acc[ai][bj][m][n], 0, 0, 0); __builtin_amdgcn_s_setprio(0); } while (0)
; #define PG8_WAIT_V(n) asm volatile("s_waitcnt vmcnt(" #n ")" ::: "memory")
; #define PG8_WAIT_L(n) asm volatile("s_waitcnt lgkmcnt(" #n ")" ::: "memory")
; #define PG8_BAR __builtin_amdgcn_s_barrier()
; #define PG8_SCHED __builtin_amdgcn_sched_barrier(0)
; template <class Epi, class Sched, bool ALIGN_EPI = false, bool SP2 = false>
; __device__ __forceinline__ void gemm_phase(PG8_LAS unsigned char* lds, const Gemm g, const Sched& S, const Epi& E, const int wid) {
;     ...
;         for (int t = 0; t < nt; t += 2) {
;             const bool last = (t == nt - 2);
;             const char* a1 = cA + (size_t)(t + 1) * kstep;
;             const char* a2 = last ? nA : cA + (size_t)(t + 2) * kstep; const char* b2 = last ? nB : cB + (size_t)(t + 2) * kstep;
;     ...
;             PG8_LDA(At, 1, 1); PG8_STAGE(PG8_SB(1, 0), b3, voffB); PG8_STAGE(PG8_SB(1, 1), b3 + hstep, voffB); PG8_STAGE(PG8_SA(1, 0), a3, voffA);
;             PG8_WAIT_V(8); PG8_WAIT_L(0); PG8_BAR; PG8_MMA(1, 0, At, B0); PG8_MMA(1, 1, At, B1); PG8_BAR; PG8_SCHED;
	s_add_i32 s33, s33, s40
	v_lshl_add_u64 v[216:217], v[216:217], 0, s[22:23]
	s_mov_b32 m0, s33
	ds_read_b128 v[184:187], v167 offset:49152
	ds_read_b128 v[188:191], v167 offset:50176
	ds_read_b128 v[192:195], v167 offset:51200
	ds_read_b128 v[196:199], v167 offset:52224
	ds_read_b128 v[200:203], v167 offset:53248
	ds_read_b128 v[204:207], v167 offset:54272
	ds_read_b128 v[208:211], v167 offset:55296
	ds_read_b128 v[212:215], v167 offset:56320
	global_load_lds_dwordx4 v[216:217], off
	v_lshl_add_u64 v[216:217], v[218:219], 0, s[22:23]
	s_add_i32 m0, s33, 0x2000
	s_add_i32 s33, s39, s40
	global_load_lds_dwordx4 v[216:217], off
	v_lshl_add_u64 v[216:217], v[220:221], 0, s[22:23]
	s_mov_b32 m0, s33
	s_nop 0
	global_load_lds_dwordx4 v[216:217], off
	v_lshl_add_u64 v[216:217], v[222:223], 0, s[22:23]
	s_add_i32 m0, s33, 0x2000
	s_nop 0
	global_load_lds_dwordx4 v[216:217], off
	v_lshl_add_u64 v[216:217], v[224:225], 0, s[22:23]
	s_mov_b32 m0, s53
	s_nop 0
	global_load_lds_dwordx4 v[216:217], off
	v_lshl_add_u64 v[216:217], v[226:227], 0, s[22:23]
	s_mov_b32 m0, s54
	s_nop 0
	global_load_lds_dwordx4 v[216:217], off
	s_waitcnt vmcnt(8)
	s_waitcnt lgkmcnt(0)
	s_barrier
	s_setprio 1
	s_waitcnt lgkmcnt(0)
	v_mfma_f32_16x16x32_bf16 v[60:63], v[128:131], v[184:187], v[60:63]
	v_mfma_f32_16x16x32_bf16 v[56:59], v[150:153], v[184:187], v[56:59]
	v_mfma_f32_16x16x32_bf16 v[44:47], v[128:131], v[192:195], v[44:47]
	v_mfma_f32_16x16x32_bf16 v[40:43], v[150:153], v[192:195], v[40:43]
	v_mfma_f32_16x16x32_bf16 v[28:31], v[128:131], v[200:203], v[28:31]
	v_mfma_f32_16x16x32_bf16 v[24:27], v[150:153], v[200:203], v[24:27]
	v_mfma_f32_16x16x32_bf16 v[12:15], v[128:131], v[208:211], v[12:15]
	v_mfma_f32_16x16x32_bf16 v[8:11], v[150:153], v[208:211], v[8:11]
	v_mfma_f32_16x16x32_bf16 v[60:63], v[146:149], v[188:191], v[60:63]
	v_mfma_f32_16x16x32_bf16 v[56:59], v[154:157], v[188:191], v[56:59]
	v_mfma_f32_16x16x32_bf16 v[44:47], v[146:149], v[196:199], v[44:47]
	v_mfma_f32_16x16x32_bf16 v[40:43], v[154:157], v[196:199], v[40:43]
	v_mfma_f32_16x16x32_bf16 v[28:31], v[146:149], v[204:207], v[28:31]
	v_mfma_f32_16x16x32_bf16 v[24:27], v[154:157], v[204:207], v[24:27]
	v_mfma_f32_16x16x32_bf16 v[12:15], v[146:149], v[212:215], v[12:15]
	v_mfma_f32_16x16x32_bf16 v[8:11], v[154:157], v[212:215], v[8:11]
	s_setprio 0
	s_setprio 1
	v_mfma_f32_16x16x32_bf16 v[52:55], v[158:161], v[184:187], v[52:55]
	v_mfma_f32_16x16x32_bf16 v[48:51], v[176:179], v[184:187], v[48:51]
	v_mfma_f32_16x16x32_bf16 v[36:39], v[158:161], v[192:195], v[36:39]
	v_mfma_f32_16x16x32_bf16 v[32:35], v[176:179], v[192:195], v[32:35]
	v_mfma_f32_16x16x32_bf16 v[20:23], v[158:161], v[200:203], v[20:23]
	v_mfma_f32_16x16x32_bf16 v[16:19], v[176:179], v[200:203], v[16:19]
	v_mfma_f32_16x16x32_bf16 v[4:7], v[158:161], v[208:211], v[4:7]
	v_mfma_f32_16x16x32_bf16 v[0:3], v[176:179], v[208:211], v[0:3]
	v_mfma_f32_16x16x32_bf16 v[52:55], v[172:175], v[188:191], v[52:55]
	v_mfma_f32_16x16x32_bf16 v[48:51], v[180:183], v[188:191], v[48:51]
	v_mfma_f32_16x16x32_bf16 v[36:39], v[172:175], v[196:199], v[36:39]
	v_mfma_f32_16x16x32_bf16 v[32:35], v[180:183], v[196:199], v[32:35]
	v_mfma_f32_16x16x32_bf16 v[20:23], v[172:175], v[204:207], v[20:23]
	v_mfma_f32_16x16x32_bf16 v[16:19], v[180:183], v[204:207], v[16:19]
	v_mfma_f32_16x16x32_bf16 v[4:7], v[172:175], v[212:215], v[4:7]
	v_mfma_f32_16x16x32_bf16 v[0:3], v[180:183], v[212:215], v[0:3]
	s_setprio 0
	s_barrier
	s_add_u32 s4, s4, 0x100
	s_addc_u32 s5, s5, 0
	s_add_u32 s0, s0, 0x100
	s_addc_u32 s1, s1, 0
	s_cmp_ge_i32 s38, s55
	s_mov_b32 s36, s38
	s_cbranch_scc0 .LBB0_20

; #define PG8_STAGE(bufoff, gbase, voff) do { _Pragma("unroll") for (int _i = 0; _i < 2; ++_i) \
;         __builtin_amdgcn_global_load_lds((const unsigned*)((const char*)(gbase) + (voff)[_i]), (PG8_LAS unsigned*)(lds + (bufoff) + ldsw + _i * 8192), 16, 0, 0); } while (0)
; #define PG8_LDA(dst, b, h) do { _Pragma("unroll") for (int m = 0; m < 4; ++m) _Pragma("unroll") for (int k = 0; k < 2; ++k) dst[m][k] = *(const PG8_LAS bf16x8*)(lds + PG8_SA(b, h) + aoff + m * 2048 + k * 1024); } while (0)
; #define PG8_LDB(dst, b, h) do { _Pragma("unroll") for (int n = 0; n < 2; ++n) _Pragma("unroll") for (int k = 0; k < 2; ++k) dst[n][k] = *(const PG8_LAS bf16x8*)(lds + PG8_SB(b, h) + boff + n * 2048 + k * 1024); } while (0)
; #define PG8_MMA(ai, bj, At, Bt) do { __builtin_amdgcn_s_setprio(1); _Pragma("unroll") for (int m = 0; m < 4; ++m) _Pragma("unroll") for (int n = 0; n < 2; ++n) _Pragma("unroll") for (int k = 0; k < 2; ++k) \
;         acc[ai][bj][m][n] = __builtin_amdgcn_mfma_f32_16x16x32_bf16(Bt[n][k], At[m][k], acc[ai][bj][m][n], 0, 0, 0); __builtin_amdgcn_s_setprio(0); } while (0)
; #define PG8_WAIT_V(n) asm volatile("s_waitcnt vmcnt(" #n ")" ::: "memory")
; #define PG8_WAIT_L(n) asm volatile("s_waitcnt lgkmcnt(" #n ")" ::: "memory")
; #define PG8_BAR __builtin_amdgcn_s_barrier()
; #define PG8_SCHED __builtin_amdgcn_sched_barrier(0)
; template <class Epi, class Sched, bool ALIGN_EPI = false, bool SP2 = false>
; __device__ __forceinline__ void gemm_phase(PG8_LAS unsigned char* lds, const Gemm g, const Sched& S, const Epi& E, const int wid) {
;     ...
;         for (int t = 0; t < nt; t += 2) {
;             const bool last = (t == nt - 2);
;             const char* a1 = cA + (size_t)(t + 1) * kstep;
;             const char* a2 = last ? nA : cA + (size_t)(t + 2) * kstep; const char* b2 = last ? nB : cB + (size_t)(t + 2) * kstep;
;             const char* a3 = a2 + kstep; const char* b3 = b2 + kstep;
;             if (last && has_next) S.a_ready(nxt);
;             if constexpr (SP2) {
;             PG8_LDB(B0, 0, 0); PG8_LDB(B1, 0, 1); PG8_SCHED; PG8_LDA(At, 0, 0); PG8_STAGE(PG8_SA(1, 1), a1 + hstep, voffA);
;             PG8_WAIT_V(8); PG8_WAIT_L(0); PG8_BAR; PG8_MMA(0, 0, At, B0); PG8_MMA(0, 1, At, B1); PG8_BAR; PG8_SCHED;
.LBB0_1100:
	ds_read_b128 v[44:47], v163
	ds_read_b128 v[52:55], v163 offset:1024
	ds_read_b128 v[60:63], v163 offset:2048
	ds_read_b128 v[68:71], v163 offset:3072
	ds_read_b128 v[166:169], v164
	ds_read_b128 v[170:173], v164 offset:1024
	ds_read_b128 v[174:177], v164 offset:2048
	ds_read_b128 v[178:181], v164 offset:3072
	s_add_i32 s8, s6, 2
	s_add_u32 s9, s4, 0x80
	s_addc_u32 s7, s5, 0
	s_cmp_eq_u32 s72, s6
	s_cselect_b32 s6, s48, s9
	s_cselect_b32 s7, s49, s7
	s_cselect_b32 s77, s51, s1
	s_cselect_b32 s76, s50, s0
	v_lshl_add_u64 v[158:159], s[4:5], 0, v[152:153]
	s_add_i32 m0, s63, 0xc000
	ds_read_b128 v[182:185], v165
	ds_read_b128 v[186:189], v165 offset:1024
	ds_read_b128 v[190:193], v165 offset:2048
	ds_read_b128 v[194:197], v165 offset:3072
	ds_read_b128 v[198:201], v165 offset:4096
	ds_read_b128 v[202:205], v165 offset:5120
	ds_read_b128 v[206:209], v165 offset:6144
	ds_read_b128 v[210:213], v165 offset:7168
	global_load_lds_dwordx4 v[158:159], off
	v_lshl_add_u64 v[158:159], s[4:5], 0, v[154:155]
	s_add_i32 m0, s63, 0xe000
	s_nop 0
	global_load_lds_dwordx4 v[158:159], off
	s_cmp_lg_u32 s8, 2
	s_cbranch_scc1 .Lw8__1100_0
	s_cmp_eq_u32 s67, 1
	s_cbranch_scc1 .Lw8__1100_0
	s_waitcnt vmcnt(24)
	s_branch .Lwj__1100_0

; #define PG8_STAGE(bufoff, gbase, voff) do { _Pragma("unroll") for (int _i = 0; _i < 2; ++_i) \
;         __builtin_amdgcn_global_load_lds((const unsigned*)((const char*)(gbase) + (voff)[_i]), (PG8_LAS unsigned*)(lds + (bufoff) + ldsw + _i * 8192), 16, 0, 0); } while (0)
; #define PG8_LDA(dst, b, h) do { _Pragma("unroll") for (int m = 0; m < 4; ++m) _Pragma("unroll") for (int k = 0; k < 2; ++k) dst[m][k] = *(const PG8_LAS bf16x8*)(lds + PG8_SA(b, h) + aoff + m * 2048 + k * 1024); } while (0)
; #define PG8_MMA(ai, bj, At, Bt) do { __builtin_amdgcn_s_setprio(1); _Pragma("unroll") for (int m = 0; m < 4; ++m) _Pragma("unroll") for (int n = 0; n < 2; ++n) _Pragma("unroll") for (int k = 0; k < 2; ++k) \
;         acc[ai][bj][m][n] = __builtin_amdgcn_mfma_f32_16x16x32_bf16(Bt[n][k], At[m][k], acc[ai][bj][m][n], 0, 0, 0); __builtin_amdgcn_s_setprio(0); } while (0)
; #define PG8_WAIT_V(n) asm volatile("s_waitcnt vmcnt(" #n ")" ::: "memory")
; #define PG8_WAIT_L(n) asm volatile("s_waitcnt lgkmcnt(" #n ")" ::: "memory")
; #define PG8_BAR __builtin_amdgcn_s_barrier()
; #define PG8_SCHED __builtin_amdgcn_sched_barrier(0)
; template <class Epi, class Sched, bool ALIGN_EPI = false, bool SP2 = false>
; __device__ __forceinline__ void gemm_phase(PG8_LAS unsigned char* lds, const Gemm g, const Sched& S, const Epi& E, const int wid) {
;     ...
;             PG8_WAIT_V(8); PG8_WAIT_L(0); PG8_BAR; PG8_MMA(0, 0, At, B0); PG8_MMA(0, 1, At, B1); PG8_BAR; PG8_SCHED;
;             PG8_LDA(At, 0, 1); PG8_STAGE(PG8_SB(0, 0), b2, voffB); PG8_STAGE(PG8_SB(0, 1), b2 + hstep, voffB); PG8_STAGE(PG8_SA(0, 0), a2, voffA);
;             PG8_WAIT_V(8); PG8_WAIT_L(0); PG8_BAR; PG8_MMA(1, 0, At, B0); PG8_MMA(1, 1, At, B1); PG8_BAR; PG8_SCHED;
.Lwj__1100_0:
	s_waitcnt lgkmcnt(0)
	s_barrier
	s_setprio 1
	s_waitcnt lgkmcnt(0)
	v_mfma_f32_16x16x32_bf16 v[140:143], v[44:47], v[182:185], v[140:143]
	v_mfma_f32_16x16x32_bf16 v[136:139], v[60:63], v[182:185], v[136:139]
	v_mfma_f32_16x16x32_bf16 v[124:127], v[44:47], v[190:193], v[124:127]
	v_mfma_f32_16x16x32_bf16 v[120:123], v[60:63], v[190:193], v[120:123]
	v_mfma_f32_16x16x32_bf16 v[108:111], v[44:47], v[198:201], v[108:111]
	v_mfma_f32_16x16x32_bf16 v[104:107], v[60:63], v[198:201], v[104:107]
	v_mfma_f32_16x16x32_bf16 v[92:95], v[44:47], v[206:209], v[92:95]
	v_mfma_f32_16x16x32_bf16 v[88:91], v[60:63], v[206:209], v[88:91]
	v_mfma_f32_16x16x32_bf16 v[140:143], v[52:55], v[186:189], v[140:143]
	v_mfma_f32_16x16x32_bf16 v[136:139], v[68:71], v[186:189], v[136:139]
	v_mfma_f32_16x16x32_bf16 v[124:127], v[52:55], v[194:197], v[124:127]
	v_mfma_f32_16x16x32_bf16 v[120:123], v[68:71], v[194:197], v[120:123]
	v_mfma_f32_16x16x32_bf16 v[108:111], v[52:55], v[202:205], v[108:111]
	v_mfma_f32_16x16x32_bf16 v[104:107], v[68:71], v[202:205], v[104:107]
	v_mfma_f32_16x16x32_bf16 v[92:95], v[52:55], v[210:213], v[92:95]
	v_mfma_f32_16x16x32_bf16 v[88:91], v[68:71], v[210:213], v[88:91]
	s_setprio 0
	s_setprio 1
	v_mfma_f32_16x16x32_bf16 v[132:135], v[166:169], v[182:185], v[132:135]
	v_mfma_f32_16x16x32_bf16 v[128:131], v[174:177], v[182:185], v[128:131]
	v_mfma_f32_16x16x32_bf16 v[116:119], v[166:169], v[190:193], v[116:119]
	v_mfma_f32_16x16x32_bf16 v[112:115], v[174:177], v[190:193], v[112:115]
	v_mfma_f32_16x16x32_bf16 v[100:103], v[166:169], v[198:201], v[100:103]
	v_mfma_f32_16x16x32_bf16 v[96:99], v[174:177], v[198:201], v[96:99]
	v_mfma_f32_16x16x32_bf16 v[84:87], v[166:169], v[206:209], v[84:87]
	v_mfma_f32_16x16x32_bf16 v[80:83], v[174:177], v[206:209], v[80:83]
	v_mfma_f32_16x16x32_bf16 v[132:135], v[170:173], v[186:189], v[132:135]
	v_mfma_f32_16x16x32_bf16 v[128:131], v[178:181], v[186:189], v[128:131]
	v_mfma_f32_16x16x32_bf16 v[116:119], v[170:173], v[194:197], v[116:119]
	v_mfma_f32_16x16x32_bf16 v[112:115], v[178:181], v[194:197], v[112:115]
	v_mfma_f32_16x16x32_bf16 v[100:103], v[170:173], v[202:205], v[100:103]
	v_mfma_f32_16x16x32_bf16 v[96:99], v[178:181], v[202:205], v[96:99]
	v_mfma_f32_16x16x32_bf16 v[84:87], v[170:173], v[210:213], v[84:87]
	v_mfma_f32_16x16x32_bf16 v[80:83], v[178:181], v[210:213], v[80:83]
	s_setprio 0
	s_barrier
	s_add_i32 s9, s75, s55
	v_lshl_add_u64 v[158:159], s[76:77], 0, v[148:149]
	s_mov_b32 m0, s9
	ds_read_b128 v[182:185], v165 offset:16384
	ds_read_b128 v[186:189], v165 offset:17408
	ds_read_b128 v[190:193], v165 offset:18432
	ds_read_b128 v[194:197], v165 offset:19456
	ds_read_b128 v[198:201], v165 offset:20480
	ds_read_b128 v[202:205], v165 offset:21504
	ds_read_b128 v[206:209], v165 offset:22528
	ds_read_b128 v[210:213], v165 offset:23552
	global_load_lds_dwordx4 v[158:159], off
	s_add_i32 m0, s9, 0x2000
	v_lshl_add_u64 v[214:215], s[76:77], 0, v[144:145]
	s_add_u32 s76, s76, s12
	s_addc_u32 s77, s77, s13
	s_add_i32 s9, s78, s55
	global_load_lds_dwordx4 v[214:215], off
	v_lshl_add_u64 v[216:217], s[76:77], 0, v[148:149]
	s_mov_b32 m0, s9
	v_lshl_add_u64 v[218:219], s[76:77], 0, v[144:145]
	global_load_lds_dwordx4 v[216:217], off
	s_add_i32 m0, s9, 0x2000
	v_lshl_add_u64 v[220:221], s[6:7], 0, v[150:151]
	global_load_lds_dwordx4 v[218:219], off
	s_mov_b32 m0, s63
	v_lshl_add_u64 v[222:223], s[6:7], 0, v[146:147]
	global_load_lds_dwordx4 v[220:221], off
	s_mov_b32 m0, s64
	s_nop 0
	global_load_lds_dwordx4 v[222:223], off
	s_cmp_lg_u32 s8, 2
	s_cbranch_scc1 .Lw8__1100_1
	s_cmp_eq_u32 s67, 1
	s_cbranch_scc1 .Lw8__1100_1
	s_waitcnt vmcnt(24)
	s_branch .Lwj__1100_1

; #define PG8_STAGE(bufoff, gbase, voff) do { _Pragma("unroll") for (int _i = 0; _i < 2; ++_i) \
;         __builtin_amdgcn_global_load_lds((const unsigned*)((const char*)(gbase) + (voff)[_i]), (PG8_LAS unsigned*)(lds + (bufoff) + ldsw + _i * 8192), 16, 0, 0); } while (0)
; #define PG8_LDA(dst, b, h) do { _Pragma("unroll") for (int m = 0; m < 4; ++m) _Pragma("unroll") for (int k = 0; k < 2; ++k) dst[m][k] = *(const PG8_LAS bf16x8*)(lds + PG8_SA(b, h) + aoff + m * 2048 + k * 1024); } while (0)
; #define PG8_LDB(dst, b, h) do { _Pragma("unroll") for (int n = 0; n < 2; ++n) _Pragma("unroll") for (int k = 0; k < 2; ++k) dst[n][k] = *(const PG8_LAS bf16x8*)(lds + PG8_SB(b, h) + boff + n * 2048 + k * 1024); } while (0)
; #define PG8_MMA(ai, bj, At, Bt) do { __builtin_amdgcn_s_setprio(1); _Pragma("unroll") for (int m = 0; m < 4; ++m) _Pragma("unroll") for (int n = 0; n < 2; ++n) _Pragma("unroll") for (int k = 0; k < 2; ++k) \
;         acc[ai][bj][m][n] = __builtin_amdgcn_mfma_f32_16x16x32_bf16(Bt[n][k], At[m][k], acc[ai][bj][m][n], 0, 0, 0); __builtin_amdgcn_s_setprio(0); } while (0)
; #define PG8_WAIT_V(n) asm volatile("s_waitcnt vmcnt(" #n ")" ::: "memory")
; #define PG8_WAIT_L(n) asm volatile("s_waitcnt lgkmcnt(" #n ")" ::: "memory")
; #define PG8_BAR __builtin_amdgcn_s_barrier()
; #define PG8_SCHED __builtin_amdgcn_sched_barrier(0)
; template <class Epi, class Sched, bool ALIGN_EPI = false, bool SP2 = false>
; __device__ __forceinline__ void gemm_phase(PG8_LAS unsigned char* lds, const Gemm g, const Sched& S, const Epi& E, const int wid) {
;     ...
;             PG8_WAIT_V(8); PG8_WAIT_L(0); PG8_BAR; PG8_MMA(1, 0, At, B0); PG8_MMA(1, 1, At, B1); PG8_BAR; PG8_SCHED;
;             PG8_LDB(B0, 1, 0); PG8_LDB(B1, 1, 1); PG8_SCHED; PG8_LDA(At, 1, 0); PG8_STAGE(PG8_SA(0, 1), a2 + hstep, voffA);
;             PG8_WAIT_V(8); PG8_WAIT_L(0); PG8_BAR; PG8_MMA(0, 0, At, B0); PG8_MMA(0, 1, At, B1); PG8_BAR; PG8_SCHED;
.Lwj__1100_1:
	s_waitcnt lgkmcnt(0)
	s_barrier
	s_setprio 1
	s_waitcnt lgkmcnt(0)
	v_mfma_f32_16x16x32_bf16 v[76:79], v[44:47], v[182:185], v[76:79]
	v_mfma_f32_16x16x32_bf16 v[72:75], v[60:63], v[182:185], v[72:75]
	v_mfma_f32_16x16x32_bf16 v[48:51], v[44:47], v[190:193], v[48:51]
	v_mfma_f32_16x16x32_bf16 v[40:43], v[60:63], v[190:193], v[40:43]
	v_mfma_f32_16x16x32_bf16 v[28:31], v[44:47], v[198:201], v[28:31]
	v_mfma_f32_16x16x32_bf16 v[24:27], v[60:63], v[198:201], v[24:27]
	v_mfma_f32_16x16x32_bf16 v[12:15], v[44:47], v[206:209], v[12:15]
	v_mfma_f32_16x16x32_bf16 v[8:11], v[60:63], v[206:209], v[8:11]
	v_mfma_f32_16x16x32_bf16 v[76:79], v[52:55], v[186:189], v[76:79]
	v_mfma_f32_16x16x32_bf16 v[72:75], v[68:71], v[186:189], v[72:75]
	v_mfma_f32_16x16x32_bf16 v[48:51], v[52:55], v[194:197], v[48:51]
	v_mfma_f32_16x16x32_bf16 v[40:43], v[68:71], v[194:197], v[40:43]
	v_mfma_f32_16x16x32_bf16 v[28:31], v[52:55], v[202:205], v[28:31]
	v_mfma_f32_16x16x32_bf16 v[24:27], v[68:71], v[202:205], v[24:27]
	v_mfma_f32_16x16x32_bf16 v[12:15], v[52:55], v[210:213], v[12:15]
	v_mfma_f32_16x16x32_bf16 v[8:11], v[68:71], v[210:213], v[8:11]
	s_setprio 0
	s_setprio 1
	v_mfma_f32_16x16x32_bf16 v[36:39], v[166:169], v[190:193], v[36:39]
	v_mfma_f32_16x16x32_bf16 v[32:35], v[174:177], v[190:193], v[32:35]
	v_mfma_f32_16x16x32_bf16 v[20:23], v[166:169], v[198:201], v[20:23]
	v_mfma_f32_16x16x32_bf16 v[16:19], v[174:177], v[198:201], v[16:19]
	v_mfma_f32_16x16x32_bf16 v[4:7], v[166:169], v[206:209], v[4:7]
	v_mfma_f32_16x16x32_bf16 v[0:3], v[174:177], v[206:209], v[0:3]
	v_mfma_f32_16x16x32_bf16 v[44:47], v[166:169], v[182:185], v[64:67]
	v_mfma_f32_16x16x32_bf16 v[52:55], v[174:177], v[182:185], v[56:59]
	v_mfma_f32_16x16x32_bf16 v[36:39], v[170:173], v[194:197], v[36:39]
	v_mfma_f32_16x16x32_bf16 v[32:35], v[178:181], v[194:197], v[32:35]
	v_mfma_f32_16x16x32_bf16 v[20:23], v[170:173], v[202:205], v[20:23]
	v_mfma_f32_16x16x32_bf16 v[16:19], v[178:181], v[202:205], v[16:19]
	v_mfma_f32_16x16x32_bf16 v[4:7], v[170:173], v[210:213], v[4:7]
	v_mfma_f32_16x16x32_bf16 v[0:3], v[178:181], v[210:213], v[0:3]
	v_mfma_f32_16x16x32_bf16 v[44:47], v[170:173], v[186:189], v[44:47]
	v_mfma_f32_16x16x32_bf16 v[52:55], v[178:181], v[186:189], v[52:55]
	s_setprio 0
	s_barrier
	s_add_i32 s9, 0, 0x18000
	s_add_i32 s33, 0, 0x1c000
	v_add_u32_e32 v68, s9, v162
	v_add_u32_e32 v178, s33, v162
	ds_read_b128 v[56:59], v68
	ds_read_b128 v[60:63], v68 offset:1024
	ds_read_b128 v[64:67], v68 offset:2048
	ds_read_b128 v[68:71], v68 offset:3072
	ds_read_b128 v[166:169], v178
	ds_read_b128 v[170:173], v178 offset:1024
	ds_read_b128 v[174:177], v178 offset:2048
	ds_read_b128 v[178:181], v178 offset:3072
	s_add_u32 s6, s6, s12
	s_addc_u32 s7, s7, s13
	s_mov_b32 m0, s65
	v_lshl_add_u64 v[224:225], s[6:7], 0, v[150:151]
	ds_read_b128 v[182:185], v165 offset:32768
	ds_read_b128 v[186:189], v165 offset:33792
	ds_read_b128 v[190:193], v165 offset:34816
	ds_read_b128 v[194:197], v165 offset:35840
	ds_read_b128 v[198:201], v165 offset:36864
	ds_read_b128 v[202:205], v165 offset:37888
	ds_read_b128 v[206:209], v165 offset:38912
	ds_read_b128 v[210:213], v165 offset:39936
	global_load_lds_dwordx4 v[224:225], off
	v_lshl_add_u64 v[224:225], s[6:7], 0, v[146:147]
	s_mov_b32 m0, s66
	s_nop 0
	global_load_lds_dwordx4 v[224:225], off
	s_waitcnt vmcnt(8)
	s_waitcnt lgkmcnt(0)
	s_barrier
	s_setprio 1
	s_waitcnt lgkmcnt(0)
	v_mfma_f32_16x16x32_bf16 v[140:143], v[56:59], v[182:185], v[140:143]
	v_mfma_f32_16x16x32_bf16 v[136:139], v[64:67], v[182:185], v[136:139]
	v_mfma_f32_16x16x32_bf16 v[124:127], v[56:59], v[190:193], v[124:127]
	v_mfma_f32_16x16x32_bf16 v[120:123], v[64:67], v[190:193], v[120:123]
	v_mfma_f32_16x16x32_bf16 v[108:111], v[56:59], v[198:201], v[108:111]
	v_mfma_f32_16x16x32_bf16 v[104:107], v[64:67], v[198:201], v[104:107]
	v_mfma_f32_16x16x32_bf16 v[92:95], v[56:59], v[206:209], v[92:95]
	v_mfma_f32_16x16x32_bf16 v[88:91], v[64:67], v[206:209], v[88:91]
	v_mfma_f32_16x16x32_bf16 v[140:143], v[60:63], v[186:189], v[140:143]
	v_mfma_f32_16x16x32_bf16 v[136:139], v[68:71], v[186:189], v[136:139]
	v_mfma_f32_16x16x32_bf16 v[124:127], v[60:63], v[194:197], v[124:127]
	v_mfma_f32_16x16x32_bf16 v[120:123], v[68:71], v[194:197], v[120:123]
	v_mfma_f32_16x16x32_bf16 v[108:111], v[60:63], v[202:205], v[108:111]
	v_mfma_f32_16x16x32_bf16 v[104:107], v[68:71], v[202:205], v[104:107]
	v_mfma_f32_16x16x32_bf16 v[92:95], v[60:63], v[210:213], v[92:95]
	v_mfma_f32_16x16x32_bf16 v[88:91], v[68:71], v[210:213], v[88:91]
	s_setprio 0
	s_setprio 1
	v_mfma_f32_16x16x32_bf16 v[132:135], v[166:169], v[182:185], v[132:135]
	v_mfma_f32_16x16x32_bf16 v[128:131], v[174:177], v[182:185], v[128:131]
	v_mfma_f32_16x16x32_bf16 v[116:119], v[166:169], v[190:193], v[116:119]
	v_mfma_f32_16x16x32_bf16 v[112:115], v[174:177], v[190:193], v[112:115]
	v_mfma_f32_16x16x32_bf16 v[100:103], v[166:169], v[198:201], v[100:103]
	v_mfma_f32_16x16x32_bf16 v[96:99], v[174:177], v[198:201], v[96:99]
	v_mfma_f32_16x16x32_bf16 v[84:87], v[166:169], v[206:209], v[84:87]
	v_mfma_f32_16x16x32_bf16 v[80:83], v[174:177], v[206:209], v[80:83]
	v_mfma_f32_16x16x32_bf16 v[132:135], v[170:173], v[186:189], v[132:135]
	v_mfma_f32_16x16x32_bf16 v[128:131], v[178:181], v[186:189], v[128:131]
	v_mfma_f32_16x16x32_bf16 v[116:119], v[170:173], v[194:197], v[116:119]
	v_mfma_f32_16x16x32_bf16 v[112:115], v[178:181], v[194:197], v[112:115]
	v_mfma_f32_16x16x32_bf16 v[100:103], v[170:173], v[202:205], v[100:103]
	v_mfma_f32_16x16x32_bf16 v[96:99], v[178:181], v[202:205], v[96:99]
	v_mfma_f32_16x16x32_bf16 v[84:87], v[170:173], v[210:213], v[84:87]
	v_mfma_f32_16x16x32_bf16 v[80:83], v[178:181], v[210:213], v[80:83]
	s_setprio 0
	s_barrier
; #define PG8_STAGE(bufoff, gbase, voff) do { _Pragma("unroll") for (int _i = 0; _i < 2; ++_i) \
;         __builtin_amdgcn_global_load_lds((const unsigned*)((const char*)(gbase) + (voff)[_i]), (PG8_LAS unsigned*)(lds + (bufoff) + ldsw + _i * 8192), 16, 0, 0); } while (0)
; #define PG8_LDA(dst, b, h) do { _Pragma("unroll") for (int m = 0; m < 4; ++m) _Pragma("unroll") for (int k = 0; k < 2; ++k) dst[m][k] = *(const PG8_LAS bf16x8*)(lds + PG8_SA(b, h) + aoff + m * 2048 + k * 1024); } while (0)
; #define PG8_MMA(ai, bj, At, Bt) do { __builtin_amdgcn_s_setprio(1); _Pragma("unroll") for (int m = 0; m < 4; ++m) _Pragma("unroll") for (int n = 0; n < 2; ++n) _Pragma("unroll") for (int k = 0; k < 2; ++k) \
;         acc[ai][bj][m][n] = __builtin_amdgcn_mfma_f32_16x16x32_bf16(Bt[n][k], At[m][k], acc[ai][bj][m][n], 0, 0, 0); __builtin_amdgcn_s_setprio(0); } while (0)
; #define PG8_WAIT_V(n) asm volatile("s_waitcnt vmcnt(" #n ")" ::: "memory")
; #define PG8_WAIT_L(n) asm volatile("s_waitcnt lgkmcnt(" #n ")" ::: "memory")
; #define PG8_BAR __builtin_amdgcn_s_barrier()
; #define PG8_SCHED __builtin_amdgcn_sched_barrier(0)
; template <class Epi, class Sched, bool ALIGN_EPI = false, bool SP2 = false>
; __device__ __forceinline__ void gemm_phase(PG8_LAS unsigned char* lds, const Gemm g, const Sched& S, const Epi& E, const int wid) {
;     ...
;         for (int t = 0; t < nt; t += 2) {
;             const bool last = (t == nt - 2);
;             const char* a1 = cA + (size_t)(t + 1) * kstep;
;             const char* a2 = last ? nA : cA + (size_t)(t + 2) * kstep; const char* b2 = last ? nB : cB + (size_t)(t + 2) * kstep;
;     ...
;             PG8_LDA(At, 1, 1); PG8_STAGE(PG8_SB(1, 0), b3, voffB); PG8_STAGE(PG8_SB(1, 1), b3 + hstep, voffB); PG8_STAGE(PG8_SA(1, 0), a3, voffA);
;             PG8_WAIT_V(8); PG8_WAIT_L(0); PG8_BAR; PG8_MMA(1, 0, At, B0); PG8_MMA(1, 1, At, B1); PG8_BAR; PG8_SCHED;
	s_add_i32 s6, s9, s55
	v_lshl_add_u64 v[158:159], v[158:159], 0, s[26:27]
	s_mov_b32 m0, s6
	ds_read_b128 v[182:185], v165 offset:49152
	ds_read_b128 v[186:189], v165 offset:50176
	ds_read_b128 v[190:193], v165 offset:51200
	ds_read_b128 v[194:197], v165 offset:52224
	ds_read_b128 v[198:201], v165 offset:53248
	ds_read_b128 v[202:205], v165 offset:54272
	ds_read_b128 v[206:209], v165 offset:55296
	ds_read_b128 v[210:213], v165 offset:56320
	global_load_lds_dwordx4 v[158:159], off
	v_lshl_add_u64 v[158:159], v[214:215], 0, s[26:27]
	s_add_i32 m0, s6, 0x2000
	s_add_i32 s6, s33, s55
	global_load_lds_dwordx4 v[158:159], off
	v_lshl_add_u64 v[158:159], v[216:217], 0, s[26:27]
	s_mov_b32 m0, s6
	s_nop 0
	global_load_lds_dwordx4 v[158:159], off
	v_lshl_add_u64 v[158:159], v[218:219], 0, s[26:27]
	s_add_i32 m0, s6, 0x2000
	s_nop 0
	global_load_lds_dwordx4 v[158:159], off
	v_lshl_add_u64 v[158:159], v[220:221], 0, s[26:27]
	s_mov_b32 m0, s68
	s_nop 0
	global_load_lds_dwordx4 v[158:159], off
	v_lshl_add_u64 v[158:159], v[222:223], 0, s[26:27]
	s_mov_b32 m0, s69
	s_nop 0
	global_load_lds_dwordx4 v[158:159], off
	s_waitcnt vmcnt(8)
	s_waitcnt lgkmcnt(0)
	s_barrier
	s_setprio 1
	s_waitcnt lgkmcnt(0)
	v_mfma_f32_16x16x32_bf16 v[76:79], v[56:59], v[182:185], v[76:79]
	v_mfma_f32_16x16x32_bf16 v[72:75], v[64:67], v[182:185], v[72:75]
	v_mfma_f32_16x16x32_bf16 v[48:51], v[56:59], v[190:193], v[48:51]
	v_mfma_f32_16x16x32_bf16 v[40:43], v[64:67], v[190:193], v[40:43]
	v_mfma_f32_16x16x32_bf16 v[28:31], v[56:59], v[198:201], v[28:31]
	v_mfma_f32_16x16x32_bf16 v[24:27], v[64:67], v[198:201], v[24:27]
	v_mfma_f32_16x16x32_bf16 v[12:15], v[56:59], v[206:209], v[12:15]
	v_mfma_f32_16x16x32_bf16 v[8:11], v[64:67], v[206:209], v[8:11]
	v_mfma_f32_16x16x32_bf16 v[76:79], v[60:63], v[186:189], v[76:79]
	v_mfma_f32_16x16x32_bf16 v[72:75], v[68:71], v[186:189], v[72:75]
	v_mfma_f32_16x16x32_bf16 v[48:51], v[60:63], v[194:197], v[48:51]
	v_mfma_f32_16x16x32_bf16 v[40:43], v[68:71], v[194:197], v[40:43]
	v_mfma_f32_16x16x32_bf16 v[28:31], v[60:63], v[202:205], v[28:31]
	v_mfma_f32_16x16x32_bf16 v[24:27], v[68:71], v[202:205], v[24:27]
	v_mfma_f32_16x16x32_bf16 v[12:15], v[60:63], v[210:213], v[12:15]
	v_mfma_f32_16x16x32_bf16 v[8:11], v[68:71], v[210:213], v[8:11]
	s_setprio 0
	s_setprio 1
	v_mfma_f32_16x16x32_bf16 v[44:47], v[166:169], v[182:185], v[44:47]
	v_mfma_f32_16x16x32_bf16 v[64:67], v[170:173], v[186:189], v[44:47]
	v_mfma_f32_16x16x32_bf16 v[44:47], v[174:177], v[182:185], v[52:55]
	v_mfma_f32_16x16x32_bf16 v[36:39], v[166:169], v[190:193], v[36:39]
	v_mfma_f32_16x16x32_bf16 v[32:35], v[174:177], v[190:193], v[32:35]
	v_mfma_f32_16x16x32_bf16 v[20:23], v[166:169], v[198:201], v[20:23]
	v_mfma_f32_16x16x32_bf16 v[16:19], v[174:177], v[198:201], v[16:19]
	v_mfma_f32_16x16x32_bf16 v[4:7], v[166:169], v[206:209], v[4:7]
	v_mfma_f32_16x16x32_bf16 v[0:3], v[174:177], v[206:209], v[0:3]
	v_mfma_f32_16x16x32_bf16 v[56:59], v[178:181], v[186:189], v[44:47]
	v_mfma_f32_16x16x32_bf16 v[36:39], v[170:173], v[194:197], v[36:39]
	v_mfma_f32_16x16x32_bf16 v[32:35], v[178:181], v[194:197], v[32:35]
	v_mfma_f32_16x16x32_bf16 v[20:23], v[170:173], v[202:205], v[20:23]
	v_mfma_f32_16x16x32_bf16 v[16:19], v[178:181], v[202:205], v[16:19]
	v_mfma_f32_16x16x32_bf16 v[4:7], v[170:173], v[210:213], v[4:7]
	v_mfma_f32_16x16x32_bf16 v[0:3], v[178:181], v[210:213], v[0:3]
	s_setprio 0
	s_barrier
	s_add_u32 s4, s4, 0x100
	s_addc_u32 s5, s5, 0
	s_add_u32 s0, s0, 0x100
	s_addc_u32 s1, s1, 0
	s_cmp_ge_i32 s8, s70
	s_mov_b32 s6, s8
	s_cbranch_scc0 .LBB0_1100

; #define PG8_STAGE(bufoff, gbase, voff) do { _Pragma("unroll") for (int _i = 0; _i < 2; ++_i) \
;         __builtin_amdgcn_global_load_lds((const unsigned*)((const char*)(gbase) + (voff)[_i]), (PG8_LAS unsigned*)(lds + (bufoff) + ldsw + _i * 8192), 16, 0, 0); } while (0)
; #define PG8_LDA(dst, b, h) do { _Pragma("unroll") for (int m = 0; m < 4; ++m) _Pragma("unroll") for (int k = 0; k < 2; ++k) dst[m][k] = *(const PG8_LAS bf16x8*)(lds + PG8_SA(b, h) + aoff + m * 2048 + k * 1024); } while (0)
; #define PG8_LDB(dst, b, h) do { _Pragma("unroll") for (int n = 0; n < 2; ++n) _Pragma("unroll") for (int k = 0; k < 2; ++k) dst[n][k] = *(const PG8_LAS bf16x8*)(lds + PG8_SB(b, h) + boff + n * 2048 + k * 1024); } while (0)
; #define PG8_MMA(ai, bj, At, Bt) do { __builtin_amdgcn_s_setprio(1); _Pragma("unroll") for (int m = 0; m < 4; ++m) _Pragma("unroll") for (int n = 0; n < 2; ++n) _Pragma("unroll") for (int k = 0; k < 2; ++k) \
;         acc[ai][bj][m][n] = __builtin_amdgcn_mfma_f32_16x16x32_bf16(Bt[n][k], At[m][k], acc[ai][bj][m][n], 0, 0, 0); __builtin_amdgcn_s_setprio(0); } while (0)
; #define PG8_WAIT_V(n) asm volatile("s_waitcnt vmcnt(" #n ")" ::: "memory")
; #define PG8_WAIT_L(n) asm volatile("s_waitcnt lgkmcnt(" #n ")" ::: "memory")
; #define PG8_BAR __builtin_amdgcn_s_barrier()
; #define PG8_SCHED __builtin_amdgcn_sched_barrier(0)
; template <class Epi, class Sched, bool ALIGN_EPI = false, bool SP2 = false>
; __device__ __forceinline__ void gemm_phase(PG8_LAS unsigned char* lds, const Gemm g, const Sched& S, const Epi& E, const int wid) {
;     ...
;         for (int t = 0; t < nt; t += 2) {
;             const bool last = (t == nt - 2);
;             const char* a1 = cA + (size_t)(t + 1) * kstep;
;             const char* a2 = last ? nA : cA + (size_t)(t + 2) * kstep; const char* b2 = last ? nB : cB + (size_t)(t + 2) * kstep;
;             const char* a3 = a2 + kstep; const char* b3 = b2 + kstep;
;             if (last && has_next) S.a_ready(nxt);
;             if constexpr (SP2) {
;             PG8_LDB(B0, 0, 0); PG8_LDB(B1, 0, 1); PG8_SCHED; PG8_LDA(At, 0, 0); PG8_STAGE(PG8_SA(1, 1), a1 + hstep, voffA);
;             PG8_WAIT_V(8); PG8_WAIT_L(0); PG8_BAR; PG8_MMA(0, 0, At, B0); PG8_MMA(0, 1, At, B1); PG8_BAR; PG8_SCHED;
.LBB0_1179:
	ds_read_b128 v[142:145], v149
	ds_read_b128 v[152:155], v149 offset:1024
	ds_read_b128 v[156:159], v149 offset:2048
	ds_read_b128 v[160:163], v149 offset:3072
	ds_read_b128 v[164:167], v150
	ds_read_b128 v[168:171], v150 offset:1024
	ds_read_b128 v[172:175], v150 offset:2048
	ds_read_b128 v[176:179], v150 offset:3072
	s_add_i32 s61, s28, 2
	s_add_u32 s33, s26, 0x80
	s_addc_u32 s29, s27, 0
	s_cmp_eq_u32 s53, s28
	s_cselect_b32 s28, s4, s33
	s_cselect_b32 s29, s5, s29
	s_cselect_b32 s63, s25, s1
	s_cselect_b32 s62, s24, s0
	v_lshl_add_u64 v[212:213], s[26:27], 0, v[136:137]
	s_add_i32 m0, s42, 0xc000
	ds_read_b128 v[180:183], v151
	ds_read_b128 v[184:187], v151 offset:1024
	ds_read_b128 v[188:191], v151 offset:2048
	ds_read_b128 v[192:195], v151 offset:3072
	ds_read_b128 v[196:199], v151 offset:4096
	ds_read_b128 v[200:203], v151 offset:5120
	ds_read_b128 v[204:207], v151 offset:6144
	ds_read_b128 v[208:211], v151 offset:7168
	global_load_lds_dwordx4 v[212:213], off
	v_lshl_add_u64 v[212:213], s[26:27], 0, v[138:139]
	s_add_i32 m0, s42, 0xe000
	s_nop 0
	global_load_lds_dwordx4 v[212:213], off
	s_cmp_lg_u32 s61, 2
	s_cbranch_scc1 .Lw8__1179_0
	s_cmp_eq_u32 s46, 1
	s_cbranch_scc1 .Lw8__1179_0
	s_waitcnt vmcnt(24)
	s_branch .Lwj__1179_0

; #define PG8_STAGE(bufoff, gbase, voff) do { _Pragma("unroll") for (int _i = 0; _i < 2; ++_i) \
;         __builtin_amdgcn_global_load_lds((const unsigned*)((const char*)(gbase) + (voff)[_i]), (PG8_LAS unsigned*)(lds + (bufoff) + ldsw + _i * 8192), 16, 0, 0); } while (0)
; #define PG8_LDA(dst, b, h) do { _Pragma("unroll") for (int m = 0; m < 4; ++m) _Pragma("unroll") for (int k = 0; k < 2; ++k) dst[m][k] = *(const PG8_LAS bf16x8*)(lds + PG8_SA(b, h) + aoff + m * 2048 + k * 1024); } while (0)
; #define PG8_MMA(ai, bj, At, Bt) do { __builtin_amdgcn_s_setprio(1); _Pragma("unroll") for (int m = 0; m < 4; ++m) _Pragma("unroll") for (int n = 0; n < 2; ++n) _Pragma("unroll") for (int k = 0; k < 2; ++k) \
;         acc[ai][bj][m][n] = __builtin_amdgcn_mfma_f32_16x16x32_bf16(Bt[n][k], At[m][k], acc[ai][bj][m][n], 0, 0, 0); __builtin_amdgcn_s_setprio(0); } while (0)
; #define PG8_WAIT_V(n) asm volatile("s_waitcnt vmcnt(" #n ")" ::: "memory")
; #define PG8_WAIT_L(n) asm volatile("s_waitcnt lgkmcnt(" #n ")" ::: "memory")
; #define PG8_BAR __builtin_amdgcn_s_barrier()
; #define PG8_SCHED __builtin_amdgcn_sched_barrier(0)
; template <class Epi, class Sched, bool ALIGN_EPI = false, bool SP2 = false>
; __device__ __forceinline__ void gemm_phase(PG8_LAS unsigned char* lds, const Gemm g, const Sched& S, const Epi& E, const int wid) {
;     ...
;             PG8_WAIT_V(8); PG8_WAIT_L(0); PG8_BAR; PG8_MMA(0, 0, At, B0); PG8_MMA(0, 1, At, B1); PG8_BAR; PG8_SCHED;
;             PG8_LDA(At, 0, 1); PG8_STAGE(PG8_SB(0, 0), b2, voffB); PG8_STAGE(PG8_SB(0, 1), b2 + hstep, voffB); PG8_STAGE(PG8_SA(0, 0), a2, voffA);
;             PG8_WAIT_V(8); PG8_WAIT_L(0); PG8_BAR; PG8_MMA(1, 0, At, B0); PG8_MMA(1, 1, At, B1); PG8_BAR; PG8_SCHED;
.Lwj__1179_0:
	s_waitcnt lgkmcnt(0)
	s_barrier
	s_setprio 1
	s_waitcnt lgkmcnt(0)
	v_mfma_f32_16x16x32_bf16 v[124:127], v[142:145], v[180:183], v[124:127]
	v_mfma_f32_16x16x32_bf16 v[120:123], v[156:159], v[180:183], v[120:123]
	v_mfma_f32_16x16x32_bf16 v[108:111], v[142:145], v[188:191], v[108:111]
	v_mfma_f32_16x16x32_bf16 v[104:107], v[156:159], v[188:191], v[104:107]
	v_mfma_f32_16x16x32_bf16 v[92:95], v[142:145], v[196:199], v[92:95]
	v_mfma_f32_16x16x32_bf16 v[88:91], v[156:159], v[196:199], v[88:91]
	v_mfma_f32_16x16x32_bf16 v[76:79], v[142:145], v[204:207], v[76:79]
	v_mfma_f32_16x16x32_bf16 v[72:75], v[156:159], v[204:207], v[72:75]
	v_mfma_f32_16x16x32_bf16 v[124:127], v[152:155], v[184:187], v[124:127]
	v_mfma_f32_16x16x32_bf16 v[120:123], v[160:163], v[184:187], v[120:123]
	v_mfma_f32_16x16x32_bf16 v[108:111], v[152:155], v[192:195], v[108:111]
	v_mfma_f32_16x16x32_bf16 v[104:107], v[160:163], v[192:195], v[104:107]
	v_mfma_f32_16x16x32_bf16 v[92:95], v[152:155], v[200:203], v[92:95]
	v_mfma_f32_16x16x32_bf16 v[88:91], v[160:163], v[200:203], v[88:91]
	v_mfma_f32_16x16x32_bf16 v[76:79], v[152:155], v[208:211], v[76:79]
	v_mfma_f32_16x16x32_bf16 v[72:75], v[160:163], v[208:211], v[72:75]
	s_setprio 0
	s_setprio 1
	v_mfma_f32_16x16x32_bf16 v[116:119], v[164:167], v[180:183], v[116:119]
	v_mfma_f32_16x16x32_bf16 v[112:115], v[172:175], v[180:183], v[112:115]
	v_mfma_f32_16x16x32_bf16 v[100:103], v[164:167], v[188:191], v[100:103]
	v_mfma_f32_16x16x32_bf16 v[96:99], v[172:175], v[188:191], v[96:99]
	v_mfma_f32_16x16x32_bf16 v[84:87], v[164:167], v[196:199], v[84:87]
	v_mfma_f32_16x16x32_bf16 v[80:83], v[172:175], v[196:199], v[80:83]
	v_mfma_f32_16x16x32_bf16 v[68:71], v[164:167], v[204:207], v[68:71]
	v_mfma_f32_16x16x32_bf16 v[64:67], v[172:175], v[204:207], v[64:67]
	v_mfma_f32_16x16x32_bf16 v[116:119], v[168:171], v[184:187], v[116:119]
	v_mfma_f32_16x16x32_bf16 v[112:115], v[176:179], v[184:187], v[112:115]
	v_mfma_f32_16x16x32_bf16 v[100:103], v[168:171], v[192:195], v[100:103]
	v_mfma_f32_16x16x32_bf16 v[96:99], v[176:179], v[192:195], v[96:99]
	v_mfma_f32_16x16x32_bf16 v[84:87], v[168:171], v[200:203], v[84:87]
	v_mfma_f32_16x16x32_bf16 v[80:83], v[176:179], v[200:203], v[80:83]
	v_mfma_f32_16x16x32_bf16 v[68:71], v[168:171], v[208:211], v[68:71]
	v_mfma_f32_16x16x32_bf16 v[64:67], v[176:179], v[208:211], v[64:67]
	s_setprio 0
	s_barrier
	s_add_i32 s33, s55, s34
	v_lshl_add_u64 v[212:213], s[62:63], 0, v[132:133]
	s_mov_b32 m0, s33
	ds_read_b128 v[180:183], v151 offset:16384
	ds_read_b128 v[184:187], v151 offset:17408
	ds_read_b128 v[188:191], v151 offset:18432
	ds_read_b128 v[192:195], v151 offset:19456
	ds_read_b128 v[196:199], v151 offset:20480
	ds_read_b128 v[200:203], v151 offset:21504
	ds_read_b128 v[204:207], v151 offset:22528
	ds_read_b128 v[208:211], v151 offset:23552
	global_load_lds_dwordx4 v[212:213], off
	s_add_i32 m0, s33, 0x2000
	v_lshl_add_u64 v[214:215], s[62:63], 0, v[128:129]
	s_add_u32 s62, s62, s8
	s_addc_u32 s63, s63, s9
	s_add_i32 s33, s56, s34
	global_load_lds_dwordx4 v[214:215], off
	v_lshl_add_u64 v[216:217], s[62:63], 0, v[132:133]
	s_mov_b32 m0, s33
	v_lshl_add_u64 v[218:219], s[62:63], 0, v[128:129]
	global_load_lds_dwordx4 v[216:217], off
	s_add_i32 m0, s33, 0x2000
	v_lshl_add_u64 v[220:221], s[28:29], 0, v[134:135]
	global_load_lds_dwordx4 v[218:219], off
	s_mov_b32 m0, s42
	v_lshl_add_u64 v[222:223], s[28:29], 0, v[130:131]
	global_load_lds_dwordx4 v[220:221], off
	s_mov_b32 m0, s43
	s_nop 0
	global_load_lds_dwordx4 v[222:223], off
	s_cmp_lg_u32 s61, 2
	s_cbranch_scc1 .Lw8__1179_1
	s_cmp_eq_u32 s46, 1
	s_cbranch_scc1 .Lw8__1179_1
	s_waitcnt vmcnt(24)
	s_branch .Lwj__1179_1

; #define PG8_STAGE(bufoff, gbase, voff) do { _Pragma("unroll") for (int _i = 0; _i < 2; ++_i) \
;         __builtin_amdgcn_global_load_lds((const unsigned*)((const char*)(gbase) + (voff)[_i]), (PG8_LAS unsigned*)(lds + (bufoff) + ldsw + _i * 8192), 16, 0, 0); } while (0)
; #define PG8_LDA(dst, b, h) do { _Pragma("unroll") for (int m = 0; m < 4; ++m) _Pragma("unroll") for (int k = 0; k < 2; ++k) dst[m][k] = *(const PG8_LAS bf16x8*)(lds + PG8_SA(b, h) + aoff + m * 2048 + k * 1024); } while (0)
; #define PG8_LDB(dst, b, h) do { _Pragma("unroll") for (int n = 0; n < 2; ++n) _Pragma("unroll") for (int k = 0; k < 2; ++k) dst[n][k] = *(const PG8_LAS bf16x8*)(lds + PG8_SB(b, h) + boff + n * 2048 + k * 1024); } while (0)
; #define PG8_MMA(ai, bj, At, Bt) do { __builtin_amdgcn_s_setprio(1); _Pragma("unroll") for (int m = 0; m < 4; ++m) _Pragma("unroll") for (int n = 0; n < 2; ++n) _Pragma("unroll") for (int k = 0; k < 2; ++k) \
;         acc[ai][bj][m][n] = __builtin_amdgcn_mfma_f32_16x16x32_bf16(Bt[n][k], At[m][k], acc[ai][bj][m][n], 0, 0, 0); __builtin_amdgcn_s_setprio(0); } while (0)
; #define PG8_WAIT_V(n) asm volatile("s_waitcnt vmcnt(" #n ")" ::: "memory")
; #define PG8_WAIT_L(n) asm volatile("s_waitcnt lgkmcnt(" #n ")" ::: "memory")
; #define PG8_BAR __builtin_amdgcn_s_barrier()
; #define PG8_SCHED __builtin_amdgcn_sched_barrier(0)
; template <class Epi, class Sched, bool ALIGN_EPI = false, bool SP2 = false>
; __device__ __forceinline__ void gemm_phase(PG8_LAS unsigned char* lds, const Gemm g, const Sched& S, const Epi& E, const int wid) {
;     ...
;             PG8_WAIT_V(8); PG8_WAIT_L(0); PG8_BAR; PG8_MMA(1, 0, At, B0); PG8_MMA(1, 1, At, B1); PG8_BAR; PG8_SCHED;
;             PG8_LDB(B0, 1, 0); PG8_LDB(B1, 1, 1); PG8_SCHED; PG8_LDA(At, 1, 0); PG8_STAGE(PG8_SA(0, 1), a2 + hstep, voffA);
;             PG8_WAIT_V(8); PG8_WAIT_L(0); PG8_BAR; PG8_MMA(0, 0, At, B0); PG8_MMA(0, 1, At, B1); PG8_BAR; PG8_SCHED;
.Lwj__1179_1:
	s_waitcnt lgkmcnt(0)
	s_barrier
	s_setprio 1
	s_waitcnt lgkmcnt(0)
	v_mfma_f32_16x16x32_bf16 v[60:63], v[142:145], v[180:183], v[60:63]
	v_mfma_f32_16x16x32_bf16 v[56:59], v[156:159], v[180:183], v[56:59]
	v_mfma_f32_16x16x32_bf16 v[44:47], v[142:145], v[188:191], v[44:47]
	v_mfma_f32_16x16x32_bf16 v[40:43], v[156:159], v[188:191], v[40:43]
	v_mfma_f32_16x16x32_bf16 v[28:31], v[142:145], v[196:199], v[28:31]
	v_mfma_f32_16x16x32_bf16 v[24:27], v[156:159], v[196:199], v[24:27]
	v_mfma_f32_16x16x32_bf16 v[12:15], v[142:145], v[204:207], v[12:15]
	v_mfma_f32_16x16x32_bf16 v[8:11], v[156:159], v[204:207], v[8:11]
	v_mfma_f32_16x16x32_bf16 v[60:63], v[152:155], v[184:187], v[60:63]
	v_mfma_f32_16x16x32_bf16 v[56:59], v[160:163], v[184:187], v[56:59]
	v_mfma_f32_16x16x32_bf16 v[44:47], v[152:155], v[192:195], v[44:47]
	v_mfma_f32_16x16x32_bf16 v[40:43], v[160:163], v[192:195], v[40:43]
	v_mfma_f32_16x16x32_bf16 v[28:31], v[152:155], v[200:203], v[28:31]
	v_mfma_f32_16x16x32_bf16 v[24:27], v[160:163], v[200:203], v[24:27]
	v_mfma_f32_16x16x32_bf16 v[12:15], v[152:155], v[208:211], v[12:15]
	v_mfma_f32_16x16x32_bf16 v[8:11], v[160:163], v[208:211], v[8:11]
	s_setprio 0
	s_setprio 1
	v_mfma_f32_16x16x32_bf16 v[52:55], v[164:167], v[180:183], v[52:55]
	v_mfma_f32_16x16x32_bf16 v[48:51], v[172:175], v[180:183], v[48:51]
	v_mfma_f32_16x16x32_bf16 v[36:39], v[164:167], v[188:191], v[36:39]
	v_mfma_f32_16x16x32_bf16 v[32:35], v[172:175], v[188:191], v[32:35]
	v_mfma_f32_16x16x32_bf16 v[20:23], v[164:167], v[196:199], v[20:23]
	v_mfma_f32_16x16x32_bf16 v[16:19], v[172:175], v[196:199], v[16:19]
	v_mfma_f32_16x16x32_bf16 v[4:7], v[164:167], v[204:207], v[4:7]
	v_mfma_f32_16x16x32_bf16 v[0:3], v[172:175], v[204:207], v[0:3]
	v_mfma_f32_16x16x32_bf16 v[52:55], v[168:171], v[184:187], v[52:55]
	v_mfma_f32_16x16x32_bf16 v[48:51], v[176:179], v[184:187], v[48:51]
	v_mfma_f32_16x16x32_bf16 v[36:39], v[168:171], v[192:195], v[36:39]
	v_mfma_f32_16x16x32_bf16 v[32:35], v[176:179], v[192:195], v[32:35]
	v_mfma_f32_16x16x32_bf16 v[20:23], v[168:171], v[200:203], v[20:23]
	v_mfma_f32_16x16x32_bf16 v[16:19], v[176:179], v[200:203], v[16:19]
	v_mfma_f32_16x16x32_bf16 v[4:7], v[168:171], v[208:211], v[4:7]
	v_mfma_f32_16x16x32_bf16 v[0:3], v[176:179], v[208:211], v[0:3]
	s_setprio 0
	s_barrier
	s_add_i32 s33, 0, 0x18000
	s_add_i32 s62, 0, 0x1c000
	v_add_u32_e32 v160, s33, v148
	v_add_u32_e32 v176, s62, v148
	ds_read_b128 v[142:145], v160
	ds_read_b128 v[152:155], v160 offset:1024
	ds_read_b128 v[156:159], v160 offset:2048
	ds_read_b128 v[160:163], v160 offset:3072
	ds_read_b128 v[164:167], v176
	ds_read_b128 v[168:171], v176 offset:1024
	ds_read_b128 v[172:175], v176 offset:2048
	ds_read_b128 v[176:179], v176 offset:3072
	s_add_u32 s28, s28, s8
	s_addc_u32 s29, s29, s9
	s_mov_b32 m0, s44
	v_lshl_add_u64 v[224:225], s[28:29], 0, v[134:135]
	ds_read_b128 v[180:183], v151 offset:32768
	ds_read_b128 v[184:187], v151 offset:33792
	ds_read_b128 v[188:191], v151 offset:34816
	ds_read_b128 v[192:195], v151 offset:35840
	ds_read_b128 v[196:199], v151 offset:36864
	ds_read_b128 v[200:203], v151 offset:37888
	ds_read_b128 v[204:207], v151 offset:38912
	ds_read_b128 v[208:211], v151 offset:39936
	global_load_lds_dwordx4 v[224:225], off
	v_lshl_add_u64 v[224:225], s[28:29], 0, v[130:131]
	s_mov_b32 m0, s45
	s_nop 0
	global_load_lds_dwordx4 v[224:225], off
	s_waitcnt vmcnt(8)
	s_waitcnt lgkmcnt(0)
	s_barrier
	s_setprio 1
	s_waitcnt lgkmcnt(0)
	v_mfma_f32_16x16x32_bf16 v[124:127], v[142:145], v[180:183], v[124:127]
	v_mfma_f32_16x16x32_bf16 v[120:123], v[156:159], v[180:183], v[120:123]
	v_mfma_f32_16x16x32_bf16 v[108:111], v[142:145], v[188:191], v[108:111]
	v_mfma_f32_16x16x32_bf16 v[104:107], v[156:159], v[188:191], v[104:107]
	v_mfma_f32_16x16x32_bf16 v[92:95], v[142:145], v[196:199], v[92:95]
	v_mfma_f32_16x16x32_bf16 v[88:91], v[156:159], v[196:199], v[88:91]
	v_mfma_f32_16x16x32_bf16 v[76:79], v[142:145], v[204:207], v[76:79]
	v_mfma_f32_16x16x32_bf16 v[72:75], v[156:159], v[204:207], v[72:75]
	v_mfma_f32_16x16x32_bf16 v[124:127], v[152:155], v[184:187], v[124:127]
	v_mfma_f32_16x16x32_bf16 v[120:123], v[160:163], v[184:187], v[120:123]
	v_mfma_f32_16x16x32_bf16 v[108:111], v[152:155], v[192:195], v[108:111]
	v_mfma_f32_16x16x32_bf16 v[104:107], v[160:163], v[192:195], v[104:107]
	v_mfma_f32_16x16x32_bf16 v[92:95], v[152:155], v[200:203], v[92:95]
	v_mfma_f32_16x16x32_bf16 v[88:91], v[160:163], v[200:203], v[88:91]
	v_mfma_f32_16x16x32_bf16 v[76:79], v[152:155], v[208:211], v[76:79]
	v_mfma_f32_16x16x32_bf16 v[72:75], v[160:163], v[208:211], v[72:75]
	s_setprio 0
	s_setprio 1
	v_mfma_f32_16x16x32_bf16 v[116:119], v[164:167], v[180:183], v[116:119]
	v_mfma_f32_16x16x32_bf16 v[112:115], v[172:175], v[180:183], v[112:115]
	v_mfma_f32_16x16x32_bf16 v[100:103], v[164:167], v[188:191], v[100:103]
	v_mfma_f32_16x16x32_bf16 v[96:99], v[172:175], v[188:191], v[96:99]
	v_mfma_f32_16x16x32_bf16 v[84:87], v[164:167], v[196:199], v[84:87]
	v_mfma_f32_16x16x32_bf16 v[80:83], v[172:175], v[196:199], v[80:83]
	v_mfma_f32_16x16x32_bf16 v[68:71], v[164:167], v[204:207], v[68:71]
	v_mfma_f32_16x16x32_bf16 v[64:67], v[172:175], v[204:207], v[64:67]
	v_mfma_f32_16x16x32_bf16 v[116:119], v[168:171], v[184:187], v[116:119]
	v_mfma_f32_16x16x32_bf16 v[112:115], v[176:179], v[184:187], v[112:115]
	v_mfma_f32_16x16x32_bf16 v[100:103], v[168:171], v[192:195], v[100:103]
	v_mfma_f32_16x16x32_bf16 v[96:99], v[176:179], v[192:195], v[96:99]
	v_mfma_f32_16x16x32_bf16 v[84:87], v[168:171], v[200:203], v[84:87]
	v_mfma_f32_16x16x32_bf16 v[80:83], v[176:179], v[200:203], v[80:83]
	v_mfma_f32_16x16x32_bf16 v[68:71], v[168:171], v[208:211], v[68:71]
	v_mfma_f32_16x16x32_bf16 v[64:67], v[176:179], v[208:211], v[64:67]
	s_setprio 0
	s_barrier
; #define PG8_STAGE(bufoff, gbase, voff) do { _Pragma("unroll") for (int _i = 0; _i < 2; ++_i) \
;         __builtin_amdgcn_global_load_lds((const unsigned*)((const char*)(gbase) + (voff)[_i]), (PG8_LAS unsigned*)(lds + (bufoff) + ldsw + _i * 8192), 16, 0, 0); } while (0)
; #define PG8_LDA(dst, b, h) do { _Pragma("unroll") for (int m = 0; m < 4; ++m) _Pragma("unroll") for (int k = 0; k < 2; ++k) dst[m][k] = *(const PG8_LAS bf16x8*)(lds + PG8_SA(b, h) + aoff + m * 2048 + k * 1024); } while (0)
; #define PG8_MMA(ai, bj, At, Bt) do { __builtin_amdgcn_s_setprio(1); _Pragma("unroll") for (int m = 0; m < 4; ++m) _Pragma("unroll") for (int n = 0; n < 2; ++n) _Pragma("unroll") for (int k = 0; k < 2; ++k) \
;         acc[ai][bj][m][n] = __builtin_amdgcn_mfma_f32_16x16x32_bf16(Bt[n][k], At[m][k], acc[ai][bj][m][n], 0, 0, 0); __builtin_amdgcn_s_setprio(0); } while (0)
; #define PG8_WAIT_V(n) asm volatile("s_waitcnt vmcnt(" #n ")" ::: "memory")
; #define PG8_WAIT_L(n) asm volatile("s_waitcnt lgkmcnt(" #n ")" ::: "memory")
; #define PG8_BAR __builtin_amdgcn_s_barrier()
; #define PG8_SCHED __builtin_amdgcn_sched_barrier(0)
; template <class Epi, class Sched, bool ALIGN_EPI = false, bool SP2 = false>
; __device__ __forceinline__ void gemm_phase(PG8_LAS unsigned char* lds, const Gemm g, const Sched& S, const Epi& E, const int wid) {
;     ...
;         for (int t = 0; t < nt; t += 2) {
;             const bool last = (t == nt - 2);
;             const char* a1 = cA + (size_t)(t + 1) * kstep;
;             const char* a2 = last ? nA : cA + (size_t)(t + 2) * kstep; const char* b2 = last ? nB : cB + (size_t)(t + 2) * kstep;
;     ...
;             PG8_LDA(At, 1, 1); PG8_STAGE(PG8_SB(1, 0), b3, voffB); PG8_STAGE(PG8_SB(1, 1), b3 + hstep, voffB); PG8_STAGE(PG8_SA(1, 0), a3, voffA);
;             PG8_WAIT_V(8); PG8_WAIT_L(0); PG8_BAR; PG8_MMA(1, 0, At, B0); PG8_MMA(1, 1, At, B1); PG8_BAR; PG8_SCHED;
	s_add_i32 s28, s33, s34
	v_lshl_add_u64 v[212:213], v[212:213], 0, s[18:19]
	s_mov_b32 m0, s28
	ds_read_b128 v[180:183], v151 offset:49152
	ds_read_b128 v[184:187], v151 offset:50176
	ds_read_b128 v[188:191], v151 offset:51200
	ds_read_b128 v[192:195], v151 offset:52224
	ds_read_b128 v[196:199], v151 offset:53248
	ds_read_b128 v[200:203], v151 offset:54272
	ds_read_b128 v[204:207], v151 offset:55296
	ds_read_b128 v[208:211], v151 offset:56320
	global_load_lds_dwordx4 v[212:213], off
	v_lshl_add_u64 v[212:213], v[214:215], 0, s[18:19]
	s_add_i32 m0, s28, 0x2000
	s_add_i32 s28, s62, s34
	global_load_lds_dwordx4 v[212:213], off
	v_lshl_add_u64 v[212:213], v[216:217], 0, s[18:19]
	s_mov_b32 m0, s28
	s_nop 0
	global_load_lds_dwordx4 v[212:213], off
	v_lshl_add_u64 v[212:213], v[218:219], 0, s[18:19]
	s_add_i32 m0, s28, 0x2000
	s_nop 0
	global_load_lds_dwordx4 v[212:213], off
	v_lshl_add_u64 v[212:213], v[220:221], 0, s[18:19]
	s_mov_b32 m0, s47
	s_nop 0
	global_load_lds_dwordx4 v[212:213], off
	v_lshl_add_u64 v[212:213], v[222:223], 0, s[18:19]
	s_mov_b32 m0, s49
	s_nop 0
	global_load_lds_dwordx4 v[212:213], off
	s_waitcnt vmcnt(8)
	s_waitcnt lgkmcnt(0)
	s_barrier
	s_setprio 1
	s_waitcnt lgkmcnt(0)
	v_mfma_f32_16x16x32_bf16 v[60:63], v[142:145], v[180:183], v[60:63]
	v_mfma_f32_16x16x32_bf16 v[56:59], v[156:159], v[180:183], v[56:59]
	v_mfma_f32_16x16x32_bf16 v[44:47], v[142:145], v[188:191], v[44:47]
	v_mfma_f32_16x16x32_bf16 v[40:43], v[156:159], v[188:191], v[40:43]
	v_mfma_f32_16x16x32_bf16 v[28:31], v[142:145], v[196:199], v[28:31]
	v_mfma_f32_16x16x32_bf16 v[24:27], v[156:159], v[196:199], v[24:27]
	v_mfma_f32_16x16x32_bf16 v[12:15], v[142:145], v[204:207], v[12:15]
	v_mfma_f32_16x16x32_bf16 v[8:11], v[156:159], v[204:207], v[8:11]
	v_mfma_f32_16x16x32_bf16 v[60:63], v[152:155], v[184:187], v[60:63]
	v_mfma_f32_16x16x32_bf16 v[56:59], v[160:163], v[184:187], v[56:59]
	v_mfma_f32_16x16x32_bf16 v[44:47], v[152:155], v[192:195], v[44:47]
	v_mfma_f32_16x16x32_bf16 v[40:43], v[160:163], v[192:195], v[40:43]
	v_mfma_f32_16x16x32_bf16 v[28:31], v[152:155], v[200:203], v[28:31]
	v_mfma_f32_16x16x32_bf16 v[24:27], v[160:163], v[200:203], v[24:27]
	v_mfma_f32_16x16x32_bf16 v[12:15], v[152:155], v[208:211], v[12:15]
	v_mfma_f32_16x16x32_bf16 v[8:11], v[160:163], v[208:211], v[8:11]
	s_setprio 0
	s_setprio 1
	v_mfma_f32_16x16x32_bf16 v[52:55], v[164:167], v[180:183], v[52:55]
	v_mfma_f32_16x16x32_bf16 v[48:51], v[172:175], v[180:183], v[48:51]
	v_mfma_f32_16x16x32_bf16 v[36:39], v[164:167], v[188:191], v[36:39]
	v_mfma_f32_16x16x32_bf16 v[32:35], v[172:175], v[188:191], v[32:35]
	v_mfma_f32_16x16x32_bf16 v[20:23], v[164:167], v[196:199], v[20:23]
	v_mfma_f32_16x16x32_bf16 v[16:19], v[172:175], v[196:199], v[16:19]
	v_mfma_f32_16x16x32_bf16 v[4:7], v[164:167], v[204:207], v[4:7]
	v_mfma_f32_16x16x32_bf16 v[0:3], v[172:175], v[204:207], v[0:3]
	v_mfma_f32_16x16x32_bf16 v[52:55], v[168:171], v[184:187], v[52:55]
	v_mfma_f32_16x16x32_bf16 v[48:51], v[176:179], v[184:187], v[48:51]
	v_mfma_f32_16x16x32_bf16 v[36:39], v[168:171], v[192:195], v[36:39]
	v_mfma_f32_16x16x32_bf16 v[32:35], v[176:179], v[192:195], v[32:35]
	v_mfma_f32_16x16x32_bf16 v[20:23], v[168:171], v[200:203], v[20:23]
	v_mfma_f32_16x16x32_bf16 v[16:19], v[176:179], v[200:203], v[16:19]
	v_mfma_f32_16x16x32_bf16 v[4:7], v[168:171], v[208:211], v[4:7]
	v_mfma_f32_16x16x32_bf16 v[0:3], v[176:179], v[208:211], v[0:3]
	s_setprio 0
	s_barrier
	s_add_u32 s26, s26, 0x100
	s_addc_u32 s27, s27, 0
	s_add_u32 s0, s0, 0x100
	s_addc_u32 s1, s1, 0
	s_cmp_ge_i32 s61, s50
	s_mov_b32 s28, s61
	s_cbranch_scc0 .LBB0_1179

; #define PG8_STAGE(bufoff, gbase, voff) do { _Pragma("unroll") for (int _i = 0; _i < 2; ++_i) \
;         __builtin_amdgcn_global_load_lds((const unsigned*)((const char*)(gbase) + (voff)[_i]), (PG8_LAS unsigned*)(lds + (bufoff) + ldsw + _i * 8192), 16, 0, 0); } while (0)
; #define PG8_LDA(dst, b, h) do { _Pragma("unroll") for (int m = 0; m < 4; ++m) _Pragma("unroll") for (int k = 0; k < 2; ++k) dst[m][k] = *(const PG8_LAS bf16x8*)(lds + PG8_SA(b, h) + aoff + m * 2048 + k * 1024); } while (0)
; #define PG8_LDB(dst, b, h) do { _Pragma("unroll") for (int n = 0; n < 2; ++n) _Pragma("unroll") for (int k = 0; k < 2; ++k) dst[n][k] = *(const PG8_LAS bf16x8*)(lds + PG8_SB(b, h) + boff + n * 2048 + k * 1024); } while (0)
; #define PG8_MMA(ai, bj, At, Bt) do { __builtin_amdgcn_s_setprio(1); _Pragma("unroll") for (int m = 0; m < 4; ++m) _Pragma("unroll") for (int n = 0; n < 2; ++n) _Pragma("unroll") for (int k = 0; k < 2; ++k) \
;         acc[ai][bj][m][n] = __builtin_amdgcn_mfma_f32_16x16x32_bf16(Bt[n][k], At[m][k], acc[ai][bj][m][n], 0, 0, 0); __builtin_amdgcn_s_setprio(0); } while (0)
; #define PG8_WAIT_V(n) asm volatile("s_waitcnt vmcnt(" #n ")" ::: "memory")
; #define PG8_WAIT_L(n) asm volatile("s_waitcnt lgkmcnt(" #n ")" ::: "memory")
; #define PG8_BAR __builtin_amdgcn_s_barrier()
; #define PG8_SCHED __builtin_amdgcn_sched_barrier(0)
; template <class Epi, class Sched, bool ALIGN_EPI = false, bool SP2 = false>
; __device__ __forceinline__ void gemm_phase(PG8_LAS unsigned char* lds, const Gemm g, const Sched& S, const Epi& E, const int wid) {
;     ...
;         for (int t = 0; t < nt; t += 2) {
;             const bool last = (t == nt - 2);
;             const char* a1 = cA + (size_t)(t + 1) * kstep;
;             const char* a2 = last ? nA : cA + (size_t)(t + 2) * kstep; const char* b2 = last ? nB : cB + (size_t)(t + 2) * kstep;
;             const char* a3 = a2 + kstep; const char* b3 = b2 + kstep;
;             if (last && has_next) S.a_ready(nxt);
;             if constexpr (SP2) {
;             PG8_LDB(B0, 0, 0); PG8_LDB(B1, 0, 1); PG8_SCHED; PG8_LDA(At, 0, 0); PG8_STAGE(PG8_SA(1, 1), a1 + hstep, voffA);
;             PG8_WAIT_V(8); PG8_WAIT_L(0); PG8_BAR; PG8_MMA(0, 0, At, B0); PG8_MMA(0, 1, At, B1); PG8_BAR; PG8_SCHED;
.LBB0_1258:
	ds_read_b128 v[142:145], v149
	ds_read_b128 v[152:155], v149 offset:1024
	ds_read_b128 v[156:159], v149 offset:2048
	ds_read_b128 v[160:163], v149 offset:3072
	ds_read_b128 v[164:167], v150
	ds_read_b128 v[168:171], v150 offset:1024
	ds_read_b128 v[172:175], v150 offset:2048
	ds_read_b128 v[176:179], v150 offset:3072
	s_add_i32 s66, s30, 2
	s_add_u32 s33, s28, 0x80
	s_addc_u32 s31, s29, 0
	s_cmp_eq_u32 s57, s30
	s_cselect_b32 s30, s4, s33
	s_cselect_b32 s31, s5, s31
	s_cselect_b32 s69, s27, s1
	s_cselect_b32 s68, s26, s0
	v_lshl_add_u64 v[212:213], s[28:29], 0, v[136:137]
	s_add_i32 m0, s46, 0xc000
	ds_read_b128 v[180:183], v151
	ds_read_b128 v[184:187], v151 offset:1024
	ds_read_b128 v[188:191], v151 offset:2048
	ds_read_b128 v[192:195], v151 offset:3072
	ds_read_b128 v[196:199], v151 offset:4096
	ds_read_b128 v[200:203], v151 offset:5120
	ds_read_b128 v[204:207], v151 offset:6144
	ds_read_b128 v[208:211], v151 offset:7168
	global_load_lds_dwordx4 v[212:213], off
	v_lshl_add_u64 v[212:213], s[28:29], 0, v[138:139]
	s_add_i32 m0, s46, 0xe000
	s_nop 0
	global_load_lds_dwordx4 v[212:213], off
	s_cmp_lg_u32 s66, 2
	s_cbranch_scc1 .Lw8__1258_0
	s_cmp_eq_u32 s51, 1
	s_cbranch_scc1 .Lw8__1258_0
	s_waitcnt vmcnt(24)
	s_branch .Lwj__1258_0

; #define PG8_STAGE(bufoff, gbase, voff) do { _Pragma("unroll") for (int _i = 0; _i < 2; ++_i) \
;         __builtin_amdgcn_global_load_lds((const unsigned*)((const char*)(gbase) + (voff)[_i]), (PG8_LAS unsigned*)(lds + (bufoff) + ldsw + _i * 8192), 16, 0, 0); } while (0)
; #define PG8_LDA(dst, b, h) do { _Pragma("unroll") for (int m = 0; m < 4; ++m) _Pragma("unroll") for (int k = 0; k < 2; ++k) dst[m][k] = *(const PG8_LAS bf16x8*)(lds + PG8_SA(b, h) + aoff + m * 2048 + k * 1024); } while (0)
; #define PG8_MMA(ai, bj, At, Bt) do { __builtin_amdgcn_s_setprio(1); _Pragma("unroll") for (int m = 0; m < 4; ++m) _Pragma("unroll") for (int n = 0; n < 2; ++n) _Pragma("unroll") for (int k = 0; k < 2; ++k) \
;         acc[ai][bj][m][n] = __builtin_amdgcn_mfma_f32_16x16x32_bf16(Bt[n][k], At[m][k], acc[ai][bj][m][n], 0, 0, 0); __builtin_amdgcn_s_setprio(0); } while (0)
; #define PG8_WAIT_V(n) asm volatile("s_waitcnt vmcnt(" #n ")" ::: "memory")
; #define PG8_WAIT_L(n) asm volatile("s_waitcnt lgkmcnt(" #n ")" ::: "memory")
; #define PG8_BAR __builtin_amdgcn_s_barrier()
; #define PG8_SCHED __builtin_amdgcn_sched_barrier(0)
; template <class Epi, class Sched, bool ALIGN_EPI = false, bool SP2 = false>
; __device__ __forceinline__ void gemm_phase(PG8_LAS unsigned char* lds, const Gemm g, const Sched& S, const Epi& E, const int wid) {
;     ...
;             PG8_WAIT_V(8); PG8_WAIT_L(0); PG8_BAR; PG8_MMA(0, 0, At, B0); PG8_MMA(0, 1, At, B1); PG8_BAR; PG8_SCHED;
;             PG8_LDA(At, 0, 1); PG8_STAGE(PG8_SB(0, 0), b2, voffB); PG8_STAGE(PG8_SB(0, 1), b2 + hstep, voffB); PG8_STAGE(PG8_SA(0, 0), a2, voffA);
;             PG8_WAIT_V(8); PG8_WAIT_L(0); PG8_BAR; PG8_MMA(1, 0, At, B0); PG8_MMA(1, 1, At, B1); PG8_BAR; PG8_SCHED;
.Lwj__1258_0:
	s_waitcnt lgkmcnt(0)
	s_barrier
	s_setprio 1
	s_waitcnt lgkmcnt(0)
	v_mfma_f32_16x16x32_bf16 v[124:127], v[142:145], v[180:183], v[124:127]
	v_mfma_f32_16x16x32_bf16 v[120:123], v[156:159], v[180:183], v[120:123]
	v_mfma_f32_16x16x32_bf16 v[108:111], v[142:145], v[188:191], v[108:111]
	v_mfma_f32_16x16x32_bf16 v[104:107], v[156:159], v[188:191], v[104:107]
	v_mfma_f32_16x16x32_bf16 v[92:95], v[142:145], v[196:199], v[92:95]
	v_mfma_f32_16x16x32_bf16 v[88:91], v[156:159], v[196:199], v[88:91]
	v_mfma_f32_16x16x32_bf16 v[76:79], v[142:145], v[204:207], v[76:79]
	v_mfma_f32_16x16x32_bf16 v[72:75], v[156:159], v[204:207], v[72:75]
	v_mfma_f32_16x16x32_bf16 v[124:127], v[152:155], v[184:187], v[124:127]
	v_mfma_f32_16x16x32_bf16 v[120:123], v[160:163], v[184:187], v[120:123]
	v_mfma_f32_16x16x32_bf16 v[108:111], v[152:155], v[192:195], v[108:111]
	v_mfma_f32_16x16x32_bf16 v[104:107], v[160:163], v[192:195], v[104:107]
	v_mfma_f32_16x16x32_bf16 v[92:95], v[152:155], v[200:203], v[92:95]
	v_mfma_f32_16x16x32_bf16 v[88:91], v[160:163], v[200:203], v[88:91]
	v_mfma_f32_16x16x32_bf16 v[76:79], v[152:155], v[208:211], v[76:79]
	v_mfma_f32_16x16x32_bf16 v[72:75], v[160:163], v[208:211], v[72:75]
	s_setprio 0
	s_setprio 1
	v_mfma_f32_16x16x32_bf16 v[116:119], v[164:167], v[180:183], v[116:119]
	v_mfma_f32_16x16x32_bf16 v[112:115], v[172:175], v[180:183], v[112:115]
	v_mfma_f32_16x16x32_bf16 v[100:103], v[164:167], v[188:191], v[100:103]
	v_mfma_f32_16x16x32_bf16 v[96:99], v[172:175], v[188:191], v[96:99]
	v_mfma_f32_16x16x32_bf16 v[84:87], v[164:167], v[196:199], v[84:87]
	v_mfma_f32_16x16x32_bf16 v[80:83], v[172:175], v[196:199], v[80:83]
	v_mfma_f32_16x16x32_bf16 v[68:71], v[164:167], v[204:207], v[68:71]
	v_mfma_f32_16x16x32_bf16 v[64:67], v[172:175], v[204:207], v[64:67]
	v_mfma_f32_16x16x32_bf16 v[116:119], v[168:171], v[184:187], v[116:119]
	v_mfma_f32_16x16x32_bf16 v[112:115], v[176:179], v[184:187], v[112:115]
	v_mfma_f32_16x16x32_bf16 v[100:103], v[168:171], v[192:195], v[100:103]
	v_mfma_f32_16x16x32_bf16 v[96:99], v[176:179], v[192:195], v[96:99]
	v_mfma_f32_16x16x32_bf16 v[84:87], v[168:171], v[200:203], v[84:87]
	v_mfma_f32_16x16x32_bf16 v[80:83], v[176:179], v[200:203], v[80:83]
	v_mfma_f32_16x16x32_bf16 v[68:71], v[168:171], v[208:211], v[68:71]
	v_mfma_f32_16x16x32_bf16 v[64:67], v[176:179], v[208:211], v[64:67]
	s_setprio 0
	s_barrier
	s_add_i32 s33, s59, s38
	v_lshl_add_u64 v[212:213], s[68:69], 0, v[132:133]
	s_mov_b32 m0, s33
	ds_read_b128 v[180:183], v151 offset:16384
	ds_read_b128 v[184:187], v151 offset:17408
	ds_read_b128 v[188:191], v151 offset:18432
	ds_read_b128 v[192:195], v151 offset:19456
	ds_read_b128 v[196:199], v151 offset:20480
	ds_read_b128 v[200:203], v151 offset:21504
	ds_read_b128 v[204:207], v151 offset:22528
	ds_read_b128 v[208:211], v151 offset:23552
	global_load_lds_dwordx4 v[212:213], off
	s_add_i32 m0, s33, 0x2000
	v_lshl_add_u64 v[214:215], s[68:69], 0, v[128:129]
	s_add_u32 s68, s68, s8
	s_addc_u32 s69, s69, s9
	s_add_i32 s33, s60, s38
	global_load_lds_dwordx4 v[214:215], off
	v_lshl_add_u64 v[216:217], s[68:69], 0, v[132:133]
	s_mov_b32 m0, s33
	v_lshl_add_u64 v[218:219], s[68:69], 0, v[128:129]
	global_load_lds_dwordx4 v[216:217], off
	s_add_i32 m0, s33, 0x2000
	v_lshl_add_u64 v[220:221], s[30:31], 0, v[134:135]
	global_load_lds_dwordx4 v[218:219], off
	s_mov_b32 m0, s46
	v_lshl_add_u64 v[222:223], s[30:31], 0, v[130:131]
	global_load_lds_dwordx4 v[220:221], off
	s_mov_b32 m0, s47
	s_nop 0
	global_load_lds_dwordx4 v[222:223], off
	s_cmp_lg_u32 s66, 2
	s_cbranch_scc1 .Lw8__1258_1
	s_cmp_eq_u32 s51, 1
	s_cbranch_scc1 .Lw8__1258_1
	s_waitcnt vmcnt(24)
	s_branch .Lwj__1258_1

; #define PG8_STAGE(bufoff, gbase, voff) do { _Pragma("unroll") for (int _i = 0; _i < 2; ++_i) \
;         __builtin_amdgcn_global_load_lds((const unsigned*)((const char*)(gbase) + (voff)[_i]), (PG8_LAS unsigned*)(lds + (bufoff) + ldsw + _i * 8192), 16, 0, 0); } while (0)
; #define PG8_LDA(dst, b, h) do { _Pragma("unroll") for (int m = 0; m < 4; ++m) _Pragma("unroll") for (int k = 0; k < 2; ++k) dst[m][k] = *(const PG8_LAS bf16x8*)(lds + PG8_SA(b, h) + aoff + m * 2048 + k * 1024); } while (0)
; #define PG8_LDB(dst, b, h) do { _Pragma("unroll") for (int n = 0; n < 2; ++n) _Pragma("unroll") for (int k = 0; k < 2; ++k) dst[n][k] = *(const PG8_LAS bf16x8*)(lds + PG8_SB(b, h) + boff + n * 2048 + k * 1024); } while (0)
; #define PG8_MMA(ai, bj, At, Bt) do { __builtin_amdgcn_s_setprio(1); _Pragma("unroll") for (int m = 0; m < 4; ++m) _Pragma("unroll") for (int n = 0; n < 2; ++n) _Pragma("unroll") for (int k = 0; k < 2; ++k) \
;         acc[ai][bj][m][n] = __builtin_amdgcn_mfma_f32_16x16x32_bf16(Bt[n][k], At[m][k], acc[ai][bj][m][n], 0, 0, 0); __builtin_amdgcn_s_setprio(0); } while (0)
; #define PG8_WAIT_V(n) asm volatile("s_waitcnt vmcnt(" #n ")" ::: "memory")
; #define PG8_WAIT_L(n) asm volatile("s_waitcnt lgkmcnt(" #n ")" ::: "memory")
; #define PG8_BAR __builtin_amdgcn_s_barrier()
; #define PG8_SCHED __builtin_amdgcn_sched_barrier(0)
; template <class Epi, class Sched, bool ALIGN_EPI = false, bool SP2 = false>
; __device__ __forceinline__ void gemm_phase(PG8_LAS unsigned char* lds, const Gemm g, const Sched& S, const Epi& E, const int wid) {
;     ...
;             PG8_WAIT_V(8); PG8_WAIT_L(0); PG8_BAR; PG8_MMA(1, 0, At, B0); PG8_MMA(1, 1, At, B1); PG8_BAR; PG8_SCHED;
;             PG8_LDB(B0, 1, 0); PG8_LDB(B1, 1, 1); PG8_SCHED; PG8_LDA(At, 1, 0); PG8_STAGE(PG8_SA(0, 1), a2 + hstep, voffA);
;             PG8_WAIT_V(8); PG8_WAIT_L(0); PG8_BAR; PG8_MMA(0, 0, At, B0); PG8_MMA(0, 1, At, B1); PG8_BAR; PG8_SCHED;
.Lwj__1258_1:
	s_waitcnt lgkmcnt(0)
	s_barrier
	s_setprio 1
	s_waitcnt lgkmcnt(0)
	v_mfma_f32_16x16x32_bf16 v[60:63], v[142:145], v[180:183], v[60:63]
	v_mfma_f32_16x16x32_bf16 v[56:59], v[156:159], v[180:183], v[56:59]
	v_mfma_f32_16x16x32_bf16 v[44:47], v[142:145], v[188:191], v[44:47]
	v_mfma_f32_16x16x32_bf16 v[40:43], v[156:159], v[188:191], v[40:43]
	v_mfma_f32_16x16x32_bf16 v[28:31], v[142:145], v[196:199], v[28:31]
	v_mfma_f32_16x16x32_bf16 v[24:27], v[156:159], v[196:199], v[24:27]
	v_mfma_f32_16x16x32_bf16 v[12:15], v[142:145], v[204:207], v[12:15]
	v_mfma_f32_16x16x32_bf16 v[8:11], v[156:159], v[204:207], v[8:11]
	v_mfma_f32_16x16x32_bf16 v[60:63], v[152:155], v[184:187], v[60:63]
	v_mfma_f32_16x16x32_bf16 v[56:59], v[160:163], v[184:187], v[56:59]
	v_mfma_f32_16x16x32_bf16 v[44:47], v[152:155], v[192:195], v[44:47]
	v_mfma_f32_16x16x32_bf16 v[40:43], v[160:163], v[192:195], v[40:43]
	v_mfma_f32_16x16x32_bf16 v[28:31], v[152:155], v[200:203], v[28:31]
	v_mfma_f32_16x16x32_bf16 v[24:27], v[160:163], v[200:203], v[24:27]
	v_mfma_f32_16x16x32_bf16 v[12:15], v[152:155], v[208:211], v[12:15]
	v_mfma_f32_16x16x32_bf16 v[8:11], v[160:163], v[208:211], v[8:11]
	s_setprio 0
	s_setprio 1
	v_mfma_f32_16x16x32_bf16 v[52:55], v[164:167], v[180:183], v[52:55]
	v_mfma_f32_16x16x32_bf16 v[48:51], v[172:175], v[180:183], v[48:51]
	v_mfma_f32_16x16x32_bf16 v[36:39], v[164:167], v[188:191], v[36:39]
	v_mfma_f32_16x16x32_bf16 v[32:35], v[172:175], v[188:191], v[32:35]
	v_mfma_f32_16x16x32_bf16 v[20:23], v[164:167], v[196:199], v[20:23]
	v_mfma_f32_16x16x32_bf16 v[16:19], v[172:175], v[196:199], v[16:19]
	v_mfma_f32_16x16x32_bf16 v[4:7], v[164:167], v[204:207], v[4:7]
	v_mfma_f32_16x16x32_bf16 v[0:3], v[172:175], v[204:207], v[0:3]
	v_mfma_f32_16x16x32_bf16 v[52:55], v[168:171], v[184:187], v[52:55]
	v_mfma_f32_16x16x32_bf16 v[48:51], v[176:179], v[184:187], v[48:51]
	v_mfma_f32_16x16x32_bf16 v[36:39], v[168:171], v[192:195], v[36:39]
	v_mfma_f32_16x16x32_bf16 v[32:35], v[176:179], v[192:195], v[32:35]
	v_mfma_f32_16x16x32_bf16 v[20:23], v[168:171], v[200:203], v[20:23]
	v_mfma_f32_16x16x32_bf16 v[16:19], v[176:179], v[200:203], v[16:19]
	v_mfma_f32_16x16x32_bf16 v[4:7], v[168:171], v[208:211], v[4:7]
	v_mfma_f32_16x16x32_bf16 v[0:3], v[176:179], v[208:211], v[0:3]
	s_setprio 0
	s_barrier
	s_add_i32 s33, 0, 0x18000
	s_add_i32 s67, 0, 0x1c000
	v_add_u32_e32 v160, s33, v148
	v_add_u32_e32 v176, s67, v148
	ds_read_b128 v[142:145], v160
	ds_read_b128 v[152:155], v160 offset:1024
	ds_read_b128 v[156:159], v160 offset:2048
	ds_read_b128 v[160:163], v160 offset:3072
	ds_read_b128 v[164:167], v176
	ds_read_b128 v[168:171], v176 offset:1024
	ds_read_b128 v[172:175], v176 offset:2048
	ds_read_b128 v[176:179], v176 offset:3072
	s_add_u32 s30, s30, s8
	s_addc_u32 s31, s31, s9
	s_mov_b32 m0, s49
	v_lshl_add_u64 v[224:225], s[30:31], 0, v[134:135]
	ds_read_b128 v[180:183], v151 offset:32768
	ds_read_b128 v[184:187], v151 offset:33792
	ds_read_b128 v[188:191], v151 offset:34816
	ds_read_b128 v[192:195], v151 offset:35840
	ds_read_b128 v[196:199], v151 offset:36864
	ds_read_b128 v[200:203], v151 offset:37888
	ds_read_b128 v[204:207], v151 offset:38912
	ds_read_b128 v[208:211], v151 offset:39936
	global_load_lds_dwordx4 v[224:225], off
	v_lshl_add_u64 v[224:225], s[30:31], 0, v[130:131]
	s_mov_b32 m0, s50
	s_nop 0
	global_load_lds_dwordx4 v[224:225], off
	s_waitcnt vmcnt(8)
	s_waitcnt lgkmcnt(0)
	s_barrier
	s_setprio 1
	s_waitcnt lgkmcnt(0)
	v_mfma_f32_16x16x32_bf16 v[124:127], v[142:145], v[180:183], v[124:127]
	v_mfma_f32_16x16x32_bf16 v[120:123], v[156:159], v[180:183], v[120:123]
	v_mfma_f32_16x16x32_bf16 v[108:111], v[142:145], v[188:191], v[108:111]
	v_mfma_f32_16x16x32_bf16 v[104:107], v[156:159], v[188:191], v[104:107]
	v_mfma_f32_16x16x32_bf16 v[92:95], v[142:145], v[196:199], v[92:95]
	v_mfma_f32_16x16x32_bf16 v[88:91], v[156:159], v[196:199], v[88:91]
	v_mfma_f32_16x16x32_bf16 v[76:79], v[142:145], v[204:207], v[76:79]
	v_mfma_f32_16x16x32_bf16 v[72:75], v[156:159], v[204:207], v[72:75]
	v_mfma_f32_16x16x32_bf16 v[124:127], v[152:155], v[184:187], v[124:127]
	v_mfma_f32_16x16x32_bf16 v[120:123], v[160:163], v[184:187], v[120:123]
	v_mfma_f32_16x16x32_bf16 v[108:111], v[152:155], v[192:195], v[108:111]
	v_mfma_f32_16x16x32_bf16 v[104:107], v[160:163], v[192:195], v[104:107]
	v_mfma_f32_16x16x32_bf16 v[92:95], v[152:155], v[200:203], v[92:95]
	v_mfma_f32_16x16x32_bf16 v[88:91], v[160:163], v[200:203], v[88:91]
	v_mfma_f32_16x16x32_bf16 v[76:79], v[152:155], v[208:211], v[76:79]
	v_mfma_f32_16x16x32_bf16 v[72:75], v[160:163], v[208:211], v[72:75]
	s_setprio 0
	s_setprio 1
	v_mfma_f32_16x16x32_bf16 v[116:119], v[164:167], v[180:183], v[116:119]
	v_mfma_f32_16x16x32_bf16 v[112:115], v[172:175], v[180:183], v[112:115]
	v_mfma_f32_16x16x32_bf16 v[100:103], v[164:167], v[188:191], v[100:103]
	v_mfma_f32_16x16x32_bf16 v[96:99], v[172:175], v[188:191], v[96:99]
	v_mfma_f32_16x16x32_bf16 v[84:87], v[164:167], v[196:199], v[84:87]
	v_mfma_f32_16x16x32_bf16 v[80:83], v[172:175], v[196:199], v[80:83]
	v_mfma_f32_16x16x32_bf16 v[68:71], v[164:167], v[204:207], v[68:71]
	v_mfma_f32_16x16x32_bf16 v[64:67], v[172:175], v[204:207], v[64:67]
	v_mfma_f32_16x16x32_bf16 v[116:119], v[168:171], v[184:187], v[116:119]
	v_mfma_f32_16x16x32_bf16 v[112:115], v[176:179], v[184:187], v[112:115]
	v_mfma_f32_16x16x32_bf16 v[100:103], v[168:171], v[192:195], v[100:103]
	v_mfma_f32_16x16x32_bf16 v[96:99], v[176:179], v[192:195], v[96:99]
	v_mfma_f32_16x16x32_bf16 v[84:87], v[168:171], v[200:203], v[84:87]
	v_mfma_f32_16x16x32_bf16 v[80:83], v[176:179], v[200:203], v[80:83]
	v_mfma_f32_16x16x32_bf16 v[68:71], v[168:171], v[208:211], v[68:71]
	v_mfma_f32_16x16x32_bf16 v[64:67], v[176:179], v[208:211], v[64:67]
	s_setprio 0
	s_barrier
; #define PG8_STAGE(bufoff, gbase, voff) do { _Pragma("unroll") for (int _i = 0; _i < 2; ++_i) \
;         __builtin_amdgcn_global_load_lds((const unsigned*)((const char*)(gbase) + (voff)[_i]), (PG8_LAS unsigned*)(lds + (bufoff) + ldsw + _i * 8192), 16, 0, 0); } while (0)
; #define PG8_LDA(dst, b, h) do { _Pragma("unroll") for (int m = 0; m < 4; ++m) _Pragma("unroll") for (int k = 0; k < 2; ++k) dst[m][k] = *(const PG8_LAS bf16x8*)(lds + PG8_SA(b, h) + aoff + m * 2048 + k * 1024); } while (0)
; #define PG8_MMA(ai, bj, At, Bt) do { __builtin_amdgcn_s_setprio(1); _Pragma("unroll") for (int m = 0; m < 4; ++m) _Pragma("unroll") for (int n = 0; n < 2; ++n) _Pragma("unroll") for (int k = 0; k < 2; ++k) \
;         acc[ai][bj][m][n] = __builtin_amdgcn_mfma_f32_16x16x32_bf16(Bt[n][k], At[m][k], acc[ai][bj][m][n], 0, 0, 0); __builtin_amdgcn_s_setprio(0); } while (0)
; #define PG8_WAIT_V(n) asm volatile("s_waitcnt vmcnt(" #n ")" ::: "memory")
; #define PG8_WAIT_L(n) asm volatile("s_waitcnt lgkmcnt(" #n ")" ::: "memory")
; #define PG8_BAR __builtin_amdgcn_s_barrier()
; #define PG8_SCHED __builtin_amdgcn_sched_barrier(0)
; template <class Epi, class Sched, bool ALIGN_EPI = false, bool SP2 = false>
; __device__ __forceinline__ void gemm_phase(PG8_LAS unsigned char* lds, const Gemm g, const Sched& S, const Epi& E, const int wid) {
;     ...
;         for (int t = 0; t < nt; t += 2) {
;             const bool last = (t == nt - 2);
;             const char* a1 = cA + (size_t)(t + 1) * kstep;
;             const char* a2 = last ? nA : cA + (size_t)(t + 2) * kstep; const char* b2 = last ? nB : cB + (size_t)(t + 2) * kstep;
;     ...
;             PG8_LDA(At, 1, 1); PG8_STAGE(PG8_SB(1, 0), b3, voffB); PG8_STAGE(PG8_SB(1, 1), b3 + hstep, voffB); PG8_STAGE(PG8_SA(1, 0), a3, voffA);
;             PG8_WAIT_V(8); PG8_WAIT_L(0); PG8_BAR; PG8_MMA(1, 0, At, B0); PG8_MMA(1, 1, At, B1); PG8_BAR; PG8_SCHED;
	s_add_i32 s30, s33, s38
	v_lshl_add_u64 v[212:213], v[212:213], 0, s[18:19]
	s_mov_b32 m0, s30
	ds_read_b128 v[180:183], v151 offset:49152
	ds_read_b128 v[184:187], v151 offset:50176
	ds_read_b128 v[188:191], v151 offset:51200
	ds_read_b128 v[192:195], v151 offset:52224
	ds_read_b128 v[196:199], v151 offset:53248
	ds_read_b128 v[200:203], v151 offset:54272
	ds_read_b128 v[204:207], v151 offset:55296
	ds_read_b128 v[208:211], v151 offset:56320
	global_load_lds_dwordx4 v[212:213], off
	v_lshl_add_u64 v[212:213], v[214:215], 0, s[18:19]
	s_add_i32 m0, s30, 0x2000
	s_add_i32 s30, s67, s38
	global_load_lds_dwordx4 v[212:213], off
	v_lshl_add_u64 v[212:213], v[216:217], 0, s[18:19]
	s_mov_b32 m0, s30
	s_nop 0
	global_load_lds_dwordx4 v[212:213], off
	v_lshl_add_u64 v[212:213], v[218:219], 0, s[18:19]
	s_add_i32 m0, s30, 0x2000
	s_nop 0
	global_load_lds_dwordx4 v[212:213], off
	v_lshl_add_u64 v[212:213], v[220:221], 0, s[18:19]
	s_mov_b32 m0, s52
	s_nop 0
	global_load_lds_dwordx4 v[212:213], off
	v_lshl_add_u64 v[212:213], v[222:223], 0, s[18:19]
	s_mov_b32 m0, s53
	s_nop 0
	global_load_lds_dwordx4 v[212:213], off
	s_waitcnt vmcnt(8)
	s_waitcnt lgkmcnt(0)
	s_barrier
	s_setprio 1
	s_waitcnt lgkmcnt(0)
	v_mfma_f32_16x16x32_bf16 v[60:63], v[142:145], v[180:183], v[60:63]
	v_mfma_f32_16x16x32_bf16 v[56:59], v[156:159], v[180:183], v[56:59]
	v_mfma_f32_16x16x32_bf16 v[44:47], v[142:145], v[188:191], v[44:47]
	v_mfma_f32_16x16x32_bf16 v[40:43], v[156:159], v[188:191], v[40:43]
	v_mfma_f32_16x16x32_bf16 v[28:31], v[142:145], v[196:199], v[28:31]
	v_mfma_f32_16x16x32_bf16 v[24:27], v[156:159], v[196:199], v[24:27]
	v_mfma_f32_16x16x32_bf16 v[12:15], v[142:145], v[204:207], v[12:15]
	v_mfma_f32_16x16x32_bf16 v[8:11], v[156:159], v[204:207], v[8:11]
	v_mfma_f32_16x16x32_bf16 v[60:63], v[152:155], v[184:187], v[60:63]
	v_mfma_f32_16x16x32_bf16 v[56:59], v[160:163], v[184:187], v[56:59]
	v_mfma_f32_16x16x32_bf16 v[44:47], v[152:155], v[192:195], v[44:47]
	v_mfma_f32_16x16x32_bf16 v[40:43], v[160:163], v[192:195], v[40:43]
	v_mfma_f32_16x16x32_bf16 v[28:31], v[152:155], v[200:203], v[28:31]
	v_mfma_f32_16x16x32_bf16 v[24:27], v[160:163], v[200:203], v[24:27]
	v_mfma_f32_16x16x32_bf16 v[12:15], v[152:155], v[208:211], v[12:15]
	v_mfma_f32_16x16x32_bf16 v[8:11], v[160:163], v[208:211], v[8:11]
	s_setprio 0
	s_setprio 1
	v_mfma_f32_16x16x32_bf16 v[52:55], v[164:167], v[180:183], v[52:55]
	v_mfma_f32_16x16x32_bf16 v[48:51], v[172:175], v[180:183], v[48:51]
	v_mfma_f32_16x16x32_bf16 v[36:39], v[164:167], v[188:191], v[36:39]
	v_mfma_f32_16x16x32_bf16 v[32:35], v[172:175], v[188:191], v[32:35]
	v_mfma_f32_16x16x32_bf16 v[20:23], v[164:167], v[196:199], v[20:23]
	v_mfma_f32_16x16x32_bf16 v[16:19], v[172:175], v[196:199], v[16:19]
	v_mfma_f32_16x16x32_bf16 v[4:7], v[164:167], v[204:207], v[4:7]
	v_mfma_f32_16x16x32_bf16 v[0:3], v[172:175], v[204:207], v[0:3]
	v_mfma_f32_16x16x32_bf16 v[52:55], v[168:171], v[184:187], v[52:55]
	v_mfma_f32_16x16x32_bf16 v[48:51], v[176:179], v[184:187], v[48:51]
	v_mfma_f32_16x16x32_bf16 v[36:39], v[168:171], v[192:195], v[36:39]
	v_mfma_f32_16x16x32_bf16 v[32:35], v[176:179], v[192:195], v[32:35]
	v_mfma_f32_16x16x32_bf16 v[20:23], v[168:171], v[200:203], v[20:23]
	v_mfma_f32_16x16x32_bf16 v[16:19], v[176:179], v[200:203], v[16:19]
	v_mfma_f32_16x16x32_bf16 v[4:7], v[168:171], v[208:211], v[4:7]
	v_mfma_f32_16x16x32_bf16 v[0:3], v[176:179], v[208:211], v[0:3]
	s_setprio 0
	s_barrier
	s_add_u32 s28, s28, 0x100
	s_addc_u32 s29, s29, 0
	s_add_u32 s0, s0, 0x100
	s_addc_u32 s1, s1, 0
	s_cmp_ge_i32 s66, s54
	s_mov_b32 s30, s66
	s_cbranch_scc0 .LBB0_1258

; #define PG8_STAGE(bufoff, gbase, voff) do { _Pragma("unroll") for (int _i = 0; _i < 2; ++_i) \
;         __builtin_amdgcn_global_load_lds((const unsigned*)((const char*)(gbase) + (voff)[_i]), (PG8_LAS unsigned*)(lds + (bufoff) + ldsw + _i * 8192), 16, 0, 0); } while (0)
; #define PG8_LDA(dst, b, h) do { _Pragma("unroll") for (int m = 0; m < 4; ++m) _Pragma("unroll") for (int k = 0; k < 2; ++k) dst[m][k] = *(const PG8_LAS bf16x8*)(lds + PG8_SA(b, h) + aoff + m * 2048 + k * 1024); } while (0)
; #define PG8_LDB(dst, b, h) do { _Pragma("unroll") for (int n = 0; n < 2; ++n) _Pragma("unroll") for (int k = 0; k < 2; ++k) dst[n][k] = *(const PG8_LAS bf16x8*)(lds + PG8_SB(b, h) + boff + n * 2048 + k * 1024); } while (0)
; #define PG8_MMA(ai, bj, At, Bt) do { __builtin_amdgcn_s_setprio(1); _Pragma("unroll") for (int m = 0; m < 4; ++m) _Pragma("unroll") for (int n = 0; n < 2; ++n) _Pragma("unroll") for (int k = 0; k < 2; ++k) \
;         acc[ai][bj][m][n] = __builtin_amdgcn_mfma_f32_16x16x32_bf16(Bt[n][k], At[m][k], acc[ai][bj][m][n], 0, 0, 0); __builtin_amdgcn_s_setprio(0); } while (0)
; #define PG8_WAIT_V(n) asm volatile("s_waitcnt vmcnt(" #n ")" ::: "memory")
; #define PG8_WAIT_L(n) asm volatile("s_waitcnt lgkmcnt(" #n ")" ::: "memory")
; #define PG8_BAR __builtin_amdgcn_s_barrier()
; #define PG8_SCHED __builtin_amdgcn_sched_barrier(0)
; template <class Epi, class Sched, bool ALIGN_EPI = false, bool SP2 = false>
; __device__ __forceinline__ void gemm_phase(PG8_LAS unsigned char* lds, const Gemm g, const Sched& S, const Epi& E, const int wid) {
;     ...
;         for (int t = 0; t < nt; t += 2) {
;             const bool last = (t == nt - 2);
;             const char* a1 = cA + (size_t)(t + 1) * kstep;
;             const char* a2 = last ? nA : cA + (size_t)(t + 2) * kstep; const char* b2 = last ? nB : cB + (size_t)(t + 2) * kstep;
;             const char* a3 = a2 + kstep; const char* b3 = b2 + kstep;
;             if (last && has_next) S.a_ready(nxt);
;             if constexpr (SP2) {
;             PG8_LDB(B0, 0, 0); PG8_LDB(B1, 0, 1); PG8_SCHED; PG8_LDA(At, 0, 0); PG8_STAGE(PG8_SA(1, 1), a1 + hstep, voffA);
;             PG8_WAIT_V(8); PG8_WAIT_L(0); PG8_BAR; PG8_MMA(0, 0, At, B0); PG8_MMA(0, 1, At, B1); PG8_BAR; PG8_SCHED;
.LBB0_1339:
	ds_read_b128 v[142:145], v149
	ds_read_b128 v[154:157], v149 offset:1024
	ds_read_b128 v[158:161], v149 offset:2048
	ds_read_b128 v[162:165], v149 offset:3072
	ds_read_b128 v[166:169], v150
	ds_read_b128 v[170:173], v150 offset:1024
	ds_read_b128 v[174:177], v150 offset:2048
	ds_read_b128 v[178:181], v150 offset:3072
	s_add_i32 s36, s34, 2
	s_add_u32 s33, s4, 0x80
	s_addc_u32 s35, s5, 0
	s_cmp_eq_u32 s54, s34
	s_cselect_b32 s34, s28, s33
	s_cselect_b32 s35, s29, s35
	s_cselect_b32 s69, s31, s1
	s_cselect_b32 s68, s30, s0
	v_lshl_add_u64 v[214:215], s[4:5], 0, v[136:137]
	s_add_i32 m0, s43, 0xc000
	ds_read_b128 v[182:185], v151
	ds_read_b128 v[186:189], v151 offset:1024
	ds_read_b128 v[190:193], v151 offset:2048
	ds_read_b128 v[194:197], v151 offset:3072
	ds_read_b128 v[198:201], v151 offset:4096
	ds_read_b128 v[202:205], v151 offset:5120
	ds_read_b128 v[206:209], v151 offset:6144
	ds_read_b128 v[210:213], v151 offset:7168
	global_load_lds_dwordx4 v[214:215], off
	v_lshl_add_u64 v[214:215], s[4:5], 0, v[138:139]
	s_add_i32 m0, s43, 0xe000
	s_nop 0
	global_load_lds_dwordx4 v[214:215], off
	s_cmp_lg_u32 s36, 2
	s_cbranch_scc1 .Lw8__1339_0
	s_cmp_eq_u32 s64, 1
	s_cbranch_scc1 .Lw8__1339_0
	s_waitcnt vmcnt(32)
	s_branch .Lwj__1339_0

; #define PG8_STAGE(bufoff, gbase, voff) do { _Pragma("unroll") for (int _i = 0; _i < 2; ++_i) \
;         __builtin_amdgcn_global_load_lds((const unsigned*)((const char*)(gbase) + (voff)[_i]), (PG8_LAS unsigned*)(lds + (bufoff) + ldsw + _i * 8192), 16, 0, 0); } while (0)
; #define PG8_LDA(dst, b, h) do { _Pragma("unroll") for (int m = 0; m < 4; ++m) _Pragma("unroll") for (int k = 0; k < 2; ++k) dst[m][k] = *(const PG8_LAS bf16x8*)(lds + PG8_SA(b, h) + aoff + m * 2048 + k * 1024); } while (0)
; #define PG8_MMA(ai, bj, At, Bt) do { __builtin_amdgcn_s_setprio(1); _Pragma("unroll") for (int m = 0; m < 4; ++m) _Pragma("unroll") for (int n = 0; n < 2; ++n) _Pragma("unroll") for (int k = 0; k < 2; ++k) \
;         acc[ai][bj][m][n] = __builtin_amdgcn_mfma_f32_16x16x32_bf16(Bt[n][k], At[m][k], acc[ai][bj][m][n], 0, 0, 0); __builtin_amdgcn_s_setprio(0); } while (0)
; #define PG8_WAIT_V(n) asm volatile("s_waitcnt vmcnt(" #n ")" ::: "memory")
; #define PG8_WAIT_L(n) asm volatile("s_waitcnt lgkmcnt(" #n ")" ::: "memory")
; #define PG8_BAR __builtin_amdgcn_s_barrier()
; #define PG8_SCHED __builtin_amdgcn_sched_barrier(0)
; template <class Epi, class Sched, bool ALIGN_EPI = false, bool SP2 = false>
; __device__ __forceinline__ void gemm_phase(PG8_LAS unsigned char* lds, const Gemm g, const Sched& S, const Epi& E, const int wid) {
;     ...
;             PG8_WAIT_V(8); PG8_WAIT_L(0); PG8_BAR; PG8_MMA(0, 0, At, B0); PG8_MMA(0, 1, At, B1); PG8_BAR; PG8_SCHED;
;             PG8_LDA(At, 0, 1); PG8_STAGE(PG8_SB(0, 0), b2, voffB); PG8_STAGE(PG8_SB(0, 1), b2 + hstep, voffB); PG8_STAGE(PG8_SA(0, 0), a2, voffA);
;             PG8_WAIT_V(8); PG8_WAIT_L(0); PG8_BAR; PG8_MMA(1, 0, At, B0); PG8_MMA(1, 1, At, B1); PG8_BAR; PG8_SCHED;
.Lwj__1339_0:
	s_waitcnt lgkmcnt(0)
	s_barrier
	s_setprio 1
	s_waitcnt lgkmcnt(0)
	v_mfma_f32_16x16x32_bf16 v[120:123], v[142:145], v[182:185], v[120:123]
	v_mfma_f32_16x16x32_bf16 v[124:127], v[158:161], v[182:185], v[124:127]
	v_mfma_f32_16x16x32_bf16 v[108:111], v[142:145], v[190:193], v[108:111]
	v_mfma_f32_16x16x32_bf16 v[104:107], v[158:161], v[190:193], v[104:107]
	v_mfma_f32_16x16x32_bf16 v[92:95], v[142:145], v[198:201], v[92:95]
	v_mfma_f32_16x16x32_bf16 v[88:91], v[158:161], v[198:201], v[88:91]
	v_mfma_f32_16x16x32_bf16 v[76:79], v[142:145], v[206:209], v[76:79]
	v_mfma_f32_16x16x32_bf16 v[72:75], v[158:161], v[206:209], v[72:75]
	v_mfma_f32_16x16x32_bf16 v[120:123], v[154:157], v[186:189], v[120:123]
	v_mfma_f32_16x16x32_bf16 v[124:127], v[162:165], v[186:189], v[124:127]
	v_mfma_f32_16x16x32_bf16 v[108:111], v[154:157], v[194:197], v[108:111]
	v_mfma_f32_16x16x32_bf16 v[104:107], v[162:165], v[194:197], v[104:107]
	v_mfma_f32_16x16x32_bf16 v[92:95], v[154:157], v[202:205], v[92:95]
	v_mfma_f32_16x16x32_bf16 v[88:91], v[162:165], v[202:205], v[88:91]
	v_mfma_f32_16x16x32_bf16 v[76:79], v[154:157], v[210:213], v[76:79]
	v_mfma_f32_16x16x32_bf16 v[72:75], v[162:165], v[210:213], v[72:75]
	s_setprio 0
	s_setprio 1
	v_mfma_f32_16x16x32_bf16 v[116:119], v[166:169], v[182:185], v[116:119]
	v_mfma_f32_16x16x32_bf16 v[112:115], v[174:177], v[182:185], v[112:115]
	v_mfma_f32_16x16x32_bf16 v[100:103], v[166:169], v[190:193], v[100:103]
	v_mfma_f32_16x16x32_bf16 v[96:99], v[174:177], v[190:193], v[96:99]
	v_mfma_f32_16x16x32_bf16 v[84:87], v[166:169], v[198:201], v[84:87]
	v_mfma_f32_16x16x32_bf16 v[80:83], v[174:177], v[198:201], v[80:83]
	v_mfma_f32_16x16x32_bf16 v[68:71], v[166:169], v[206:209], v[68:71]
	v_mfma_f32_16x16x32_bf16 v[64:67], v[174:177], v[206:209], v[64:67]
	v_mfma_f32_16x16x32_bf16 v[116:119], v[170:173], v[186:189], v[116:119]
	v_mfma_f32_16x16x32_bf16 v[112:115], v[178:181], v[186:189], v[112:115]
	v_mfma_f32_16x16x32_bf16 v[100:103], v[170:173], v[194:197], v[100:103]
	v_mfma_f32_16x16x32_bf16 v[96:99], v[178:181], v[194:197], v[96:99]
	v_mfma_f32_16x16x32_bf16 v[84:87], v[170:173], v[202:205], v[84:87]
	v_mfma_f32_16x16x32_bf16 v[80:83], v[178:181], v[202:205], v[80:83]
	v_mfma_f32_16x16x32_bf16 v[68:71], v[170:173], v[210:213], v[68:71]
	v_mfma_f32_16x16x32_bf16 v[64:67], v[178:181], v[210:213], v[64:67]
	s_setprio 0
	s_barrier
	s_add_i32 s33, s62, s42
	v_lshl_add_u64 v[214:215], s[68:69], 0, v[130:131]
	s_mov_b32 m0, s33
	ds_read_b128 v[182:185], v151 offset:16384
	ds_read_b128 v[186:189], v151 offset:17408
	ds_read_b128 v[190:193], v151 offset:18432
	ds_read_b128 v[194:197], v151 offset:19456
	ds_read_b128 v[198:201], v151 offset:20480
	ds_read_b128 v[202:205], v151 offset:21504
	ds_read_b128 v[206:209], v151 offset:22528
	ds_read_b128 v[210:213], v151 offset:23552
	global_load_lds_dwordx4 v[214:215], off
	s_add_i32 m0, s33, 0x2000
	v_lshl_add_u64 v[216:217], s[68:69], 0, v[134:135]
	s_add_u32 s68, s68, s8
	s_addc_u32 s69, s69, s9
	s_add_i32 s33, s63, s42
	global_load_lds_dwordx4 v[216:217], off
	v_lshl_add_u64 v[218:219], s[68:69], 0, v[130:131]
	s_mov_b32 m0, s33
	v_lshl_add_u64 v[220:221], s[68:69], 0, v[134:135]
	global_load_lds_dwordx4 v[218:219], off
	s_add_i32 m0, s33, 0x2000
	v_lshl_add_u64 v[222:223], s[34:35], 0, v[128:129]
	global_load_lds_dwordx4 v[220:221], off
	s_mov_b32 m0, s43
	v_lshl_add_u64 v[224:225], s[34:35], 0, v[132:133]
	global_load_lds_dwordx4 v[222:223], off
	s_mov_b32 m0, s44
	s_nop 0
	global_load_lds_dwordx4 v[224:225], off
	s_cmp_lg_u32 s36, 2
	s_cbranch_scc1 .Lw8__1339_1
	s_cmp_eq_u32 s64, 1
	s_cbranch_scc1 .Lw8__1339_1
	s_waitcnt vmcnt(32)
	s_branch .Lwj__1339_1

; #define PG8_STAGE(bufoff, gbase, voff) do { _Pragma("unroll") for (int _i = 0; _i < 2; ++_i) \
;         __builtin_amdgcn_global_load_lds((const unsigned*)((const char*)(gbase) + (voff)[_i]), (PG8_LAS unsigned*)(lds + (bufoff) + ldsw + _i * 8192), 16, 0, 0); } while (0)
; #define PG8_LDA(dst, b, h) do { _Pragma("unroll") for (int m = 0; m < 4; ++m) _Pragma("unroll") for (int k = 0; k < 2; ++k) dst[m][k] = *(const PG8_LAS bf16x8*)(lds + PG8_SA(b, h) + aoff + m * 2048 + k * 1024); } while (0)
; #define PG8_LDB(dst, b, h) do { _Pragma("unroll") for (int n = 0; n < 2; ++n) _Pragma("unroll") for (int k = 0; k < 2; ++k) dst[n][k] = *(const PG8_LAS bf16x8*)(lds + PG8_SB(b, h) + boff + n * 2048 + k * 1024); } while (0)
; #define PG8_MMA(ai, bj, At, Bt) do { __builtin_amdgcn_s_setprio(1); _Pragma("unroll") for (int m = 0; m < 4; ++m) _Pragma("unroll") for (int n = 0; n < 2; ++n) _Pragma("unroll") for (int k = 0; k < 2; ++k) \
;         acc[ai][bj][m][n] = __builtin_amdgcn_mfma_f32_16x16x32_bf16(Bt[n][k], At[m][k], acc[ai][bj][m][n], 0, 0, 0); __builtin_amdgcn_s_setprio(0); } while (0)
; #define PG8_WAIT_V(n) asm volatile("s_waitcnt vmcnt(" #n ")" ::: "memory")
; #define PG8_WAIT_L(n) asm volatile("s_waitcnt lgkmcnt(" #n ")" ::: "memory")
; #define PG8_BAR __builtin_amdgcn_s_barrier()
; #define PG8_SCHED __builtin_amdgcn_sched_barrier(0)
; template <class Epi, class Sched, bool ALIGN_EPI = false, bool SP2 = false>
; __device__ __forceinline__ void gemm_phase(PG8_LAS unsigned char* lds, const Gemm g, const Sched& S, const Epi& E, const int wid) {
;     ...
;             PG8_WAIT_V(8); PG8_WAIT_L(0); PG8_BAR; PG8_MMA(1, 0, At, B0); PG8_MMA(1, 1, At, B1); PG8_BAR; PG8_SCHED;
;             PG8_LDB(B0, 1, 0); PG8_LDB(B1, 1, 1); PG8_SCHED; PG8_LDA(At, 1, 0); PG8_STAGE(PG8_SA(0, 1), a2 + hstep, voffA);
;             PG8_WAIT_V(8); PG8_WAIT_L(0); PG8_BAR; PG8_MMA(0, 0, At, B0); PG8_MMA(0, 1, At, B1); PG8_BAR; PG8_SCHED;
.Lwj__1339_1:
	s_waitcnt lgkmcnt(0)
	s_barrier
	s_setprio 1
	s_waitcnt lgkmcnt(0)
	v_mfma_f32_16x16x32_bf16 v[60:63], v[142:145], v[182:185], v[60:63]
	v_mfma_f32_16x16x32_bf16 v[56:59], v[158:161], v[182:185], v[56:59]
	v_mfma_f32_16x16x32_bf16 v[44:47], v[142:145], v[190:193], v[44:47]
	v_mfma_f32_16x16x32_bf16 v[40:43], v[158:161], v[190:193], v[40:43]
	v_mfma_f32_16x16x32_bf16 v[28:31], v[142:145], v[198:201], v[28:31]
	v_mfma_f32_16x16x32_bf16 v[24:27], v[158:161], v[198:201], v[24:27]
	v_mfma_f32_16x16x32_bf16 v[12:15], v[142:145], v[206:209], v[12:15]
	v_mfma_f32_16x16x32_bf16 v[8:11], v[158:161], v[206:209], v[8:11]
	v_mfma_f32_16x16x32_bf16 v[60:63], v[154:157], v[186:189], v[60:63]
	v_mfma_f32_16x16x32_bf16 v[56:59], v[162:165], v[186:189], v[56:59]
	v_mfma_f32_16x16x32_bf16 v[44:47], v[154:157], v[194:197], v[44:47]
	v_mfma_f32_16x16x32_bf16 v[40:43], v[162:165], v[194:197], v[40:43]
	v_mfma_f32_16x16x32_bf16 v[28:31], v[154:157], v[202:205], v[28:31]
	v_mfma_f32_16x16x32_bf16 v[24:27], v[162:165], v[202:205], v[24:27]
	v_mfma_f32_16x16x32_bf16 v[12:15], v[154:157], v[210:213], v[12:15]
	v_mfma_f32_16x16x32_bf16 v[8:11], v[162:165], v[210:213], v[8:11]
	s_setprio 0
	s_setprio 1
	v_mfma_f32_16x16x32_bf16 v[52:55], v[166:169], v[182:185], v[52:55]
	v_mfma_f32_16x16x32_bf16 v[48:51], v[174:177], v[182:185], v[48:51]
	v_mfma_f32_16x16x32_bf16 v[36:39], v[166:169], v[190:193], v[36:39]
	v_mfma_f32_16x16x32_bf16 v[32:35], v[174:177], v[190:193], v[32:35]
	v_mfma_f32_16x16x32_bf16 v[20:23], v[166:169], v[198:201], v[20:23]
	v_mfma_f32_16x16x32_bf16 v[16:19], v[174:177], v[198:201], v[16:19]
	v_mfma_f32_16x16x32_bf16 v[4:7], v[166:169], v[206:209], v[4:7]
	v_mfma_f32_16x16x32_bf16 v[0:3], v[174:177], v[206:209], v[0:3]
	v_mfma_f32_16x16x32_bf16 v[52:55], v[170:173], v[186:189], v[52:55]
	v_mfma_f32_16x16x32_bf16 v[48:51], v[178:181], v[186:189], v[48:51]
	v_mfma_f32_16x16x32_bf16 v[36:39], v[170:173], v[194:197], v[36:39]
	v_mfma_f32_16x16x32_bf16 v[32:35], v[178:181], v[194:197], v[32:35]
	v_mfma_f32_16x16x32_bf16 v[20:23], v[170:173], v[202:205], v[20:23]
	v_mfma_f32_16x16x32_bf16 v[16:19], v[178:181], v[202:205], v[16:19]
	v_mfma_f32_16x16x32_bf16 v[4:7], v[170:173], v[210:213], v[4:7]
	v_mfma_f32_16x16x32_bf16 v[0:3], v[178:181], v[210:213], v[0:3]
	s_setprio 0
	s_barrier
	s_add_i32 s33, 0, 0x18000
	v_add_u32_e32 v153, s33, v148
	s_add_i32 s37, 0, 0x1c000
	ds_read_b128 v[142:145], v153
	ds_read_b128 v[154:157], v153 offset:1024
	ds_read_b128 v[158:161], v153 offset:2048
	ds_read_b128 v[162:165], v153 offset:3072
	v_add_u32_e32 v153, s37, v148
	ds_read_b128 v[166:169], v153
	ds_read_b128 v[170:173], v153 offset:1024
	ds_read_b128 v[174:177], v153 offset:2048
	ds_read_b128 v[178:181], v153 offset:3072
	s_add_u32 s34, s34, s8
	s_addc_u32 s35, s35, s9
	s_mov_b32 m0, s45
	v_lshl_add_u64 v[226:227], s[34:35], 0, v[128:129]
	ds_read_b128 v[182:185], v151 offset:32768
	ds_read_b128 v[186:189], v151 offset:33792
	ds_read_b128 v[190:193], v151 offset:34816
	ds_read_b128 v[194:197], v151 offset:35840
	ds_read_b128 v[198:201], v151 offset:36864
	ds_read_b128 v[202:205], v151 offset:37888
	ds_read_b128 v[206:209], v151 offset:38912
	ds_read_b128 v[210:213], v151 offset:39936
	global_load_lds_dwordx4 v[226:227], off
	v_lshl_add_u64 v[226:227], s[34:35], 0, v[132:133]
	s_mov_b32 m0, s46
	s_nop 0
	global_load_lds_dwordx4 v[226:227], off
	s_waitcnt vmcnt(8)
	s_waitcnt lgkmcnt(0)
	s_barrier
	s_setprio 1
	s_waitcnt lgkmcnt(0)
	v_mfma_f32_16x16x32_bf16 v[120:123], v[142:145], v[182:185], v[120:123]
	v_mfma_f32_16x16x32_bf16 v[124:127], v[158:161], v[182:185], v[124:127]
	v_mfma_f32_16x16x32_bf16 v[108:111], v[142:145], v[190:193], v[108:111]
	v_mfma_f32_16x16x32_bf16 v[104:107], v[158:161], v[190:193], v[104:107]
	v_mfma_f32_16x16x32_bf16 v[92:95], v[142:145], v[198:201], v[92:95]
	v_mfma_f32_16x16x32_bf16 v[88:91], v[158:161], v[198:201], v[88:91]
	v_mfma_f32_16x16x32_bf16 v[76:79], v[142:145], v[206:209], v[76:79]
	v_mfma_f32_16x16x32_bf16 v[72:75], v[158:161], v[206:209], v[72:75]
	v_mfma_f32_16x16x32_bf16 v[120:123], v[154:157], v[186:189], v[120:123]
	v_mfma_f32_16x16x32_bf16 v[124:127], v[162:165], v[186:189], v[124:127]
	v_mfma_f32_16x16x32_bf16 v[108:111], v[154:157], v[194:197], v[108:111]
	v_mfma_f32_16x16x32_bf16 v[104:107], v[162:165], v[194:197], v[104:107]
	v_mfma_f32_16x16x32_bf16 v[92:95], v[154:157], v[202:205], v[92:95]
	v_mfma_f32_16x16x32_bf16 v[88:91], v[162:165], v[202:205], v[88:91]
	v_mfma_f32_16x16x32_bf16 v[76:79], v[154:157], v[210:213], v[76:79]
	v_mfma_f32_16x16x32_bf16 v[72:75], v[162:165], v[210:213], v[72:75]
	s_setprio 0
	s_setprio 1
	v_mfma_f32_16x16x32_bf16 v[116:119], v[166:169], v[182:185], v[116:119]
	v_mfma_f32_16x16x32_bf16 v[112:115], v[174:177], v[182:185], v[112:115]
	v_mfma_f32_16x16x32_bf16 v[100:103], v[166:169], v[190:193], v[100:103]
	v_mfma_f32_16x16x32_bf16 v[96:99], v[174:177], v[190:193], v[96:99]
	v_mfma_f32_16x16x32_bf16 v[84:87], v[166:169], v[198:201], v[84:87]
	v_mfma_f32_16x16x32_bf16 v[80:83], v[174:177], v[198:201], v[80:83]
	v_mfma_f32_16x16x32_bf16 v[68:71], v[166:169], v[206:209], v[68:71]
	v_mfma_f32_16x16x32_bf16 v[64:67], v[174:177], v[206:209], v[64:67]
	v_mfma_f32_16x16x32_bf16 v[116:119], v[170:173], v[186:189], v[116:119]
	v_mfma_f32_16x16x32_bf16 v[112:115], v[178:181], v[186:189], v[112:115]
	v_mfma_f32_16x16x32_bf16 v[100:103], v[170:173], v[194:197], v[100:103]
	v_mfma_f32_16x16x32_bf16 v[96:99], v[178:181], v[194:197], v[96:99]
	v_mfma_f32_16x16x32_bf16 v[84:87], v[170:173], v[202:205], v[84:87]
	v_mfma_f32_16x16x32_bf16 v[80:83], v[178:181], v[202:205], v[80:83]
	v_mfma_f32_16x16x32_bf16 v[68:71], v[170:173], v[210:213], v[68:71]
	v_mfma_f32_16x16x32_bf16 v[64:67], v[178:181], v[210:213], v[64:67]
	s_setprio 0
	s_barrier
; #define PG8_STAGE(bufoff, gbase, voff) do { _Pragma("unroll") for (int _i = 0; _i < 2; ++_i) \
;         __builtin_amdgcn_global_load_lds((const unsigned*)((const char*)(gbase) + (voff)[_i]), (PG8_LAS unsigned*)(lds + (bufoff) + ldsw + _i * 8192), 16, 0, 0); } while (0)
; #define PG8_LDA(dst, b, h) do { _Pragma("unroll") for (int m = 0; m < 4; ++m) _Pragma("unroll") for (int k = 0; k < 2; ++k) dst[m][k] = *(const PG8_LAS bf16x8*)(lds + PG8_SA(b, h) + aoff + m * 2048 + k * 1024); } while (0)
; #define PG8_MMA(ai, bj, At, Bt) do { __builtin_amdgcn_s_setprio(1); _Pragma("unroll") for (int m = 0; m < 4; ++m) _Pragma("unroll") for (int n = 0; n < 2; ++n) _Pragma("unroll") for (int k = 0; k < 2; ++k) \
;         acc[ai][bj][m][n] = __builtin_amdgcn_mfma_f32_16x16x32_bf16(Bt[n][k], At[m][k], acc[ai][bj][m][n], 0, 0, 0); __builtin_amdgcn_s_setprio(0); } while (0)
; #define PG8_WAIT_V(n) asm volatile("s_waitcnt vmcnt(" #n ")" ::: "memory")
; #define PG8_WAIT_L(n) asm volatile("s_waitcnt lgkmcnt(" #n ")" ::: "memory")
; #define PG8_BAR __builtin_amdgcn_s_barrier()
; #define PG8_SCHED __builtin_amdgcn_sched_barrier(0)
; template <class Epi, class Sched, bool ALIGN_EPI = false, bool SP2 = false>
; __device__ __forceinline__ void gemm_phase(PG8_LAS unsigned char* lds, const Gemm g, const Sched& S, const Epi& E, const int wid) {
;     ...
;         for (int t = 0; t < nt; t += 2) {
;             const bool last = (t == nt - 2);
;             const char* a1 = cA + (size_t)(t + 1) * kstep;
;             const char* a2 = last ? nA : cA + (size_t)(t + 2) * kstep; const char* b2 = last ? nB : cB + (size_t)(t + 2) * kstep;
;     ...
;             PG8_LDA(At, 1, 1); PG8_STAGE(PG8_SB(1, 0), b3, voffB); PG8_STAGE(PG8_SB(1, 1), b3 + hstep, voffB); PG8_STAGE(PG8_SA(1, 0), a3, voffA);
;             PG8_WAIT_V(8); PG8_WAIT_L(0); PG8_BAR; PG8_MMA(1, 0, At, B0); PG8_MMA(1, 1, At, B1); PG8_BAR; PG8_SCHED;
	s_add_i32 s33, s33, s42
	v_lshl_add_u64 v[214:215], v[214:215], 0, s[22:23]
	s_mov_b32 m0, s33
	ds_read_b128 v[182:185], v151 offset:49152
	ds_read_b128 v[186:189], v151 offset:50176
	ds_read_b128 v[190:193], v151 offset:51200
	ds_read_b128 v[194:197], v151 offset:52224
	ds_read_b128 v[198:201], v151 offset:53248
	ds_read_b128 v[202:205], v151 offset:54272
	ds_read_b128 v[206:209], v151 offset:55296
	ds_read_b128 v[210:213], v151 offset:56320
	global_load_lds_dwordx4 v[214:215], off
	v_lshl_add_u64 v[214:215], v[216:217], 0, s[22:23]
	s_add_i32 m0, s33, 0x2000
	s_add_i32 s33, s37, s42
	global_load_lds_dwordx4 v[214:215], off
	v_lshl_add_u64 v[214:215], v[218:219], 0, s[22:23]
	s_mov_b32 m0, s33
	s_nop 0
	global_load_lds_dwordx4 v[214:215], off
	v_lshl_add_u64 v[214:215], v[220:221], 0, s[22:23]
	s_add_i32 m0, s33, 0x2000
	s_nop 0
	global_load_lds_dwordx4 v[214:215], off
	v_lshl_add_u64 v[214:215], v[222:223], 0, s[22:23]
	s_mov_b32 m0, s47
	s_nop 0
	global_load_lds_dwordx4 v[214:215], off
	v_lshl_add_u64 v[214:215], v[224:225], 0, s[22:23]
	s_mov_b32 m0, s49
	s_nop 0
	global_load_lds_dwordx4 v[214:215], off
	s_waitcnt vmcnt(8)
	s_waitcnt lgkmcnt(0)
	s_barrier
	s_setprio 1
	s_waitcnt lgkmcnt(0)
	v_mfma_f32_16x16x32_bf16 v[60:63], v[142:145], v[182:185], v[60:63]
	v_mfma_f32_16x16x32_bf16 v[56:59], v[158:161], v[182:185], v[56:59]
	v_mfma_f32_16x16x32_bf16 v[44:47], v[142:145], v[190:193], v[44:47]
	v_mfma_f32_16x16x32_bf16 v[40:43], v[158:161], v[190:193], v[40:43]
	v_mfma_f32_16x16x32_bf16 v[28:31], v[142:145], v[198:201], v[28:31]
	v_mfma_f32_16x16x32_bf16 v[24:27], v[158:161], v[198:201], v[24:27]
	v_mfma_f32_16x16x32_bf16 v[12:15], v[142:145], v[206:209], v[12:15]
	v_mfma_f32_16x16x32_bf16 v[8:11], v[158:161], v[206:209], v[8:11]
	v_mfma_f32_16x16x32_bf16 v[60:63], v[154:157], v[186:189], v[60:63]
	v_mfma_f32_16x16x32_bf16 v[56:59], v[162:165], v[186:189], v[56:59]
	v_mfma_f32_16x16x32_bf16 v[44:47], v[154:157], v[194:197], v[44:47]
	v_mfma_f32_16x16x32_bf16 v[40:43], v[162:165], v[194:197], v[40:43]
	v_mfma_f32_16x16x32_bf16 v[28:31], v[154:157], v[202:205], v[28:31]
	v_mfma_f32_16x16x32_bf16 v[24:27], v[162:165], v[202:205], v[24:27]
	v_mfma_f32_16x16x32_bf16 v[12:15], v[154:157], v[210:213], v[12:15]
	v_mfma_f32_16x16x32_bf16 v[8:11], v[162:165], v[210:213], v[8:11]
	s_setprio 0
	s_setprio 1
	v_mfma_f32_16x16x32_bf16 v[52:55], v[166:169], v[182:185], v[52:55]
	v_mfma_f32_16x16x32_bf16 v[48:51], v[174:177], v[182:185], v[48:51]
	v_mfma_f32_16x16x32_bf16 v[36:39], v[166:169], v[190:193], v[36:39]
	v_mfma_f32_16x16x32_bf16 v[32:35], v[174:177], v[190:193], v[32:35]
	v_mfma_f32_16x16x32_bf16 v[20:23], v[166:169], v[198:201], v[20:23]
	v_mfma_f32_16x16x32_bf16 v[16:19], v[174:177], v[198:201], v[16:19]
	v_mfma_f32_16x16x32_bf16 v[4:7], v[166:169], v[206:209], v[4:7]
	v_mfma_f32_16x16x32_bf16 v[0:3], v[174:177], v[206:209], v[0:3]
	v_mfma_f32_16x16x32_bf16 v[52:55], v[170:173], v[186:189], v[52:55]
	v_mfma_f32_16x16x32_bf16 v[48:51], v[178:181], v[186:189], v[48:51]
	v_mfma_f32_16x16x32_bf16 v[36:39], v[170:173], v[194:197], v[36:39]
	v_mfma_f32_16x16x32_bf16 v[32:35], v[178:181], v[194:197], v[32:35]
	v_mfma_f32_16x16x32_bf16 v[20:23], v[170:173], v[202:205], v[20:23]
	v_mfma_f32_16x16x32_bf16 v[16:19], v[178:181], v[202:205], v[16:19]
	v_mfma_f32_16x16x32_bf16 v[4:7], v[170:173], v[210:213], v[4:7]
	v_mfma_f32_16x16x32_bf16 v[0:3], v[178:181], v[210:213], v[0:3]
	s_setprio 0
	s_barrier
	s_add_u32 s4, s4, 0x100
	s_addc_u32 s5, s5, 0
	s_add_u32 s0, s0, 0x100
	s_addc_u32 s1, s1, 0
	s_cmp_ge_i32 s36, s51
	s_mov_b32 s34, s36
	s_cbranch_scc0 .LBB0_1339

; #define PG8_STAGE(bufoff, gbase, voff) do { _Pragma("unroll") for (int _i = 0; _i < 2; ++_i) \
;         __builtin_amdgcn_global_load_lds((const unsigned*)((const char*)(gbase) + (voff)[_i]), (PG8_LAS unsigned*)(lds + (bufoff) + ldsw + _i * 8192), 16, 0, 0); } while (0)
; #define PG8_LDA(dst, b, h) do { _Pragma("unroll") for (int m = 0; m < 4; ++m) _Pragma("unroll") for (int k = 0; k < 2; ++k) dst[m][k] = *(const PG8_LAS bf16x8*)(lds + PG8_SA(b, h) + aoff + m * 2048 + k * 1024); } while (0)
; #define PG8_LDB(dst, b, h) do { _Pragma("unroll") for (int n = 0; n < 2; ++n) _Pragma("unroll") for (int k = 0; k < 2; ++k) dst[n][k] = *(const PG8_LAS bf16x8*)(lds + PG8_SB(b, h) + boff + n * 2048 + k * 1024); } while (0)
; #define PG8_MMA(ai, bj, At, Bt) do { __builtin_amdgcn_s_setprio(1); _Pragma("unroll") for (int m = 0; m < 4; ++m) _Pragma("unroll") for (int n = 0; n < 2; ++n) _Pragma("unroll") for (int k = 0; k < 2; ++k) \
;         acc[ai][bj][m][n] = __builtin_amdgcn_mfma_f32_16x16x32_bf16(Bt[n][k], At[m][k], acc[ai][bj][m][n], 0, 0, 0); __builtin_amdgcn_s_setprio(0); } while (0)
; #define PG8_WAIT_V(n) asm volatile("s_waitcnt vmcnt(" #n ")" ::: "memory")
; #define PG8_WAIT_L(n) asm volatile("s_waitcnt lgkmcnt(" #n ")" ::: "memory")
; #define PG8_BAR __builtin_amdgcn_s_barrier()
; #define PG8_SCHED __builtin_amdgcn_sched_barrier(0)
; template <class Epi, class Sched, bool ALIGN_EPI = false, bool SP2 = false>
; __device__ __forceinline__ void gemm_phase(PG8_LAS unsigned char* lds, const Gemm g, const Sched& S, const Epi& E, const int wid) {
;     ...
;         for (int t = 0; t < nt; t += 2) {
;             const bool last = (t == nt - 2);
;             const char* a1 = cA + (size_t)(t + 1) * kstep;
;             const char* a2 = last ? nA : cA + (size_t)(t + 2) * kstep; const char* b2 = last ? nB : cB + (size_t)(t + 2) * kstep;
;             const char* a3 = a2 + kstep; const char* b3 = b2 + kstep;
;             if (last && has_next) S.a_ready(nxt);
;             if constexpr (SP2) {
;             PG8_LDB(B0, 0, 0); PG8_LDB(B1, 0, 1); PG8_SCHED; PG8_LDA(At, 0, 0); PG8_STAGE(PG8_SA(1, 1), a1 + hstep, voffA);
;             PG8_WAIT_V(8); PG8_WAIT_L(0); PG8_BAR; PG8_MMA(0, 0, At, B0); PG8_MMA(0, 1, At, B1); PG8_BAR; PG8_SCHED;
.LBB0_1495:
	ds_read_b128 v[142:145], v149
	ds_read_b128 v[152:155], v149 offset:1024
	ds_read_b128 v[156:159], v149 offset:2048
	ds_read_b128 v[160:163], v149 offset:3072
	ds_read_b128 v[164:167], v150
	ds_read_b128 v[168:171], v150 offset:1024
	ds_read_b128 v[172:175], v150 offset:2048
	ds_read_b128 v[176:179], v150 offset:3072
	s_add_i32 s8, s6, 2
	s_add_u32 s9, s4, 0x80
	s_addc_u32 s7, s5, 0
	s_cmp_eq_u32 s55, s6
	s_cselect_b32 s6, s26, s9
	s_cselect_b32 s7, s27, s7
	s_cselect_b32 s65, s29, s1
	s_cselect_b32 s64, s28, s0
	v_lshl_add_u64 v[212:213], s[4:5], 0, v[136:137]
	s_add_i32 m0, s44, 0xc000
	ds_read_b128 v[180:183], v151
	ds_read_b128 v[184:187], v151 offset:1024
	ds_read_b128 v[188:191], v151 offset:2048
	ds_read_b128 v[192:195], v151 offset:3072
	ds_read_b128 v[196:199], v151 offset:4096
	ds_read_b128 v[200:203], v151 offset:5120
	ds_read_b128 v[204:207], v151 offset:6144
	ds_read_b128 v[208:211], v151 offset:7168
	global_load_lds_dwordx4 v[212:213], off
	v_lshl_add_u64 v[212:213], s[4:5], 0, v[138:139]
	s_add_i32 m0, s44, 0xe000
	s_nop 0
	global_load_lds_dwordx4 v[212:213], off
	s_cmp_lg_u32 s8, 2
	s_cbranch_scc1 .Lw8__1495_0
	s_cmp_eq_u32 s49, 1
	s_cbranch_scc1 .Lw8__1495_0
	s_waitcnt vmcnt(16)
	s_branch .Lwj__1495_0

; #define PG8_STAGE(bufoff, gbase, voff) do { _Pragma("unroll") for (int _i = 0; _i < 2; ++_i) \
;         __builtin_amdgcn_global_load_lds((const unsigned*)((const char*)(gbase) + (voff)[_i]), (PG8_LAS unsigned*)(lds + (bufoff) + ldsw + _i * 8192), 16, 0, 0); } while (0)
; #define PG8_LDA(dst, b, h) do { _Pragma("unroll") for (int m = 0; m < 4; ++m) _Pragma("unroll") for (int k = 0; k < 2; ++k) dst[m][k] = *(const PG8_LAS bf16x8*)(lds + PG8_SA(b, h) + aoff + m * 2048 + k * 1024); } while (0)
; #define PG8_MMA(ai, bj, At, Bt) do { __builtin_amdgcn_s_setprio(1); _Pragma("unroll") for (int m = 0; m < 4; ++m) _Pragma("unroll") for (int n = 0; n < 2; ++n) _Pragma("unroll") for (int k = 0; k < 2; ++k) \
;         acc[ai][bj][m][n] = __builtin_amdgcn_mfma_f32_16x16x32_bf16(Bt[n][k], At[m][k], acc[ai][bj][m][n], 0, 0, 0); __builtin_amdgcn_s_setprio(0); } while (0)
; #define PG8_WAIT_V(n) asm volatile("s_waitcnt vmcnt(" #n ")" ::: "memory")
; #define PG8_WAIT_L(n) asm volatile("s_waitcnt lgkmcnt(" #n ")" ::: "memory")
; #define PG8_BAR __builtin_amdgcn_s_barrier()
; #define PG8_SCHED __builtin_amdgcn_sched_barrier(0)
; template <class Epi, class Sched, bool ALIGN_EPI = false, bool SP2 = false>
; __device__ __forceinline__ void gemm_phase(PG8_LAS unsigned char* lds, const Gemm g, const Sched& S, const Epi& E, const int wid) {
;     ...
;             PG8_WAIT_V(8); PG8_WAIT_L(0); PG8_BAR; PG8_MMA(0, 0, At, B0); PG8_MMA(0, 1, At, B1); PG8_BAR; PG8_SCHED;
;             PG8_LDA(At, 0, 1); PG8_STAGE(PG8_SB(0, 0), b2, voffB); PG8_STAGE(PG8_SB(0, 1), b2 + hstep, voffB); PG8_STAGE(PG8_SA(0, 0), a2, voffA);
;             PG8_WAIT_V(8); PG8_WAIT_L(0); PG8_BAR; PG8_MMA(1, 0, At, B0); PG8_MMA(1, 1, At, B1); PG8_BAR; PG8_SCHED;
.Lwj__1495_0:
	s_waitcnt lgkmcnt(0)
	s_barrier
	s_setprio 1
	s_waitcnt lgkmcnt(0)
	v_mfma_f32_16x16x32_bf16 v[120:123], v[142:145], v[180:183], v[120:123]
	v_mfma_f32_16x16x32_bf16 v[112:115], v[156:159], v[180:183], v[112:115]
	v_mfma_f32_16x16x32_bf16 v[104:107], v[142:145], v[188:191], v[104:107]
	v_mfma_f32_16x16x32_bf16 v[96:99], v[156:159], v[188:191], v[96:99]
	v_mfma_f32_16x16x32_bf16 v[88:91], v[142:145], v[196:199], v[88:91]
	v_mfma_f32_16x16x32_bf16 v[80:83], v[156:159], v[196:199], v[80:83]
	v_mfma_f32_16x16x32_bf16 v[72:75], v[142:145], v[204:207], v[72:75]
	v_mfma_f32_16x16x32_bf16 v[64:67], v[156:159], v[204:207], v[64:67]
	v_mfma_f32_16x16x32_bf16 v[120:123], v[152:155], v[184:187], v[120:123]
	v_mfma_f32_16x16x32_bf16 v[112:115], v[160:163], v[184:187], v[112:115]
	v_mfma_f32_16x16x32_bf16 v[104:107], v[152:155], v[192:195], v[104:107]
	v_mfma_f32_16x16x32_bf16 v[96:99], v[160:163], v[192:195], v[96:99]
	v_mfma_f32_16x16x32_bf16 v[88:91], v[152:155], v[200:203], v[88:91]
	v_mfma_f32_16x16x32_bf16 v[80:83], v[160:163], v[200:203], v[80:83]
	v_mfma_f32_16x16x32_bf16 v[72:75], v[152:155], v[208:211], v[72:75]
	v_mfma_f32_16x16x32_bf16 v[64:67], v[160:163], v[208:211], v[64:67]
	s_setprio 0
	s_setprio 1
	v_mfma_f32_16x16x32_bf16 v[124:127], v[164:167], v[180:183], v[124:127]
	v_mfma_f32_16x16x32_bf16 v[116:119], v[172:175], v[180:183], v[116:119]
	v_mfma_f32_16x16x32_bf16 v[108:111], v[164:167], v[188:191], v[108:111]
	v_mfma_f32_16x16x32_bf16 v[100:103], v[172:175], v[188:191], v[100:103]
	v_mfma_f32_16x16x32_bf16 v[92:95], v[164:167], v[196:199], v[92:95]
	v_mfma_f32_16x16x32_bf16 v[84:87], v[172:175], v[196:199], v[84:87]
	v_mfma_f32_16x16x32_bf16 v[76:79], v[164:167], v[204:207], v[76:79]
	v_mfma_f32_16x16x32_bf16 v[68:71], v[172:175], v[204:207], v[68:71]
	v_mfma_f32_16x16x32_bf16 v[124:127], v[168:171], v[184:187], v[124:127]
	v_mfma_f32_16x16x32_bf16 v[116:119], v[176:179], v[184:187], v[116:119]
	v_mfma_f32_16x16x32_bf16 v[108:111], v[168:171], v[192:195], v[108:111]
	v_mfma_f32_16x16x32_bf16 v[100:103], v[176:179], v[192:195], v[100:103]
	v_mfma_f32_16x16x32_bf16 v[92:95], v[168:171], v[200:203], v[92:95]
	v_mfma_f32_16x16x32_bf16 v[84:87], v[176:179], v[200:203], v[84:87]
	v_mfma_f32_16x16x32_bf16 v[76:79], v[168:171], v[208:211], v[76:79]
	v_mfma_f32_16x16x32_bf16 v[68:71], v[176:179], v[208:211], v[68:71]
	s_setprio 0
	s_barrier
	s_add_i32 s9, s57, s36
	v_lshl_add_u64 v[212:213], s[64:65], 0, v[132:133]
	s_mov_b32 m0, s9
	ds_read_b128 v[180:183], v151 offset:16384
	ds_read_b128 v[184:187], v151 offset:17408
	ds_read_b128 v[188:191], v151 offset:18432
	ds_read_b128 v[192:195], v151 offset:19456
	ds_read_b128 v[196:199], v151 offset:20480
	ds_read_b128 v[200:203], v151 offset:21504
	ds_read_b128 v[204:207], v151 offset:22528
	ds_read_b128 v[208:211], v151 offset:23552
	global_load_lds_dwordx4 v[212:213], off
	s_add_i32 m0, s9, 0x2000
	v_lshl_add_u64 v[214:215], s[64:65], 0, v[128:129]
	s_add_u32 s64, s64, s12
	s_addc_u32 s65, s65, s13
	s_add_i32 s9, s58, s36
	global_load_lds_dwordx4 v[214:215], off
	v_lshl_add_u64 v[216:217], s[64:65], 0, v[132:133]
	s_mov_b32 m0, s9
	v_lshl_add_u64 v[218:219], s[64:65], 0, v[128:129]
	global_load_lds_dwordx4 v[216:217], off
	s_add_i32 m0, s9, 0x2000
	v_lshl_add_u64 v[220:221], s[6:7], 0, v[134:135]
	global_load_lds_dwordx4 v[218:219], off
	s_mov_b32 m0, s44
	v_lshl_add_u64 v[222:223], s[6:7], 0, v[130:131]
	global_load_lds_dwordx4 v[220:221], off
	s_mov_b32 m0, s45
	s_nop 0
	global_load_lds_dwordx4 v[222:223], off
	s_cmp_lg_u32 s8, 2
	s_cbranch_scc1 .Lw8__1495_1
	s_cmp_eq_u32 s49, 1
	s_cbranch_scc1 .Lw8__1495_1
	s_waitcnt vmcnt(16)
	s_branch .Lwj__1495_1

; #define PG8_STAGE(bufoff, gbase, voff) do { _Pragma("unroll") for (int _i = 0; _i < 2; ++_i) \
;         __builtin_amdgcn_global_load_lds((const unsigned*)((const char*)(gbase) + (voff)[_i]), (PG8_LAS unsigned*)(lds + (bufoff) + ldsw + _i * 8192), 16, 0, 0); } while (0)
; #define PG8_LDA(dst, b, h) do { _Pragma("unroll") for (int m = 0; m < 4; ++m) _Pragma("unroll") for (int k = 0; k < 2; ++k) dst[m][k] = *(const PG8_LAS bf16x8*)(lds + PG8_SA(b, h) + aoff + m * 2048 + k * 1024); } while (0)
; #define PG8_LDB(dst, b, h) do { _Pragma("unroll") for (int n = 0; n < 2; ++n) _Pragma("unroll") for (int k = 0; k < 2; ++k) dst[n][k] = *(const PG8_LAS bf16x8*)(lds + PG8_SB(b, h) + boff + n * 2048 + k * 1024); } while (0)
; #define PG8_MMA(ai, bj, At, Bt) do { __builtin_amdgcn_s_setprio(1); _Pragma("unroll") for (int m = 0; m < 4; ++m) _Pragma("unroll") for (int n = 0; n < 2; ++n) _Pragma("unroll") for (int k = 0; k < 2; ++k) \
;         acc[ai][bj][m][n] = __builtin_amdgcn_mfma_f32_16x16x32_bf16(Bt[n][k], At[m][k], acc[ai][bj][m][n], 0, 0, 0); __builtin_amdgcn_s_setprio(0); } while (0)
; #define PG8_WAIT_V(n) asm volatile("s_waitcnt vmcnt(" #n ")" ::: "memory")
; #define PG8_WAIT_L(n) asm volatile("s_waitcnt lgkmcnt(" #n ")" ::: "memory")
; #define PG8_BAR __builtin_amdgcn_s_barrier()
; #define PG8_SCHED __builtin_amdgcn_sched_barrier(0)
; template <class Epi, class Sched, bool ALIGN_EPI = false, bool SP2 = false>
; __device__ __forceinline__ void gemm_phase(PG8_LAS unsigned char* lds, const Gemm g, const Sched& S, const Epi& E, const int wid) {
;     ...
;             PG8_WAIT_V(8); PG8_WAIT_L(0); PG8_BAR; PG8_MMA(1, 0, At, B0); PG8_MMA(1, 1, At, B1); PG8_BAR; PG8_SCHED;
;             PG8_LDB(B0, 1, 0); PG8_LDB(B1, 1, 1); PG8_SCHED; PG8_LDA(At, 1, 0); PG8_STAGE(PG8_SA(0, 1), a2 + hstep, voffA);
;             PG8_WAIT_V(8); PG8_WAIT_L(0); PG8_BAR; PG8_MMA(0, 0, At, B0); PG8_MMA(0, 1, At, B1); PG8_BAR; PG8_SCHED;
.Lwj__1495_1:
	s_waitcnt lgkmcnt(0)
	s_barrier
	s_setprio 1
	s_waitcnt lgkmcnt(0)
	v_mfma_f32_16x16x32_bf16 v[56:59], v[142:145], v[180:183], v[56:59]
	v_mfma_f32_16x16x32_bf16 v[48:51], v[156:159], v[180:183], v[48:51]
	v_mfma_f32_16x16x32_bf16 v[40:43], v[142:145], v[188:191], v[40:43]
	v_mfma_f32_16x16x32_bf16 v[32:35], v[156:159], v[188:191], v[32:35]
	v_mfma_f32_16x16x32_bf16 v[24:27], v[142:145], v[196:199], v[24:27]
	v_mfma_f32_16x16x32_bf16 v[16:19], v[156:159], v[196:199], v[16:19]
	v_mfma_f32_16x16x32_bf16 v[8:11], v[142:145], v[204:207], v[8:11]
	v_mfma_f32_16x16x32_bf16 v[4:7], v[156:159], v[204:207], v[4:7]
	v_mfma_f32_16x16x32_bf16 v[56:59], v[152:155], v[184:187], v[56:59]
	v_mfma_f32_16x16x32_bf16 v[48:51], v[160:163], v[184:187], v[48:51]
	v_mfma_f32_16x16x32_bf16 v[40:43], v[152:155], v[192:195], v[40:43]
	v_mfma_f32_16x16x32_bf16 v[32:35], v[160:163], v[192:195], v[32:35]
	v_mfma_f32_16x16x32_bf16 v[24:27], v[152:155], v[200:203], v[24:27]
	v_mfma_f32_16x16x32_bf16 v[16:19], v[160:163], v[200:203], v[16:19]
	v_mfma_f32_16x16x32_bf16 v[8:11], v[152:155], v[208:211], v[8:11]
	v_mfma_f32_16x16x32_bf16 v[4:7], v[160:163], v[208:211], v[4:7]
	s_setprio 0
	s_setprio 1
	v_mfma_f32_16x16x32_bf16 v[60:63], v[164:167], v[180:183], v[60:63]
	v_mfma_f32_16x16x32_bf16 v[52:55], v[172:175], v[180:183], v[52:55]
	v_mfma_f32_16x16x32_bf16 v[44:47], v[164:167], v[188:191], v[44:47]
	v_mfma_f32_16x16x32_bf16 v[36:39], v[172:175], v[188:191], v[36:39]
	v_mfma_f32_16x16x32_bf16 v[28:31], v[164:167], v[196:199], v[28:31]
	v_mfma_f32_16x16x32_bf16 v[20:23], v[172:175], v[196:199], v[20:23]
	v_mfma_f32_16x16x32_bf16 v[12:15], v[164:167], v[204:207], v[12:15]
	v_mfma_f32_16x16x32_bf16 v[0:3], v[172:175], v[204:207], v[0:3]
	v_mfma_f32_16x16x32_bf16 v[60:63], v[168:171], v[184:187], v[60:63]
	v_mfma_f32_16x16x32_bf16 v[52:55], v[176:179], v[184:187], v[52:55]
	v_mfma_f32_16x16x32_bf16 v[44:47], v[168:171], v[192:195], v[44:47]
	v_mfma_f32_16x16x32_bf16 v[36:39], v[176:179], v[192:195], v[36:39]
	v_mfma_f32_16x16x32_bf16 v[28:31], v[168:171], v[200:203], v[28:31]
	v_mfma_f32_16x16x32_bf16 v[20:23], v[176:179], v[200:203], v[20:23]
	v_mfma_f32_16x16x32_bf16 v[12:15], v[168:171], v[208:211], v[12:15]
	v_mfma_f32_16x16x32_bf16 v[0:3], v[176:179], v[208:211], v[0:3]
	s_setprio 0
	s_barrier
	s_add_i32 s9, 0, 0x18000
	s_add_i32 s33, 0, 0x1c000
	v_add_u32_e32 v160, s9, v148
	v_add_u32_e32 v176, s33, v148
	ds_read_b128 v[142:145], v160
	ds_read_b128 v[152:155], v160 offset:1024
	ds_read_b128 v[156:159], v160 offset:2048
	ds_read_b128 v[160:163], v160 offset:3072
	ds_read_b128 v[164:167], v176
	ds_read_b128 v[168:171], v176 offset:1024
	ds_read_b128 v[172:175], v176 offset:2048
	ds_read_b128 v[176:179], v176 offset:3072
	s_add_u32 s6, s6, s12
	s_addc_u32 s7, s7, s13
	s_mov_b32 m0, s46
	v_lshl_add_u64 v[224:225], s[6:7], 0, v[134:135]
	ds_read_b128 v[180:183], v151 offset:32768
	ds_read_b128 v[184:187], v151 offset:33792
	ds_read_b128 v[188:191], v151 offset:34816
	ds_read_b128 v[192:195], v151 offset:35840
	ds_read_b128 v[196:199], v151 offset:36864
	ds_read_b128 v[200:203], v151 offset:37888
	ds_read_b128 v[204:207], v151 offset:38912
	ds_read_b128 v[208:211], v151 offset:39936
	global_load_lds_dwordx4 v[224:225], off
	v_lshl_add_u64 v[224:225], s[6:7], 0, v[130:131]
	s_mov_b32 m0, s47
	s_nop 0
	global_load_lds_dwordx4 v[224:225], off
	s_waitcnt vmcnt(8)
	s_waitcnt lgkmcnt(0)
	s_barrier
	s_setprio 1
	s_waitcnt lgkmcnt(0)
	v_mfma_f32_16x16x32_bf16 v[120:123], v[142:145], v[180:183], v[120:123]
	v_mfma_f32_16x16x32_bf16 v[112:115], v[156:159], v[180:183], v[112:115]
	v_mfma_f32_16x16x32_bf16 v[104:107], v[142:145], v[188:191], v[104:107]
	v_mfma_f32_16x16x32_bf16 v[96:99], v[156:159], v[188:191], v[96:99]
	v_mfma_f32_16x16x32_bf16 v[88:91], v[142:145], v[196:199], v[88:91]
	v_mfma_f32_16x16x32_bf16 v[80:83], v[156:159], v[196:199], v[80:83]
	v_mfma_f32_16x16x32_bf16 v[72:75], v[142:145], v[204:207], v[72:75]
	v_mfma_f32_16x16x32_bf16 v[64:67], v[156:159], v[204:207], v[64:67]
	v_mfma_f32_16x16x32_bf16 v[120:123], v[152:155], v[184:187], v[120:123]
	v_mfma_f32_16x16x32_bf16 v[112:115], v[160:163], v[184:187], v[112:115]
	v_mfma_f32_16x16x32_bf16 v[104:107], v[152:155], v[192:195], v[104:107]
	v_mfma_f32_16x16x32_bf16 v[96:99], v[160:163], v[192:195], v[96:99]
	v_mfma_f32_16x16x32_bf16 v[88:91], v[152:155], v[200:203], v[88:91]
	v_mfma_f32_16x16x32_bf16 v[80:83], v[160:163], v[200:203], v[80:83]
	v_mfma_f32_16x16x32_bf16 v[72:75], v[152:155], v[208:211], v[72:75]
	v_mfma_f32_16x16x32_bf16 v[64:67], v[160:163], v[208:211], v[64:67]
	s_setprio 0
	s_setprio 1
	v_mfma_f32_16x16x32_bf16 v[124:127], v[164:167], v[180:183], v[124:127]
	v_mfma_f32_16x16x32_bf16 v[116:119], v[172:175], v[180:183], v[116:119]
	v_mfma_f32_16x16x32_bf16 v[108:111], v[164:167], v[188:191], v[108:111]
	v_mfma_f32_16x16x32_bf16 v[100:103], v[172:175], v[188:191], v[100:103]
	v_mfma_f32_16x16x32_bf16 v[92:95], v[164:167], v[196:199], v[92:95]
	v_mfma_f32_16x16x32_bf16 v[84:87], v[172:175], v[196:199], v[84:87]
	v_mfma_f32_16x16x32_bf16 v[76:79], v[164:167], v[204:207], v[76:79]
	v_mfma_f32_16x16x32_bf16 v[68:71], v[172:175], v[204:207], v[68:71]
	v_mfma_f32_16x16x32_bf16 v[124:127], v[168:171], v[184:187], v[124:127]
	v_mfma_f32_16x16x32_bf16 v[116:119], v[176:179], v[184:187], v[116:119]
	v_mfma_f32_16x16x32_bf16 v[108:111], v[168:171], v[192:195], v[108:111]
	v_mfma_f32_16x16x32_bf16 v[100:103], v[176:179], v[192:195], v[100:103]
	v_mfma_f32_16x16x32_bf16 v[92:95], v[168:171], v[200:203], v[92:95]
	v_mfma_f32_16x16x32_bf16 v[84:87], v[176:179], v[200:203], v[84:87]
	v_mfma_f32_16x16x32_bf16 v[76:79], v[168:171], v[208:211], v[76:79]
	v_mfma_f32_16x16x32_bf16 v[68:71], v[176:179], v[208:211], v[68:71]
	s_setprio 0
	s_barrier
; #define PG8_STAGE(bufoff, gbase, voff) do { _Pragma("unroll") for (int _i = 0; _i < 2; ++_i) \
;         __builtin_amdgcn_global_load_lds((const unsigned*)((const char*)(gbase) + (voff)[_i]), (PG8_LAS unsigned*)(lds + (bufoff) + ldsw + _i * 8192), 16, 0, 0); } while (0)
; #define PG8_LDA(dst, b, h) do { _Pragma("unroll") for (int m = 0; m < 4; ++m) _Pragma("unroll") for (int k = 0; k < 2; ++k) dst[m][k] = *(const PG8_LAS bf16x8*)(lds + PG8_SA(b, h) + aoff + m * 2048 + k * 1024); } while (0)
; #define PG8_MMA(ai, bj, At, Bt) do { __builtin_amdgcn_s_setprio(1); _Pragma("unroll") for (int m = 0; m < 4; ++m) _Pragma("unroll") for (int n = 0; n < 2; ++n) _Pragma("unroll") for (int k = 0; k < 2; ++k) \
;         acc[ai][bj][m][n] = __builtin_amdgcn_mfma_f32_16x16x32_bf16(Bt[n][k], At[m][k], acc[ai][bj][m][n], 0, 0, 0); __builtin_amdgcn_s_setprio(0); } while (0)
; #define PG8_WAIT_V(n) asm volatile("s_waitcnt vmcnt(" #n ")" ::: "memory")
; #define PG8_WAIT_L(n) asm volatile("s_waitcnt lgkmcnt(" #n ")" ::: "memory")
; #define PG8_BAR __builtin_amdgcn_s_barrier()
; #define PG8_SCHED __builtin_amdgcn_sched_barrier(0)
; template <class Epi, class Sched, bool ALIGN_EPI = false, bool SP2 = false>
; __device__ __forceinline__ void gemm_phase(PG8_LAS unsigned char* lds, const Gemm g, const Sched& S, const Epi& E, const int wid) {
;     ...
;         for (int t = 0; t < nt; t += 2) {
;             const bool last = (t == nt - 2);
;             const char* a1 = cA + (size_t)(t + 1) * kstep;
;             const char* a2 = last ? nA : cA + (size_t)(t + 2) * kstep; const char* b2 = last ? nB : cB + (size_t)(t + 2) * kstep;
;     ...
;             PG8_LDA(At, 1, 1); PG8_STAGE(PG8_SB(1, 0), b3, voffB); PG8_STAGE(PG8_SB(1, 1), b3 + hstep, voffB); PG8_STAGE(PG8_SA(1, 0), a3, voffA);
;             PG8_WAIT_V(8); PG8_WAIT_L(0); PG8_BAR; PG8_MMA(1, 0, At, B0); PG8_MMA(1, 1, At, B1); PG8_BAR; PG8_SCHED;
	s_add_i32 s6, s9, s36
	v_lshl_add_u64 v[212:213], v[212:213], 0, s[20:21]
	s_mov_b32 m0, s6
	ds_read_b128 v[180:183], v151 offset:49152
	ds_read_b128 v[184:187], v151 offset:50176
	ds_read_b128 v[188:191], v151 offset:51200
	ds_read_b128 v[192:195], v151 offset:52224
	ds_read_b128 v[196:199], v151 offset:53248
	ds_read_b128 v[200:203], v151 offset:54272
	ds_read_b128 v[204:207], v151 offset:55296
	ds_read_b128 v[208:211], v151 offset:56320
	global_load_lds_dwordx4 v[212:213], off
	v_lshl_add_u64 v[212:213], v[214:215], 0, s[20:21]
	s_add_i32 m0, s6, 0x2000
	s_add_i32 s6, s33, s36
	global_load_lds_dwordx4 v[212:213], off
	v_lshl_add_u64 v[212:213], v[216:217], 0, s[20:21]
	s_mov_b32 m0, s6
	s_nop 0
	global_load_lds_dwordx4 v[212:213], off
	v_lshl_add_u64 v[212:213], v[218:219], 0, s[20:21]
	s_add_i32 m0, s6, 0x2000
	s_nop 0
	global_load_lds_dwordx4 v[212:213], off
	v_lshl_add_u64 v[212:213], v[220:221], 0, s[20:21]
	s_mov_b32 m0, s50
	s_nop 0
	global_load_lds_dwordx4 v[212:213], off
	v_lshl_add_u64 v[212:213], v[222:223], 0, s[20:21]
	s_mov_b32 m0, s51
	s_nop 0
	global_load_lds_dwordx4 v[212:213], off
	s_waitcnt vmcnt(8)
	s_waitcnt lgkmcnt(0)
	s_barrier
	s_setprio 1
	s_waitcnt lgkmcnt(0)
	v_mfma_f32_16x16x32_bf16 v[56:59], v[142:145], v[180:183], v[56:59]
	v_mfma_f32_16x16x32_bf16 v[48:51], v[156:159], v[180:183], v[48:51]
	v_mfma_f32_16x16x32_bf16 v[40:43], v[142:145], v[188:191], v[40:43]
	v_mfma_f32_16x16x32_bf16 v[32:35], v[156:159], v[188:191], v[32:35]
	v_mfma_f32_16x16x32_bf16 v[24:27], v[142:145], v[196:199], v[24:27]
	v_mfma_f32_16x16x32_bf16 v[16:19], v[156:159], v[196:199], v[16:19]
	v_mfma_f32_16x16x32_bf16 v[8:11], v[142:145], v[204:207], v[8:11]
	v_mfma_f32_16x16x32_bf16 v[4:7], v[156:159], v[204:207], v[4:7]
	v_mfma_f32_16x16x32_bf16 v[56:59], v[152:155], v[184:187], v[56:59]
	v_mfma_f32_16x16x32_bf16 v[48:51], v[160:163], v[184:187], v[48:51]
	v_mfma_f32_16x16x32_bf16 v[40:43], v[152:155], v[192:195], v[40:43]
	v_mfma_f32_16x16x32_bf16 v[32:35], v[160:163], v[192:195], v[32:35]
	v_mfma_f32_16x16x32_bf16 v[24:27], v[152:155], v[200:203], v[24:27]
	v_mfma_f32_16x16x32_bf16 v[16:19], v[160:163], v[200:203], v[16:19]
	v_mfma_f32_16x16x32_bf16 v[8:11], v[152:155], v[208:211], v[8:11]
	v_mfma_f32_16x16x32_bf16 v[4:7], v[160:163], v[208:211], v[4:7]
	s_setprio 0
	s_setprio 1
	v_mfma_f32_16x16x32_bf16 v[60:63], v[164:167], v[180:183], v[60:63]
	v_mfma_f32_16x16x32_bf16 v[52:55], v[172:175], v[180:183], v[52:55]
	v_mfma_f32_16x16x32_bf16 v[44:47], v[164:167], v[188:191], v[44:47]
	v_mfma_f32_16x16x32_bf16 v[36:39], v[172:175], v[188:191], v[36:39]
	v_mfma_f32_16x16x32_bf16 v[28:31], v[164:167], v[196:199], v[28:31]
	v_mfma_f32_16x16x32_bf16 v[20:23], v[172:175], v[196:199], v[20:23]
	v_mfma_f32_16x16x32_bf16 v[12:15], v[164:167], v[204:207], v[12:15]
	v_mfma_f32_16x16x32_bf16 v[0:3], v[172:175], v[204:207], v[0:3]
	v_mfma_f32_16x16x32_bf16 v[60:63], v[168:171], v[184:187], v[60:63]
	v_mfma_f32_16x16x32_bf16 v[52:55], v[176:179], v[184:187], v[52:55]
	v_mfma_f32_16x16x32_bf16 v[44:47], v[168:171], v[192:195], v[44:47]
	v_mfma_f32_16x16x32_bf16 v[36:39], v[176:179], v[192:195], v[36:39]
	v_mfma_f32_16x16x32_bf16 v[28:31], v[168:171], v[200:203], v[28:31]
	v_mfma_f32_16x16x32_bf16 v[20:23], v[176:179], v[200:203], v[20:23]
	v_mfma_f32_16x16x32_bf16 v[12:15], v[168:171], v[208:211], v[12:15]
	v_mfma_f32_16x16x32_bf16 v[0:3], v[176:179], v[208:211], v[0:3]
	s_setprio 0
	s_barrier
	s_add_u32 s4, s4, 0x100
	s_addc_u32 s5, s5, 0
	s_add_u32 s0, s0, 0x100
	s_addc_u32 s1, s1, 0
	s_cmp_ge_i32 s8, s52
	s_mov_b32 s6, s8
	s_cbranch_scc0 .LBB0_1495

; #define PG8_STAGE(bufoff, gbase, voff) do { _Pragma("unroll") for (int _i = 0; _i < 2; ++_i) \
;         __builtin_amdgcn_global_load_lds((const unsigned*)((const char*)(gbase) + (voff)[_i]), (PG8_LAS unsigned*)(lds + (bufoff) + ldsw + _i * 8192), 16, 0, 0); } while (0)
; #define PG8_LDA(dst, b, h) do { _Pragma("unroll") for (int m = 0; m < 4; ++m) _Pragma("unroll") for (int k = 0; k < 2; ++k) dst[m][k] = *(const PG8_LAS bf16x8*)(lds + PG8_SA(b, h) + aoff + m * 2048 + k * 1024); } while (0)
; #define PG8_LDB(dst, b, h) do { _Pragma("unroll") for (int n = 0; n < 2; ++n) _Pragma("unroll") for (int k = 0; k < 2; ++k) dst[n][k] = *(const PG8_LAS bf16x8*)(lds + PG8_SB(b, h) + boff + n * 2048 + k * 1024); } while (0)
; #define PG8_MMA(ai, bj, At, Bt) do { __builtin_amdgcn_s_setprio(1); _Pragma("unroll") for (int m = 0; m < 4; ++m) _Pragma("unroll") for (int n = 0; n < 2; ++n) _Pragma("unroll") for (int k = 0; k < 2; ++k) \
;         acc[ai][bj][m][n] = __builtin_amdgcn_mfma_f32_16x16x32_bf16(Bt[n][k], At[m][k], acc[ai][bj][m][n], 0, 0, 0); __builtin_amdgcn_s_setprio(0); } while (0)
; #define PG8_WAIT_V(n) asm volatile("s_waitcnt vmcnt(" #n ")" ::: "memory")
; #define PG8_WAIT_L(n) asm volatile("s_waitcnt lgkmcnt(" #n ")" ::: "memory")
; #define PG8_BAR __builtin_amdgcn_s_barrier()
; #define PG8_SCHED __builtin_amdgcn_sched_barrier(0)
; template <class Epi, class Sched, bool ALIGN_EPI = false, bool SP2 = false>
; __device__ __forceinline__ void gemm_phase(PG8_LAS unsigned char* lds, const Gemm g, const Sched& S, const Epi& E, const int wid) {
;     ...
;         for (int t = 0; t < nt; t += 2) {
;             const bool last = (t == nt - 2);
;             const char* a1 = cA + (size_t)(t + 1) * kstep;
;             const char* a2 = last ? nA : cA + (size_t)(t + 2) * kstep; const char* b2 = last ? nB : cB + (size_t)(t + 2) * kstep;
;             const char* a3 = a2 + kstep; const char* b3 = b2 + kstep;
;             if (last && has_next) S.a_ready(nxt);
;             if constexpr (SP2) {
;             PG8_LDB(B0, 0, 0); PG8_LDB(B1, 0, 1); PG8_SCHED; PG8_LDA(At, 0, 0); PG8_STAGE(PG8_SA(1, 1), a1 + hstep, voffA);
;             PG8_WAIT_V(8); PG8_WAIT_L(0); PG8_BAR; PG8_MMA(0, 0, At, B0); PG8_MMA(0, 1, At, B1); PG8_BAR; PG8_SCHED;
.LBB0_1574:
	ds_read_b128 v[146:149], v143
	ds_read_b128 v[150:153], v143 offset:1024
	ds_read_b128 v[154:157], v143 offset:2048
	ds_read_b128 v[158:161], v143 offset:3072
	ds_read_b128 v[162:165], v144
	ds_read_b128 v[166:169], v144 offset:1024
	ds_read_b128 v[170:173], v144 offset:2048
	ds_read_b128 v[174:177], v144 offset:3072
	s_add_i32 s75, s42, 2
	s_add_u32 s33, s40, 0x80
	s_addc_u32 s43, s41, 0
	s_cmp_eq_u32 s65, s42
	s_cselect_b32 s42, s2, s33
	s_cselect_b32 s43, s3, s43
	s_cselect_b32 s77, s39, s74
	s_cselect_b32 s76, s38, s73
	v_lshl_add_u64 v[138:139], s[40:41], 0, v[132:133]
	s_add_i32 m0, s55, 0xc000
	ds_read_b128 v[178:181], v145
	ds_read_b128 v[182:185], v145 offset:1024
	ds_read_b128 v[186:189], v145 offset:2048
	ds_read_b128 v[190:193], v145 offset:3072
	ds_read_b128 v[194:197], v145 offset:4096
	ds_read_b128 v[198:201], v145 offset:5120
	ds_read_b128 v[202:205], v145 offset:6144
	ds_read_b128 v[206:209], v145 offset:7168
	global_load_lds_dwordx4 v[138:139], off
	v_lshl_add_u64 v[138:139], s[40:41], 0, v[134:135]
	s_add_i32 m0, s55, 0xe000
	s_nop 0
	global_load_lds_dwordx4 v[138:139], off
	s_cmp_lg_u32 s75, 2
	s_cbranch_scc1 .Lw8__1574_0
	s_cmp_eq_u32 s59, 1
	s_cbranch_scc1 .Lw8__1574_0
	s_waitcnt vmcnt(40)
	s_branch .Lwj__1574_0

; #define PG8_STAGE(bufoff, gbase, voff) do { _Pragma("unroll") for (int _i = 0; _i < 2; ++_i) \
;         __builtin_amdgcn_global_load_lds((const unsigned*)((const char*)(gbase) + (voff)[_i]), (PG8_LAS unsigned*)(lds + (bufoff) + ldsw + _i * 8192), 16, 0, 0); } while (0)
; #define PG8_LDA(dst, b, h) do { _Pragma("unroll") for (int m = 0; m < 4; ++m) _Pragma("unroll") for (int k = 0; k < 2; ++k) dst[m][k] = *(const PG8_LAS bf16x8*)(lds + PG8_SA(b, h) + aoff + m * 2048 + k * 1024); } while (0)
; #define PG8_MMA(ai, bj, At, Bt) do { __builtin_amdgcn_s_setprio(1); _Pragma("unroll") for (int m = 0; m < 4; ++m) _Pragma("unroll") for (int n = 0; n < 2; ++n) _Pragma("unroll") for (int k = 0; k < 2; ++k) \
;         acc[ai][bj][m][n] = __builtin_amdgcn_mfma_f32_16x16x32_bf16(Bt[n][k], At[m][k], acc[ai][bj][m][n], 0, 0, 0); __builtin_amdgcn_s_setprio(0); } while (0)
; #define PG8_WAIT_V(n) asm volatile("s_waitcnt vmcnt(" #n ")" ::: "memory")
; #define PG8_WAIT_L(n) asm volatile("s_waitcnt lgkmcnt(" #n ")" ::: "memory")
; #define PG8_BAR __builtin_amdgcn_s_barrier()
; #define PG8_SCHED __builtin_amdgcn_sched_barrier(0)
; template <class Epi, class Sched, bool ALIGN_EPI = false, bool SP2 = false>
; __device__ __forceinline__ void gemm_phase(PG8_LAS unsigned char* lds, const Gemm g, const Sched& S, const Epi& E, const int wid) {
;     ...
;             PG8_WAIT_V(8); PG8_WAIT_L(0); PG8_BAR; PG8_MMA(0, 0, At, B0); PG8_MMA(0, 1, At, B1); PG8_BAR; PG8_SCHED;
;             PG8_LDA(At, 0, 1); PG8_STAGE(PG8_SB(0, 0), b2, voffB); PG8_STAGE(PG8_SB(0, 1), b2 + hstep, voffB); PG8_STAGE(PG8_SA(0, 0), a2, voffA);
;             PG8_WAIT_V(8); PG8_WAIT_L(0); PG8_BAR; PG8_MMA(1, 0, At, B0); PG8_MMA(1, 1, At, B1); PG8_BAR; PG8_SCHED;
.Lwj__1574_0:
	s_waitcnt lgkmcnt(0)
	s_barrier
	s_setprio 1
	s_waitcnt lgkmcnt(0)
	v_mfma_f32_16x16x32_bf16 v[124:127], v[146:149], v[178:181], v[124:127]
	v_mfma_f32_16x16x32_bf16 v[120:123], v[154:157], v[178:181], v[120:123]
	v_mfma_f32_16x16x32_bf16 v[108:111], v[146:149], v[186:189], v[108:111]
	v_mfma_f32_16x16x32_bf16 v[104:107], v[154:157], v[186:189], v[104:107]
	v_mfma_f32_16x16x32_bf16 v[92:95], v[146:149], v[194:197], v[92:95]
	v_mfma_f32_16x16x32_bf16 v[88:91], v[154:157], v[194:197], v[88:91]
	v_mfma_f32_16x16x32_bf16 v[76:79], v[146:149], v[202:205], v[76:79]
	v_mfma_f32_16x16x32_bf16 v[72:75], v[154:157], v[202:205], v[72:75]
	v_mfma_f32_16x16x32_bf16 v[124:127], v[150:153], v[182:185], v[124:127]
	v_mfma_f32_16x16x32_bf16 v[120:123], v[158:161], v[182:185], v[120:123]
	v_mfma_f32_16x16x32_bf16 v[108:111], v[150:153], v[190:193], v[108:111]
	v_mfma_f32_16x16x32_bf16 v[104:107], v[158:161], v[190:193], v[104:107]
	v_mfma_f32_16x16x32_bf16 v[92:95], v[150:153], v[198:201], v[92:95]
	v_mfma_f32_16x16x32_bf16 v[88:91], v[158:161], v[198:201], v[88:91]
	v_mfma_f32_16x16x32_bf16 v[76:79], v[150:153], v[206:209], v[76:79]
	v_mfma_f32_16x16x32_bf16 v[72:75], v[158:161], v[206:209], v[72:75]
	s_setprio 0
	s_setprio 1
	v_mfma_f32_16x16x32_bf16 v[116:119], v[162:165], v[178:181], v[116:119]
	v_mfma_f32_16x16x32_bf16 v[112:115], v[170:173], v[178:181], v[112:115]
	v_mfma_f32_16x16x32_bf16 v[100:103], v[162:165], v[186:189], v[100:103]
	v_mfma_f32_16x16x32_bf16 v[96:99], v[170:173], v[186:189], v[96:99]
	v_mfma_f32_16x16x32_bf16 v[84:87], v[162:165], v[194:197], v[84:87]
	v_mfma_f32_16x16x32_bf16 v[80:83], v[170:173], v[194:197], v[80:83]
	v_mfma_f32_16x16x32_bf16 v[68:71], v[162:165], v[202:205], v[68:71]
	v_mfma_f32_16x16x32_bf16 v[64:67], v[170:173], v[202:205], v[64:67]
	v_mfma_f32_16x16x32_bf16 v[116:119], v[166:169], v[182:185], v[116:119]
	v_mfma_f32_16x16x32_bf16 v[112:115], v[174:177], v[182:185], v[112:115]
	v_mfma_f32_16x16x32_bf16 v[100:103], v[166:169], v[190:193], v[100:103]
	v_mfma_f32_16x16x32_bf16 v[96:99], v[174:177], v[190:193], v[96:99]
	v_mfma_f32_16x16x32_bf16 v[84:87], v[166:169], v[198:201], v[84:87]
	v_mfma_f32_16x16x32_bf16 v[80:83], v[174:177], v[198:201], v[80:83]
	v_mfma_f32_16x16x32_bf16 v[68:71], v[166:169], v[206:209], v[68:71]
	v_mfma_f32_16x16x32_bf16 v[64:67], v[174:177], v[206:209], v[64:67]
	s_setprio 0
	s_barrier
	s_add_i32 s33, s67, s47
	v_lshl_add_u64 v[138:139], s[76:77], 0, v[130:131]
	s_mov_b32 m0, s33
	ds_read_b128 v[178:181], v145 offset:16384
	ds_read_b128 v[182:185], v145 offset:17408
	ds_read_b128 v[186:189], v145 offset:18432
	ds_read_b128 v[190:193], v145 offset:19456
	ds_read_b128 v[194:197], v145 offset:20480
	ds_read_b128 v[198:201], v145 offset:21504
	ds_read_b128 v[202:205], v145 offset:22528
	ds_read_b128 v[206:209], v145 offset:23552
	global_load_lds_dwordx4 v[138:139], off
	s_add_i32 m0, s33, 0x2000
	v_lshl_add_u64 v[210:211], s[76:77], 0, v[128:129]
	s_add_u32 s76, s76, s8
	s_addc_u32 s77, s77, s9
	s_add_i32 s33, s68, s47
	global_load_lds_dwordx4 v[210:211], off
	v_lshl_add_u64 v[212:213], s[76:77], 0, v[130:131]
	s_mov_b32 m0, s33
	v_lshl_add_u64 v[214:215], s[76:77], 0, v[128:129]
	global_load_lds_dwordx4 v[212:213], off
	s_add_i32 m0, s33, 0x2000
	v_lshl_add_u64 v[216:217], s[42:43], 0, v[130:131]
	global_load_lds_dwordx4 v[214:215], off
	s_mov_b32 m0, s55
	v_lshl_add_u64 v[218:219], s[42:43], 0, v[128:129]
	global_load_lds_dwordx4 v[216:217], off
	s_mov_b32 m0, s56
	s_nop 0
	global_load_lds_dwordx4 v[218:219], off
	s_cmp_lg_u32 s75, 2
	s_cbranch_scc1 .Lw8__1574_1
	s_cmp_eq_u32 s59, 1
	s_cbranch_scc1 .Lw8__1574_1
	s_waitcnt vmcnt(40)
	s_branch .Lwj__1574_1

; #define PG8_STAGE(bufoff, gbase, voff) do { _Pragma("unroll") for (int _i = 0; _i < 2; ++_i) \
;         __builtin_amdgcn_global_load_lds((const unsigned*)((const char*)(gbase) + (voff)[_i]), (PG8_LAS unsigned*)(lds + (bufoff) + ldsw + _i * 8192), 16, 0, 0); } while (0)
; #define PG8_LDA(dst, b, h) do { _Pragma("unroll") for (int m = 0; m < 4; ++m) _Pragma("unroll") for (int k = 0; k < 2; ++k) dst[m][k] = *(const PG8_LAS bf16x8*)(lds + PG8_SA(b, h) + aoff + m * 2048 + k * 1024); } while (0)
; #define PG8_LDB(dst, b, h) do { _Pragma("unroll") for (int n = 0; n < 2; ++n) _Pragma("unroll") for (int k = 0; k < 2; ++k) dst[n][k] = *(const PG8_LAS bf16x8*)(lds + PG8_SB(b, h) + boff + n * 2048 + k * 1024); } while (0)
; #define PG8_MMA(ai, bj, At, Bt) do { __builtin_amdgcn_s_setprio(1); _Pragma("unroll") for (int m = 0; m < 4; ++m) _Pragma("unroll") for (int n = 0; n < 2; ++n) _Pragma("unroll") for (int k = 0; k < 2; ++k) \
;         acc[ai][bj][m][n] = __builtin_amdgcn_mfma_f32_16x16x32_bf16(Bt[n][k], At[m][k], acc[ai][bj][m][n], 0, 0, 0); __builtin_amdgcn_s_setprio(0); } while (0)
; #define PG8_WAIT_V(n) asm volatile("s_waitcnt vmcnt(" #n ")" ::: "memory")
; #define PG8_WAIT_L(n) asm volatile("s_waitcnt lgkmcnt(" #n ")" ::: "memory")
; #define PG8_BAR __builtin_amdgcn_s_barrier()
; #define PG8_SCHED __builtin_amdgcn_sched_barrier(0)
; template <class Epi, class Sched, bool ALIGN_EPI = false, bool SP2 = false>
; __device__ __forceinline__ void gemm_phase(PG8_LAS unsigned char* lds, const Gemm g, const Sched& S, const Epi& E, const int wid) {
;     ...
;             PG8_WAIT_V(8); PG8_WAIT_L(0); PG8_BAR; PG8_MMA(1, 0, At, B0); PG8_MMA(1, 1, At, B1); PG8_BAR; PG8_SCHED;
;             PG8_LDB(B0, 1, 0); PG8_LDB(B1, 1, 1); PG8_SCHED; PG8_LDA(At, 1, 0); PG8_STAGE(PG8_SA(0, 1), a2 + hstep, voffA);
;             PG8_WAIT_V(8); PG8_WAIT_L(0); PG8_BAR; PG8_MMA(0, 0, At, B0); PG8_MMA(0, 1, At, B1); PG8_BAR; PG8_SCHED;
.Lwj__1574_1:
	s_waitcnt lgkmcnt(0)
	s_barrier
	s_setprio 1
	s_waitcnt lgkmcnt(0)
	v_mfma_f32_16x16x32_bf16 v[60:63], v[146:149], v[178:181], v[60:63]
	v_mfma_f32_16x16x32_bf16 v[56:59], v[154:157], v[178:181], v[56:59]
	v_mfma_f32_16x16x32_bf16 v[44:47], v[146:149], v[186:189], v[44:47]
	v_mfma_f32_16x16x32_bf16 v[40:43], v[154:157], v[186:189], v[40:43]
	v_mfma_f32_16x16x32_bf16 v[28:31], v[146:149], v[194:197], v[28:31]
	v_mfma_f32_16x16x32_bf16 v[24:27], v[154:157], v[194:197], v[24:27]
	v_mfma_f32_16x16x32_bf16 v[12:15], v[146:149], v[202:205], v[12:15]
	v_mfma_f32_16x16x32_bf16 v[8:11], v[154:157], v[202:205], v[8:11]
	v_mfma_f32_16x16x32_bf16 v[60:63], v[150:153], v[182:185], v[60:63]
	v_mfma_f32_16x16x32_bf16 v[56:59], v[158:161], v[182:185], v[56:59]
	v_mfma_f32_16x16x32_bf16 v[44:47], v[150:153], v[190:193], v[44:47]
	v_mfma_f32_16x16x32_bf16 v[40:43], v[158:161], v[190:193], v[40:43]
	v_mfma_f32_16x16x32_bf16 v[28:31], v[150:153], v[198:201], v[28:31]
	v_mfma_f32_16x16x32_bf16 v[24:27], v[158:161], v[198:201], v[24:27]
	v_mfma_f32_16x16x32_bf16 v[12:15], v[150:153], v[206:209], v[12:15]
	v_mfma_f32_16x16x32_bf16 v[8:11], v[158:161], v[206:209], v[8:11]
	s_setprio 0
	s_setprio 1
	v_mfma_f32_16x16x32_bf16 v[52:55], v[162:165], v[178:181], v[52:55]
	v_mfma_f32_16x16x32_bf16 v[48:51], v[170:173], v[178:181], v[48:51]
	v_mfma_f32_16x16x32_bf16 v[36:39], v[162:165], v[186:189], v[36:39]
	v_mfma_f32_16x16x32_bf16 v[32:35], v[170:173], v[186:189], v[32:35]
	v_mfma_f32_16x16x32_bf16 v[20:23], v[162:165], v[194:197], v[20:23]
	v_mfma_f32_16x16x32_bf16 v[16:19], v[170:173], v[194:197], v[16:19]
	v_mfma_f32_16x16x32_bf16 v[4:7], v[162:165], v[202:205], v[4:7]
	v_mfma_f32_16x16x32_bf16 v[0:3], v[170:173], v[202:205], v[0:3]
	v_mfma_f32_16x16x32_bf16 v[52:55], v[166:169], v[182:185], v[52:55]
	v_mfma_f32_16x16x32_bf16 v[48:51], v[174:177], v[182:185], v[48:51]
	v_mfma_f32_16x16x32_bf16 v[36:39], v[166:169], v[190:193], v[36:39]
	v_mfma_f32_16x16x32_bf16 v[32:35], v[174:177], v[190:193], v[32:35]
	v_mfma_f32_16x16x32_bf16 v[20:23], v[166:169], v[198:201], v[20:23]
	v_mfma_f32_16x16x32_bf16 v[16:19], v[174:177], v[198:201], v[16:19]
	v_mfma_f32_16x16x32_bf16 v[4:7], v[166:169], v[206:209], v[4:7]
	v_mfma_f32_16x16x32_bf16 v[0:3], v[174:177], v[206:209], v[0:3]
	s_setprio 0
	s_barrier
	s_add_i32 s33, 0, 0x18000
	s_add_i32 s76, 0, 0x1c000
	v_add_u32_e32 v158, s33, v142
	v_add_u32_e32 v174, s76, v142
	ds_read_b128 v[146:149], v158
	ds_read_b128 v[150:153], v158 offset:1024
	ds_read_b128 v[154:157], v158 offset:2048
	ds_read_b128 v[158:161], v158 offset:3072
	ds_read_b128 v[162:165], v174
	ds_read_b128 v[166:169], v174 offset:1024
	ds_read_b128 v[170:173], v174 offset:2048
	ds_read_b128 v[174:177], v174 offset:3072
	s_add_u32 s42, s42, s8
	s_addc_u32 s43, s43, s9
	s_mov_b32 m0, s57
	v_lshl_add_u64 v[220:221], s[42:43], 0, v[130:131]
	ds_read_b128 v[178:181], v145 offset:32768
	ds_read_b128 v[182:185], v145 offset:33792
	ds_read_b128 v[186:189], v145 offset:34816
	ds_read_b128 v[190:193], v145 offset:35840
	ds_read_b128 v[194:197], v145 offset:36864
	ds_read_b128 v[198:201], v145 offset:37888
	ds_read_b128 v[202:205], v145 offset:38912
	ds_read_b128 v[206:209], v145 offset:39936
	global_load_lds_dwordx4 v[220:221], off
	v_lshl_add_u64 v[220:221], s[42:43], 0, v[128:129]
	s_mov_b32 m0, s58
	s_nop 0
	global_load_lds_dwordx4 v[220:221], off
	s_waitcnt vmcnt(8)
	s_waitcnt lgkmcnt(0)
	s_barrier
	s_setprio 1
	s_waitcnt lgkmcnt(0)
	v_mfma_f32_16x16x32_bf16 v[124:127], v[146:149], v[178:181], v[124:127]
	v_mfma_f32_16x16x32_bf16 v[120:123], v[154:157], v[178:181], v[120:123]
	v_mfma_f32_16x16x32_bf16 v[108:111], v[146:149], v[186:189], v[108:111]
	v_mfma_f32_16x16x32_bf16 v[104:107], v[154:157], v[186:189], v[104:107]
	v_mfma_f32_16x16x32_bf16 v[92:95], v[146:149], v[194:197], v[92:95]
	v_mfma_f32_16x16x32_bf16 v[88:91], v[154:157], v[194:197], v[88:91]
	v_mfma_f32_16x16x32_bf16 v[76:79], v[146:149], v[202:205], v[76:79]
	v_mfma_f32_16x16x32_bf16 v[72:75], v[154:157], v[202:205], v[72:75]
	v_mfma_f32_16x16x32_bf16 v[124:127], v[150:153], v[182:185], v[124:127]
	v_mfma_f32_16x16x32_bf16 v[120:123], v[158:161], v[182:185], v[120:123]
	v_mfma_f32_16x16x32_bf16 v[108:111], v[150:153], v[190:193], v[108:111]
	v_mfma_f32_16x16x32_bf16 v[104:107], v[158:161], v[190:193], v[104:107]
	v_mfma_f32_16x16x32_bf16 v[92:95], v[150:153], v[198:201], v[92:95]
	v_mfma_f32_16x16x32_bf16 v[88:91], v[158:161], v[198:201], v[88:91]
	v_mfma_f32_16x16x32_bf16 v[76:79], v[150:153], v[206:209], v[76:79]
	v_mfma_f32_16x16x32_bf16 v[72:75], v[158:161], v[206:209], v[72:75]
	s_setprio 0
	s_setprio 1
	v_mfma_f32_16x16x32_bf16 v[116:119], v[162:165], v[178:181], v[116:119]
	v_mfma_f32_16x16x32_bf16 v[112:115], v[170:173], v[178:181], v[112:115]
	v_mfma_f32_16x16x32_bf16 v[100:103], v[162:165], v[186:189], v[100:103]
	v_mfma_f32_16x16x32_bf16 v[96:99], v[170:173], v[186:189], v[96:99]
	v_mfma_f32_16x16x32_bf16 v[84:87], v[162:165], v[194:197], v[84:87]
	v_mfma_f32_16x16x32_bf16 v[80:83], v[170:173], v[194:197], v[80:83]
	v_mfma_f32_16x16x32_bf16 v[68:71], v[162:165], v[202:205], v[68:71]
	v_mfma_f32_16x16x32_bf16 v[64:67], v[170:173], v[202:205], v[64:67]
	v_mfma_f32_16x16x32_bf16 v[116:119], v[166:169], v[182:185], v[116:119]
	v_mfma_f32_16x16x32_bf16 v[112:115], v[174:177], v[182:185], v[112:115]
	v_mfma_f32_16x16x32_bf16 v[100:103], v[166:169], v[190:193], v[100:103]
	v_mfma_f32_16x16x32_bf16 v[96:99], v[174:177], v[190:193], v[96:99]
	v_mfma_f32_16x16x32_bf16 v[84:87], v[166:169], v[198:201], v[84:87]
	v_mfma_f32_16x16x32_bf16 v[80:83], v[174:177], v[198:201], v[80:83]
	v_mfma_f32_16x16x32_bf16 v[68:71], v[166:169], v[206:209], v[68:71]
	v_mfma_f32_16x16x32_bf16 v[64:67], v[174:177], v[206:209], v[64:67]
	s_setprio 0
	s_barrier
; #define PG8_STAGE(bufoff, gbase, voff) do { _Pragma("unroll") for (int _i = 0; _i < 2; ++_i) \
;         __builtin_amdgcn_global_load_lds((const unsigned*)((const char*)(gbase) + (voff)[_i]), (PG8_LAS unsigned*)(lds + (bufoff) + ldsw + _i * 8192), 16, 0, 0); } while (0)
; #define PG8_LDA(dst, b, h) do { _Pragma("unroll") for (int m = 0; m < 4; ++m) _Pragma("unroll") for (int k = 0; k < 2; ++k) dst[m][k] = *(const PG8_LAS bf16x8*)(lds + PG8_SA(b, h) + aoff + m * 2048 + k * 1024); } while (0)
; #define PG8_MMA(ai, bj, At, Bt) do { __builtin_amdgcn_s_setprio(1); _Pragma("unroll") for (int m = 0; m < 4; ++m) _Pragma("unroll") for (int n = 0; n < 2; ++n) _Pragma("unroll") for (int k = 0; k < 2; ++k) \
;         acc[ai][bj][m][n] = __builtin_amdgcn_mfma_f32_16x16x32_bf16(Bt[n][k], At[m][k], acc[ai][bj][m][n], 0, 0, 0); __builtin_amdgcn_s_setprio(0); } while (0)
; #define PG8_WAIT_V(n) asm volatile("s_waitcnt vmcnt(" #n ")" ::: "memory")
; #define PG8_WAIT_L(n) asm volatile("s_waitcnt lgkmcnt(" #n ")" ::: "memory")
; #define PG8_BAR __builtin_amdgcn_s_barrier()
; #define PG8_SCHED __builtin_amdgcn_sched_barrier(0)
; template <class Epi, class Sched, bool ALIGN_EPI = false, bool SP2 = false>
; __device__ __forceinline__ void gemm_phase(PG8_LAS unsigned char* lds, const Gemm g, const Sched& S, const Epi& E, const int wid) {
;     ...
;         for (int t = 0; t < nt; t += 2) {
;             const bool last = (t == nt - 2);
;             const char* a1 = cA + (size_t)(t + 1) * kstep;
;             const char* a2 = last ? nA : cA + (size_t)(t + 2) * kstep; const char* b2 = last ? nB : cB + (size_t)(t + 2) * kstep;
;     ...
;             PG8_LDA(At, 1, 1); PG8_STAGE(PG8_SB(1, 0), b3, voffB); PG8_STAGE(PG8_SB(1, 1), b3 + hstep, voffB); PG8_STAGE(PG8_SA(1, 0), a3, voffA);
;             PG8_WAIT_V(8); PG8_WAIT_L(0); PG8_BAR; PG8_MMA(1, 0, At, B0); PG8_MMA(1, 1, At, B1); PG8_BAR; PG8_SCHED;
	s_add_i32 s33, s33, s47
	v_lshl_add_u64 v[138:139], v[138:139], 0, s[16:17]
	s_mov_b32 m0, s33
	ds_read_b128 v[178:181], v145 offset:49152
	ds_read_b128 v[182:185], v145 offset:50176
	ds_read_b128 v[186:189], v145 offset:51200
	ds_read_b128 v[190:193], v145 offset:52224
	ds_read_b128 v[194:197], v145 offset:53248
	ds_read_b128 v[198:201], v145 offset:54272
	ds_read_b128 v[202:205], v145 offset:55296
	ds_read_b128 v[206:209], v145 offset:56320
	global_load_lds_dwordx4 v[138:139], off
	v_lshl_add_u64 v[138:139], v[210:211], 0, s[16:17]
	s_add_i32 m0, s33, 0x2000
	s_add_i32 s33, s76, s47
	global_load_lds_dwordx4 v[138:139], off
	v_lshl_add_u64 v[138:139], v[212:213], 0, s[16:17]
	s_mov_b32 m0, s33
	s_nop 0
	global_load_lds_dwordx4 v[138:139], off
	v_lshl_add_u64 v[138:139], v[214:215], 0, s[16:17]
	s_add_i32 m0, s33, 0x2000
	s_nop 0
	global_load_lds_dwordx4 v[138:139], off
	v_lshl_add_u64 v[138:139], v[216:217], 0, s[16:17]
	s_mov_b32 m0, s60
	s_nop 0
	global_load_lds_dwordx4 v[138:139], off
	v_lshl_add_u64 v[138:139], v[218:219], 0, s[16:17]
	s_mov_b32 m0, s61
	s_nop 0
	global_load_lds_dwordx4 v[138:139], off
	s_waitcnt vmcnt(8)
	s_waitcnt lgkmcnt(0)
	s_barrier
	s_setprio 1
	s_waitcnt lgkmcnt(0)
	v_mfma_f32_16x16x32_bf16 v[60:63], v[146:149], v[178:181], v[60:63]
	v_mfma_f32_16x16x32_bf16 v[56:59], v[154:157], v[178:181], v[56:59]
	v_mfma_f32_16x16x32_bf16 v[44:47], v[146:149], v[186:189], v[44:47]
	v_mfma_f32_16x16x32_bf16 v[40:43], v[154:157], v[186:189], v[40:43]
	v_mfma_f32_16x16x32_bf16 v[28:31], v[146:149], v[194:197], v[28:31]
	v_mfma_f32_16x16x32_bf16 v[24:27], v[154:157], v[194:197], v[24:27]
	v_mfma_f32_16x16x32_bf16 v[12:15], v[146:149], v[202:205], v[12:15]
	v_mfma_f32_16x16x32_bf16 v[8:11], v[154:157], v[202:205], v[8:11]
	v_mfma_f32_16x16x32_bf16 v[60:63], v[150:153], v[182:185], v[60:63]
	v_mfma_f32_16x16x32_bf16 v[56:59], v[158:161], v[182:185], v[56:59]
	v_mfma_f32_16x16x32_bf16 v[44:47], v[150:153], v[190:193], v[44:47]
	v_mfma_f32_16x16x32_bf16 v[40:43], v[158:161], v[190:193], v[40:43]
	v_mfma_f32_16x16x32_bf16 v[28:31], v[150:153], v[198:201], v[28:31]
	v_mfma_f32_16x16x32_bf16 v[24:27], v[158:161], v[198:201], v[24:27]
	v_mfma_f32_16x16x32_bf16 v[12:15], v[150:153], v[206:209], v[12:15]
	v_mfma_f32_16x16x32_bf16 v[8:11], v[158:161], v[206:209], v[8:11]
	s_setprio 0
	s_setprio 1
	v_mfma_f32_16x16x32_bf16 v[52:55], v[162:165], v[178:181], v[52:55]
	v_mfma_f32_16x16x32_bf16 v[48:51], v[170:173], v[178:181], v[48:51]
	v_mfma_f32_16x16x32_bf16 v[36:39], v[162:165], v[186:189], v[36:39]
	v_mfma_f32_16x16x32_bf16 v[32:35], v[170:173], v[186:189], v[32:35]
	v_mfma_f32_16x16x32_bf16 v[20:23], v[162:165], v[194:197], v[20:23]
	v_mfma_f32_16x16x32_bf16 v[16:19], v[170:173], v[194:197], v[16:19]
	v_mfma_f32_16x16x32_bf16 v[4:7], v[162:165], v[202:205], v[4:7]
	v_mfma_f32_16x16x32_bf16 v[0:3], v[170:173], v[202:205], v[0:3]
	v_mfma_f32_16x16x32_bf16 v[52:55], v[166:169], v[182:185], v[52:55]
	v_mfma_f32_16x16x32_bf16 v[48:51], v[174:177], v[182:185], v[48:51]
	v_mfma_f32_16x16x32_bf16 v[36:39], v[166:169], v[190:193], v[36:39]
	v_mfma_f32_16x16x32_bf16 v[32:35], v[174:177], v[190:193], v[32:35]
	v_mfma_f32_16x16x32_bf16 v[20:23], v[166:169], v[198:201], v[20:23]
	v_mfma_f32_16x16x32_bf16 v[16:19], v[174:177], v[198:201], v[16:19]
	v_mfma_f32_16x16x32_bf16 v[4:7], v[166:169], v[206:209], v[4:7]
	v_mfma_f32_16x16x32_bf16 v[0:3], v[174:177], v[206:209], v[0:3]
	s_setprio 0
	s_barrier
	s_add_u32 s40, s40, 0x100
	s_addc_u32 s41, s41, 0
	s_add_u32 s73, s73, 0x100
	s_addc_u32 s74, s74, 0
	s_cmp_ge_i32 s75, s62
	s_mov_b32 s42, s75
	s_cbranch_scc0 .LBB0_1574
